# lever 1 wait consolidation: the vmcnt(8) and lgkmcnt(0) before each load-segment barrier in the GEMM K-loops merged into one s_waitcnt (on top of v11)
# baseline (speedup 1.0000x reference)
; #define PG8_STAGE(bufoff, gbase, voff) do { _Pragma("unroll") for (int _i = 0; _i < 2; ++_i) \
;         __builtin_amdgcn_global_load_lds((const unsigned*)((const char*)(gbase) + (voff)[_i]), (PG8_LAS unsigned*)(lds + (bufoff) + ldsw + _i * 8192), 16, 0, 0); } while (0)
; #define PG8_LDA(dst, b, h) do { _Pragma("unroll") for (int m = 0; m < 4; ++m) _Pragma("unroll") for (int k = 0; k < 2; ++k) dst[m][k] = *(const PG8_LAS bf16x8*)(lds + PG8_SA(b, h) + aoff + m * 2048 + k * 1024); } while (0)
; #define PG8_LDB(dst, b, h) do { _Pragma("unroll") for (int n = 0; n < 2; ++n) _Pragma("unroll") for (int k = 0; k < 2; ++k) dst[n][k] = *(const PG8_LAS bf16x8*)(lds + PG8_SB(b, h) + boff + n * 2048 + k * 1024); } while (0)
; #define PG8_MMA(ai, bj, At, Bt) do { __builtin_amdgcn_s_setprio(1); _Pragma("unroll") for (int m = 0; m < 4; ++m) _Pragma("unroll") for (int n = 0; n < 2; ++n) _Pragma("unroll") for (int k = 0; k < 2; ++k) \
;         acc[ai][bj][m][n] = __builtin_amdgcn_mfma_f32_16x16x32_bf16(Bt[n][k], At[m][k], acc[ai][bj][m][n], 0, 0, 0); __builtin_amdgcn_s_setprio(0); } while (0)
; #define PG8_WAIT_V(n) asm volatile("s_waitcnt vmcnt(" #n ")" ::: "memory")
; #define PG8_WAIT_L(n) asm volatile("s_waitcnt lgkmcnt(" #n ")" ::: "memory")
; template <class Epi, class Sched, bool ALIGN_EPI = false, bool SP2 = false>
; __device__ __forceinline__ void gemm_phase(PG8_LAS unsigned char* lds, const Gemm g, const Sched S, const Epi E) {
;     ...
;             const bool last = (t == nt - 2);
;             const char* a1 = cA + (size_t)(t + 1) * kstep;
;             const char* a2 = last ? nA : cA + (size_t)(t + 2) * kstep; const char* b2 = last ? nB : cB + (size_t)(t + 2) * kstep;
;             const char* a3 = a2 + kstep; const char* b3 = b2 + kstep;
;             if (last && has_next) S.a_ready(nxt);
;             if constexpr (SP2) {
;             PG8_LDB(B0, 0, 0); PG8_LDB(B1, 0, 1); PG8_SCHED; PG8_LDA(At, 0, 0); PG8_STAGE(PG8_SA(1, 1), a1 + hstep, voffA);
;             PG8_WAIT_V(8); PG8_WAIT_L(0); PG8_BAR; PG8_MMA(0, 0, At, B0); PG8_MMA(0, 1, At, B1); PG8_BAR; PG8_SCHED;
;             PG8_LDA(At, 0, 1); PG8_STAGE(PG8_SB(0, 0), b2, voffB); PG8_STAGE(PG8_SB(0, 1), b2 + hstep, voffB); PG8_STAGE(PG8_SA(0, 0), a2, voffA);
;             PG8_WAIT_V(8); PG8_WAIT_L(0); PG8_BAR; PG8_MMA(1, 0, At, B0); PG8_MMA(1, 1, At, B1); PG8_BAR; PG8_SCHED;
.LBB0_193:
	ds_read_b128 v[184:187], v145
	ds_read_b128 v[188:191], v145 offset:1024
	ds_read_b128 v[192:195], v145 offset:2048
	ds_read_b128 v[196:199], v145 offset:3072
	ds_read_b128 v[200:203], v145 offset:4096
	ds_read_b128 v[224:227], v145 offset:5120
	ds_read_b128 v[228:231], v145 offset:6144
	ds_read_b128 v[232:235], v145 offset:7168
	s_add_u32 s25, s56, 0xfff80080
	s_addc_u32 s26, s57, -1
	s_add_i32 s27, 0, 0x10000
	s_cmp_eq_u32 s24, 28
	s_cselect_b32 s65, s45, s26
	s_cselect_b32 s64, vcc_lo, s25
	v_add_u32_e32 v140, s27, v143
	s_cselect_b32 s59, s43, s15
	s_cselect_b32 s58, vcc_hi, s14
	s_add_i32 s25, 0, 0x14000
	ds_read_b128 v[146:149], v140
	ds_read_b128 v[150:153], v140 offset:1024
	ds_read_b128 v[154:157], v140 offset:2048
	ds_read_b128 v[158:161], v140 offset:3072
	v_add_u32_e32 v140, s25, v143
	ds_read_b128 v[168:171], v140
	ds_read_b128 v[172:175], v140 offset:1024
	ds_read_b128 v[176:179], v140 offset:2048
	ds_read_b128 v[180:183], v140 offset:3072
	v_lshl_add_u64 v[140:141], s[56:57], 0, v[136:137]
	s_add_i32 m0, s75, 0xc000
	s_nop 0
	global_load_lds_dwordx4 v[140:141], off
	v_lshl_add_u64 v[140:141], s[56:57], 0, v[138:139]
	s_add_i32 m0, s75, 0xe000
	s_nop 0
	global_load_lds_dwordx4 v[140:141], off
	s_waitcnt vmcnt(8) lgkmcnt(0)
	s_barrier
	s_setprio 1
	v_mfma_f32_16x16x32_bf16 v[126:129], v[146:149], v[184:187], v[126:129]
	v_mfma_f32_16x16x32_bf16 v[126:129], v[150:153], v[188:191], v[126:129]
	v_mfma_f32_16x16x32_bf16 v[118:121], v[154:157], v[184:187], v[118:121]
	v_mfma_f32_16x16x32_bf16 v[118:121], v[158:161], v[188:191], v[118:121]
	v_mfma_f32_16x16x32_bf16 v[110:113], v[146:149], v[192:195], v[110:113]
	v_mfma_f32_16x16x32_bf16 v[110:113], v[150:153], v[196:199], v[110:113]
	v_mfma_f32_16x16x32_bf16 v[102:105], v[154:157], v[192:195], v[102:105]
	v_mfma_f32_16x16x32_bf16 v[102:105], v[158:161], v[196:199], v[102:105]
	v_mfma_f32_16x16x32_bf16 v[94:97], v[146:149], v[200:203], v[94:97]
	v_mfma_f32_16x16x32_bf16 v[94:97], v[150:153], v[224:227], v[94:97]
	v_mfma_f32_16x16x32_bf16 v[86:89], v[154:157], v[200:203], v[86:89]
	v_mfma_f32_16x16x32_bf16 v[86:89], v[158:161], v[224:227], v[86:89]
	v_mfma_f32_16x16x32_bf16 v[78:81], v[146:149], v[228:231], v[78:81]
	v_mfma_f32_16x16x32_bf16 v[78:81], v[150:153], v[232:235], v[78:81]
	v_mfma_f32_16x16x32_bf16 v[70:73], v[154:157], v[228:231], v[70:73]
	v_mfma_f32_16x16x32_bf16 v[70:73], v[158:161], v[232:235], v[70:73]
	v_mfma_f32_16x16x32_bf16 v[122:125], v[168:171], v[184:187], v[122:125]
	v_mfma_f32_16x16x32_bf16 v[122:125], v[172:175], v[188:191], v[122:125]
	v_mfma_f32_16x16x32_bf16 v[114:117], v[176:179], v[184:187], v[114:117]
	v_mfma_f32_16x16x32_bf16 v[114:117], v[180:183], v[188:191], v[114:117]
	v_mfma_f32_16x16x32_bf16 v[106:109], v[168:171], v[192:195], v[106:109]
	v_mfma_f32_16x16x32_bf16 v[106:109], v[172:175], v[196:199], v[106:109]
	v_mfma_f32_16x16x32_bf16 v[98:101], v[176:179], v[192:195], v[98:101]
	v_mfma_f32_16x16x32_bf16 v[98:101], v[180:183], v[196:199], v[98:101]
	v_mfma_f32_16x16x32_bf16 v[90:93], v[168:171], v[200:203], v[90:93]
	v_mfma_f32_16x16x32_bf16 v[90:93], v[172:175], v[224:227], v[90:93]
	v_mfma_f32_16x16x32_bf16 v[82:85], v[176:179], v[200:203], v[82:85]
	v_mfma_f32_16x16x32_bf16 v[82:85], v[180:183], v[224:227], v[82:85]
	v_mfma_f32_16x16x32_bf16 v[74:77], v[168:171], v[228:231], v[74:77]
	v_mfma_f32_16x16x32_bf16 v[74:77], v[172:175], v[232:235], v[74:77]
	v_mfma_f32_16x16x32_bf16 v[66:69], v[176:179], v[228:231], v[66:69]
	v_mfma_f32_16x16x32_bf16 v[66:69], v[180:183], v[232:235], v[66:69]
	s_setprio 0
	s_barrier
	ds_read_b128 v[184:187], v145 offset:16384
	ds_read_b128 v[188:191], v145 offset:17408
	ds_read_b128 v[192:195], v145 offset:18432
	ds_read_b128 v[196:199], v145 offset:19456
	ds_read_b128 v[200:203], v145 offset:20480
	ds_read_b128 v[224:227], v145 offset:21504
	ds_read_b128 v[228:231], v145 offset:22528
	ds_read_b128 v[232:235], v145 offset:23552
	s_add_i32 s26, s27, s74
	v_lshl_add_u64 v[140:141], s[58:59], 0, v[0:1]
	s_mov_b32 m0, s26
	s_nop 0
	global_load_lds_dwordx4 v[140:141], off
	s_add_i32 m0, s26, 0x2000
	s_add_u32 s26, s58, 0x80000
	v_lshl_add_u64 v[236:237], s[58:59], 0, v[130:131]
	s_addc_u32 s27, s59, 0
	s_add_i32 s25, s25, s74
	global_load_lds_dwordx4 v[236:237], off
	v_lshl_add_u64 v[238:239], s[26:27], 0, v[0:1]
	s_mov_b32 m0, s25
	v_lshl_add_u64 v[240:241], s[64:65], 0, v[132:133]
	global_load_lds_dwordx4 v[238:239], off
	v_lshl_add_u64 v[238:239], s[26:27], 0, v[130:131]
	s_add_i32 m0, s25, 0x2000
	s_nop 0
	global_load_lds_dwordx4 v[238:239], off
	v_lshl_add_u64 v[238:239], s[64:65], 0, v[134:135]
	s_mov_b32 m0, s75
	s_nop 0
	global_load_lds_dwordx4 v[238:239], off
	s_mov_b32 m0, s21
	s_nop 0
	global_load_lds_dwordx4 v[240:241], off
	s_waitcnt vmcnt(8) lgkmcnt(0)
	s_barrier
; #define PG8_STAGE(bufoff, gbase, voff) do { _Pragma("unroll") for (int _i = 0; _i < 2; ++_i) \
;         __builtin_amdgcn_global_load_lds((const unsigned*)((const char*)(gbase) + (voff)[_i]), (PG8_LAS unsigned*)(lds + (bufoff) + ldsw + _i * 8192), 16, 0, 0); } while (0)
; #define PG8_LDA(dst, b, h) do { _Pragma("unroll") for (int m = 0; m < 4; ++m) _Pragma("unroll") for (int k = 0; k < 2; ++k) dst[m][k] = *(const PG8_LAS bf16x8*)(lds + PG8_SA(b, h) + aoff + m * 2048 + k * 1024); } while (0)
; #define PG8_LDB(dst, b, h) do { _Pragma("unroll") for (int n = 0; n < 2; ++n) _Pragma("unroll") for (int k = 0; k < 2; ++k) dst[n][k] = *(const PG8_LAS bf16x8*)(lds + PG8_SB(b, h) + boff + n * 2048 + k * 1024); } while (0)
; #define PG8_MMA(ai, bj, At, Bt) do { __builtin_amdgcn_s_setprio(1); _Pragma("unroll") for (int m = 0; m < 4; ++m) _Pragma("unroll") for (int n = 0; n < 2; ++n) _Pragma("unroll") for (int k = 0; k < 2; ++k) \
;         acc[ai][bj][m][n] = __builtin_amdgcn_mfma_f32_16x16x32_bf16(Bt[n][k], At[m][k], acc[ai][bj][m][n], 0, 0, 0); __builtin_amdgcn_s_setprio(0); } while (0)
; #define PG8_WAIT_V(n) asm volatile("s_waitcnt vmcnt(" #n ")" ::: "memory")
; #define PG8_WAIT_L(n) asm volatile("s_waitcnt lgkmcnt(" #n ")" ::: "memory")
; #define PG8_BAR __builtin_amdgcn_s_barrier()
; #define PG8_SCHED __builtin_amdgcn_sched_barrier(0)
; template <class Epi, class Sched, bool ALIGN_EPI = false, bool SP2 = false>
; __device__ __forceinline__ void gemm_phase(PG8_LAS unsigned char* lds, const Gemm g, const Sched S, const Epi E) {
;     ...
;             PG8_WAIT_V(8); PG8_WAIT_L(0); PG8_BAR; PG8_MMA(1, 0, At, B0); PG8_MMA(1, 1, At, B1); PG8_BAR; PG8_SCHED;
;             PG8_LDB(B0, 1, 0); PG8_LDB(B1, 1, 1); PG8_SCHED; PG8_LDA(At, 1, 0); PG8_STAGE(PG8_SA(0, 1), a2 + hstep, voffA);
;             PG8_WAIT_V(8); PG8_WAIT_L(0); PG8_BAR; PG8_MMA(0, 0, At, B0); PG8_MMA(0, 1, At, B1); PG8_BAR; PG8_SCHED;
	s_setprio 1
	v_mfma_f32_16x16x32_bf16 v[62:65], v[146:149], v[184:187], v[62:65]
	v_mfma_f32_16x16x32_bf16 v[62:65], v[150:153], v[188:191], v[62:65]
	v_mfma_f32_16x16x32_bf16 v[54:57], v[154:157], v[184:187], v[54:57]
	v_mfma_f32_16x16x32_bf16 v[54:57], v[158:161], v[188:191], v[54:57]
	v_mfma_f32_16x16x32_bf16 v[46:49], v[146:149], v[192:195], v[46:49]
	v_mfma_f32_16x16x32_bf16 v[46:49], v[150:153], v[196:199], v[46:49]
	v_mfma_f32_16x16x32_bf16 v[38:41], v[154:157], v[192:195], v[38:41]
	v_mfma_f32_16x16x32_bf16 v[38:41], v[158:161], v[196:199], v[38:41]
	v_mfma_f32_16x16x32_bf16 v[30:33], v[146:149], v[200:203], v[30:33]
	v_mfma_f32_16x16x32_bf16 v[30:33], v[150:153], v[224:227], v[30:33]
	v_mfma_f32_16x16x32_bf16 v[22:25], v[154:157], v[200:203], v[22:25]
	v_mfma_f32_16x16x32_bf16 v[22:25], v[158:161], v[224:227], v[22:25]
	v_mfma_f32_16x16x32_bf16 v[14:17], v[146:149], v[228:231], v[14:17]
	v_mfma_f32_16x16x32_bf16 v[14:17], v[150:153], v[232:235], v[14:17]
	v_mfma_f32_16x16x32_bf16 v[6:9], v[154:157], v[228:231], v[6:9]
	v_mfma_f32_16x16x32_bf16 v[6:9], v[158:161], v[232:235], v[6:9]
	v_mfma_f32_16x16x32_bf16 v[58:61], v[168:171], v[184:187], v[58:61]
	v_mfma_f32_16x16x32_bf16 v[58:61], v[172:175], v[188:191], v[58:61]
	v_mfma_f32_16x16x32_bf16 v[50:53], v[176:179], v[184:187], v[50:53]
	v_mfma_f32_16x16x32_bf16 v[50:53], v[180:183], v[188:191], v[50:53]
	v_mfma_f32_16x16x32_bf16 v[42:45], v[168:171], v[192:195], v[42:45]
	v_mfma_f32_16x16x32_bf16 v[42:45], v[172:175], v[196:199], v[42:45]
	v_mfma_f32_16x16x32_bf16 v[34:37], v[176:179], v[192:195], v[34:37]
	v_mfma_f32_16x16x32_bf16 v[34:37], v[180:183], v[196:199], v[34:37]
	v_mfma_f32_16x16x32_bf16 v[26:29], v[168:171], v[200:203], v[26:29]
	v_mfma_f32_16x16x32_bf16 v[26:29], v[172:175], v[224:227], v[26:29]
	v_mfma_f32_16x16x32_bf16 v[18:21], v[176:179], v[200:203], v[18:21]
	v_mfma_f32_16x16x32_bf16 v[18:21], v[180:183], v[224:227], v[18:21]
	v_mfma_f32_16x16x32_bf16 v[10:13], v[168:171], v[228:231], v[10:13]
	v_mfma_f32_16x16x32_bf16 v[10:13], v[172:175], v[232:235], v[10:13]
	v_mfma_f32_16x16x32_bf16 v[2:5], v[176:179], v[228:231], v[2:5]
	v_mfma_f32_16x16x32_bf16 v[2:5], v[180:183], v[232:235], v[2:5]
	s_setprio 0
	s_barrier
	ds_read_b128 v[184:187], v145 offset:32768
	ds_read_b128 v[188:191], v145 offset:33792
	ds_read_b128 v[192:195], v145 offset:34816
	ds_read_b128 v[196:199], v145 offset:35840
	ds_read_b128 v[200:203], v145 offset:36864
	ds_read_b128 v[224:227], v145 offset:37888
	ds_read_b128 v[228:231], v145 offset:38912
	ds_read_b128 v[232:235], v145 offset:39936
	s_add_i32 s25, 0, 0x18000
	s_add_i32 s30, 0, 0x1c000
	v_add_u32_e32 v158, s25, v143
	v_add_u32_e32 v167, s30, v143
	ds_read_b128 v[146:149], v158
	ds_read_b128 v[150:153], v158 offset:1024
	ds_read_b128 v[154:157], v158 offset:2048
	ds_read_b128 v[158:161], v158 offset:3072
	ds_read_b128 v[168:171], v167
	ds_read_b128 v[172:175], v167 offset:1024
	ds_read_b128 v[176:179], v167 offset:2048
	ds_read_b128 v[180:183], v167 offset:3072
	s_add_u32 s26, s64, 0x80000
	s_addc_u32 s27, s65, 0
	s_mov_b32 m0, s47
	v_lshl_add_u64 v[242:243], s[26:27], 0, v[134:135]
	global_load_lds_dwordx4 v[242:243], off
	v_lshl_add_u64 v[242:243], s[26:27], 0, v[132:133]
	s_mov_b32 m0, s77
	s_nop 0
	global_load_lds_dwordx4 v[242:243], off
	s_waitcnt vmcnt(8) lgkmcnt(0)
	s_barrier
	s_setprio 1
	v_mfma_f32_16x16x32_bf16 v[126:129], v[146:149], v[184:187], v[126:129]
	v_mfma_f32_16x16x32_bf16 v[126:129], v[150:153], v[188:191], v[126:129]
	v_mfma_f32_16x16x32_bf16 v[118:121], v[154:157], v[184:187], v[118:121]
	v_mfma_f32_16x16x32_bf16 v[118:121], v[158:161], v[188:191], v[118:121]
	v_mfma_f32_16x16x32_bf16 v[110:113], v[146:149], v[192:195], v[110:113]
	v_mfma_f32_16x16x32_bf16 v[110:113], v[150:153], v[196:199], v[110:113]
	v_mfma_f32_16x16x32_bf16 v[102:105], v[154:157], v[192:195], v[102:105]
	v_mfma_f32_16x16x32_bf16 v[102:105], v[158:161], v[196:199], v[102:105]
	v_mfma_f32_16x16x32_bf16 v[94:97], v[146:149], v[200:203], v[94:97]
	v_mfma_f32_16x16x32_bf16 v[94:97], v[150:153], v[224:227], v[94:97]
	v_mfma_f32_16x16x32_bf16 v[86:89], v[154:157], v[200:203], v[86:89]
	v_mfma_f32_16x16x32_bf16 v[86:89], v[158:161], v[224:227], v[86:89]
	v_mfma_f32_16x16x32_bf16 v[78:81], v[146:149], v[228:231], v[78:81]
	v_mfma_f32_16x16x32_bf16 v[78:81], v[150:153], v[232:235], v[78:81]
	v_mfma_f32_16x16x32_bf16 v[70:73], v[154:157], v[228:231], v[70:73]
	v_mfma_f32_16x16x32_bf16 v[70:73], v[158:161], v[232:235], v[70:73]
	v_mfma_f32_16x16x32_bf16 v[122:125], v[168:171], v[184:187], v[122:125]
	v_mfma_f32_16x16x32_bf16 v[122:125], v[172:175], v[188:191], v[122:125]
	v_mfma_f32_16x16x32_bf16 v[114:117], v[176:179], v[184:187], v[114:117]
	v_mfma_f32_16x16x32_bf16 v[114:117], v[180:183], v[188:191], v[114:117]
	v_mfma_f32_16x16x32_bf16 v[106:109], v[168:171], v[192:195], v[106:109]
	v_mfma_f32_16x16x32_bf16 v[106:109], v[172:175], v[196:199], v[106:109]
	v_mfma_f32_16x16x32_bf16 v[98:101], v[176:179], v[192:195], v[98:101]
	v_mfma_f32_16x16x32_bf16 v[98:101], v[180:183], v[196:199], v[98:101]
	v_mfma_f32_16x16x32_bf16 v[90:93], v[168:171], v[200:203], v[90:93]
	v_mfma_f32_16x16x32_bf16 v[90:93], v[172:175], v[224:227], v[90:93]
	v_mfma_f32_16x16x32_bf16 v[82:85], v[176:179], v[200:203], v[82:85]
	v_mfma_f32_16x16x32_bf16 v[82:85], v[180:183], v[224:227], v[82:85]
	v_mfma_f32_16x16x32_bf16 v[74:77], v[168:171], v[228:231], v[74:77]
	v_mfma_f32_16x16x32_bf16 v[74:77], v[172:175], v[232:235], v[74:77]
	v_mfma_f32_16x16x32_bf16 v[66:69], v[176:179], v[228:231], v[66:69]
	v_mfma_f32_16x16x32_bf16 v[66:69], v[180:183], v[232:235], v[66:69]
	s_setprio 0
	s_barrier
; #define PG8_STAGE(bufoff, gbase, voff) do { _Pragma("unroll") for (int _i = 0; _i < 2; ++_i) \
;         __builtin_amdgcn_global_load_lds((const unsigned*)((const char*)(gbase) + (voff)[_i]), (PG8_LAS unsigned*)(lds + (bufoff) + ldsw + _i * 8192), 16, 0, 0); } while (0)
; #define PG8_LDA(dst, b, h) do { _Pragma("unroll") for (int m = 0; m < 4; ++m) _Pragma("unroll") for (int k = 0; k < 2; ++k) dst[m][k] = *(const PG8_LAS bf16x8*)(lds + PG8_SA(b, h) + aoff + m * 2048 + k * 1024); } while (0)
; #define PG8_MMA(ai, bj, At, Bt) do { __builtin_amdgcn_s_setprio(1); _Pragma("unroll") for (int m = 0; m < 4; ++m) _Pragma("unroll") for (int n = 0; n < 2; ++n) _Pragma("unroll") for (int k = 0; k < 2; ++k) \
;         acc[ai][bj][m][n] = __builtin_amdgcn_mfma_f32_16x16x32_bf16(Bt[n][k], At[m][k], acc[ai][bj][m][n], 0, 0, 0); __builtin_amdgcn_s_setprio(0); } while (0)
; #define PG8_WAIT_V(n) asm volatile("s_waitcnt vmcnt(" #n ")" ::: "memory")
; #define PG8_WAIT_L(n) asm volatile("s_waitcnt lgkmcnt(" #n ")" ::: "memory")
; #define PG8_BAR __builtin_amdgcn_s_barrier()
; #define PG8_SCHED __builtin_amdgcn_sched_barrier(0)
; template <class Epi, class Sched, bool ALIGN_EPI = false, bool SP2 = false>
; __device__ __forceinline__ void gemm_phase(PG8_LAS unsigned char* lds, const Gemm g, const Sched S, const Epi E) {
;     ...
;             PG8_LDA(At, 1, 1); PG8_STAGE(PG8_SB(1, 0), b3, voffB); PG8_STAGE(PG8_SB(1, 1), b3 + hstep, voffB); PG8_STAGE(PG8_SA(1, 0), a3, voffA);
;             PG8_WAIT_V(8); PG8_WAIT_L(0); PG8_BAR; PG8_MMA(1, 0, At, B0); PG8_MMA(1, 1, At, B1); PG8_BAR; PG8_SCHED;
;     ...
;         if constexpr (ALIGN_EPI) { if (wr == 0) PG8_BAR; }
	ds_read_b128 v[184:187], v145 offset:49152
	ds_read_b128 v[188:191], v145 offset:50176
	ds_read_b128 v[192:195], v145 offset:51200
	ds_read_b128 v[196:199], v145 offset:52224
	ds_read_b128 v[200:203], v145 offset:53248
	ds_read_b128 v[224:227], v145 offset:54272
	ds_read_b128 v[228:231], v145 offset:55296
	ds_read_b128 v[232:235], v145 offset:56320
	s_add_i32 s25, s25, s74
	v_lshl_add_u64 v[140:141], v[140:141], 0, s[28:29]
	s_mov_b32 m0, s25
	s_nop 0
	global_load_lds_dwordx4 v[140:141], off
	s_add_i32 m0, s25, 0x2000
	s_add_u32 s26, s58, 0x80080
	v_lshl_add_u64 v[140:141], v[236:237], 0, s[28:29]
	s_addc_u32 s27, s59, 0
	s_add_i32 s25, s30, s74
	global_load_lds_dwordx4 v[140:141], off
	v_lshl_add_u64 v[140:141], s[26:27], 0, v[0:1]
	s_mov_b32 m0, s25
	s_nop 0
	global_load_lds_dwordx4 v[140:141], off
	v_lshl_add_u64 v[140:141], s[26:27], 0, v[130:131]
	s_add_i32 m0, s25, 0x2000
	s_nop 0
	global_load_lds_dwordx4 v[140:141], off
	v_lshl_add_u64 v[140:141], v[238:239], 0, s[28:29]
	s_mov_b32 m0, s62
	s_nop 0
	global_load_lds_dwordx4 v[140:141], off
	v_lshl_add_u64 v[140:141], v[240:241], 0, s[28:29]
	s_mov_b32 m0, s63
	s_nop 0
	global_load_lds_dwordx4 v[140:141], off
	s_waitcnt vmcnt(8) lgkmcnt(0)
	s_barrier
	s_setprio 1
	v_mfma_f32_16x16x32_bf16 v[62:65], v[146:149], v[184:187], v[62:65]
	v_mfma_f32_16x16x32_bf16 v[62:65], v[150:153], v[188:191], v[62:65]
	v_mfma_f32_16x16x32_bf16 v[54:57], v[154:157], v[184:187], v[54:57]
	v_mfma_f32_16x16x32_bf16 v[54:57], v[158:161], v[188:191], v[54:57]
	v_mfma_f32_16x16x32_bf16 v[46:49], v[146:149], v[192:195], v[46:49]
	v_mfma_f32_16x16x32_bf16 v[46:49], v[150:153], v[196:199], v[46:49]
	v_mfma_f32_16x16x32_bf16 v[38:41], v[154:157], v[192:195], v[38:41]
	v_mfma_f32_16x16x32_bf16 v[38:41], v[158:161], v[196:199], v[38:41]
	v_mfma_f32_16x16x32_bf16 v[30:33], v[146:149], v[200:203], v[30:33]
	v_mfma_f32_16x16x32_bf16 v[30:33], v[150:153], v[224:227], v[30:33]
	v_mfma_f32_16x16x32_bf16 v[22:25], v[154:157], v[200:203], v[22:25]
	v_mfma_f32_16x16x32_bf16 v[22:25], v[158:161], v[224:227], v[22:25]
	v_mfma_f32_16x16x32_bf16 v[14:17], v[146:149], v[228:231], v[14:17]
	v_mfma_f32_16x16x32_bf16 v[14:17], v[150:153], v[232:235], v[14:17]
	v_mfma_f32_16x16x32_bf16 v[6:9], v[154:157], v[228:231], v[6:9]
	v_mfma_f32_16x16x32_bf16 v[6:9], v[158:161], v[232:235], v[6:9]
	v_mfma_f32_16x16x32_bf16 v[58:61], v[168:171], v[184:187], v[58:61]
	v_mfma_f32_16x16x32_bf16 v[58:61], v[172:175], v[188:191], v[58:61]
	v_mfma_f32_16x16x32_bf16 v[50:53], v[176:179], v[184:187], v[50:53]
	v_mfma_f32_16x16x32_bf16 v[50:53], v[180:183], v[188:191], v[50:53]
	v_mfma_f32_16x16x32_bf16 v[42:45], v[168:171], v[192:195], v[42:45]
	v_mfma_f32_16x16x32_bf16 v[42:45], v[172:175], v[196:199], v[42:45]
	v_mfma_f32_16x16x32_bf16 v[34:37], v[176:179], v[192:195], v[34:37]
	v_mfma_f32_16x16x32_bf16 v[34:37], v[180:183], v[196:199], v[34:37]
	v_mfma_f32_16x16x32_bf16 v[26:29], v[168:171], v[200:203], v[26:29]
	v_mfma_f32_16x16x32_bf16 v[26:29], v[172:175], v[224:227], v[26:29]
	v_mfma_f32_16x16x32_bf16 v[18:21], v[176:179], v[200:203], v[18:21]
	v_mfma_f32_16x16x32_bf16 v[18:21], v[180:183], v[224:227], v[18:21]
	v_mfma_f32_16x16x32_bf16 v[10:13], v[168:171], v[228:231], v[10:13]
	v_mfma_f32_16x16x32_bf16 v[10:13], v[172:175], v[232:235], v[10:13]
	v_mfma_f32_16x16x32_bf16 v[2:5], v[176:179], v[228:231], v[2:5]
	v_mfma_f32_16x16x32_bf16 v[2:5], v[180:183], v[232:235], v[2:5]
	s_setprio 0
	s_barrier
	s_add_i32 s24, s24, 2
	s_add_u32 s56, s56, 0x100
	s_addc_u32 s57, s57, 0
	s_add_u32 s14, s14, 0x100
	s_addc_u32 s15, s15, 0
	s_cmp_gt_u32 s24, 29
	s_cbranch_scc0 .LBB0_193
	s_and_b64 vcc, exec, s[40:41]
	s_cbranch_vccz .LBB0_196
	s_barrier

; #define PG8_STAGE(bufoff, gbase, voff) do { _Pragma("unroll") for (int _i = 0; _i < 2; ++_i) \
;         __builtin_amdgcn_global_load_lds((const unsigned*)((const char*)(gbase) + (voff)[_i]), (PG8_LAS unsigned*)(lds + (bufoff) + ldsw + _i * 8192), 16, 0, 0); } while (0)
; #define PG8_LDA(dst, b, h) do { _Pragma("unroll") for (int m = 0; m < 4; ++m) _Pragma("unroll") for (int k = 0; k < 2; ++k) dst[m][k] = *(const PG8_LAS bf16x8*)(lds + PG8_SA(b, h) + aoff + m * 2048 + k * 1024); } while (0)
; #define PG8_LDB(dst, b, h) do { _Pragma("unroll") for (int n = 0; n < 2; ++n) _Pragma("unroll") for (int k = 0; k < 2; ++k) dst[n][k] = *(const PG8_LAS bf16x8*)(lds + PG8_SB(b, h) + boff + n * 2048 + k * 1024); } while (0)
; #define PG8_MMA(ai, bj, At, Bt) do { __builtin_amdgcn_s_setprio(1); _Pragma("unroll") for (int m = 0; m < 4; ++m) _Pragma("unroll") for (int n = 0; n < 2; ++n) _Pragma("unroll") for (int k = 0; k < 2; ++k) \
;         acc[ai][bj][m][n] = __builtin_amdgcn_mfma_f32_16x16x32_bf16(Bt[n][k], At[m][k], acc[ai][bj][m][n], 0, 0, 0); __builtin_amdgcn_s_setprio(0); } while (0)
; #define PG8_WAIT_V(n) asm volatile("s_waitcnt vmcnt(" #n ")" ::: "memory")
; #define PG8_WAIT_L(n) asm volatile("s_waitcnt lgkmcnt(" #n ")" ::: "memory")
; template <class Epi, class Sched, bool ALIGN_EPI = false, bool SP2 = false>
; __device__ __forceinline__ void gemm_phase(PG8_LAS unsigned char* lds, const Gemm g, const Sched S, const Epi E) {
;     ...
;             const bool last = (t == nt - 2);
;             const char* a1 = cA + (size_t)(t + 1) * kstep;
;             const char* a2 = last ? nA : cA + (size_t)(t + 2) * kstep; const char* b2 = last ? nB : cB + (size_t)(t + 2) * kstep;
;             const char* a3 = a2 + kstep; const char* b3 = b2 + kstep;
;             if (last && has_next) S.a_ready(nxt);
;             if constexpr (SP2) {
;             PG8_LDB(B0, 0, 0); PG8_LDB(B1, 0, 1); PG8_SCHED; PG8_LDA(At, 0, 0); PG8_STAGE(PG8_SA(1, 1), a1 + hstep, voffA);
;             PG8_WAIT_V(8); PG8_WAIT_L(0); PG8_BAR; PG8_MMA(0, 0, At, B0); PG8_MMA(0, 1, At, B1); PG8_BAR; PG8_SCHED;
;             PG8_LDA(At, 0, 1); PG8_STAGE(PG8_SB(0, 0), b2, voffB); PG8_STAGE(PG8_SB(0, 1), b2 + hstep, voffB); PG8_STAGE(PG8_SA(0, 0), a2, voffA);
;             PG8_WAIT_V(8); PG8_WAIT_L(0); PG8_BAR; PG8_MMA(1, 0, At, B0); PG8_MMA(1, 1, At, B1); PG8_BAR; PG8_SCHED;
.LBB0_272:
	ds_read_b128 v[180:183], v145
	ds_read_b128 v[184:187], v145 offset:1024
	ds_read_b128 v[188:191], v145 offset:2048
	ds_read_b128 v[192:195], v145 offset:3072
	ds_read_b128 v[196:199], v145 offset:4096
	ds_read_b128 v[200:203], v145 offset:5120
	ds_read_b128 v[224:227], v145 offset:6144
	ds_read_b128 v[228:231], v145 offset:7168
	s_add_u32 s52, s50, 0x100
	s_addc_u32 s53, s51, 0
	s_add_i32 s24, 0, 0x10000
	s_cmpk_eq_i32 s15, 0x54
	s_cselect_b32 s59, s1, s53
	s_cselect_b32 s58, s0, s52
	v_add_u32_e32 v140, s24, v143
	s_cselect_b32 s57, s45, s14
	s_cselect_b32 s56, s44, s5
	s_add_i32 s26, 0, 0x14000
	ds_read_b128 v[136:139], v140
	ds_read_b128 v[146:149], v140 offset:1024
	ds_read_b128 v[150:153], v140 offset:2048
	ds_read_b128 v[154:157], v140 offset:3072
	v_add_u32_e32 v140, s26, v143
	ds_read_b128 v[158:161], v140
	ds_read_b128 v[168:171], v140 offset:1024
	ds_read_b128 v[172:175], v140 offset:2048
	ds_read_b128 v[176:179], v140 offset:3072
	v_lshl_add_u64 v[140:141], s[50:51], 0, v[132:133]
	s_add_i32 m0, s47, 0xc000
	s_nop 0
	global_load_lds_dwordx4 v[140:141], off
	v_lshl_add_u64 v[140:141], s[50:51], 0, v[134:135]
	s_add_i32 m0, s47, 0xe000
	s_nop 0
	global_load_lds_dwordx4 v[140:141], off
	s_waitcnt vmcnt(8) lgkmcnt(0)
	s_barrier
	s_setprio 1
	v_mfma_f32_16x16x32_bf16 v[126:129], v[136:139], v[180:183], v[126:129]
	v_mfma_f32_16x16x32_bf16 v[126:129], v[146:149], v[184:187], v[126:129]
	v_mfma_f32_16x16x32_bf16 v[122:125], v[150:153], v[180:183], v[122:125]
	v_mfma_f32_16x16x32_bf16 v[122:125], v[154:157], v[184:187], v[122:125]
	v_mfma_f32_16x16x32_bf16 v[110:113], v[136:139], v[188:191], v[110:113]
	v_mfma_f32_16x16x32_bf16 v[110:113], v[146:149], v[192:195], v[110:113]
	v_mfma_f32_16x16x32_bf16 v[106:109], v[150:153], v[188:191], v[106:109]
	v_mfma_f32_16x16x32_bf16 v[106:109], v[154:157], v[192:195], v[106:109]
	v_mfma_f32_16x16x32_bf16 v[94:97], v[136:139], v[196:199], v[94:97]
	v_mfma_f32_16x16x32_bf16 v[94:97], v[146:149], v[200:203], v[94:97]
	v_mfma_f32_16x16x32_bf16 v[90:93], v[150:153], v[196:199], v[90:93]
	v_mfma_f32_16x16x32_bf16 v[90:93], v[154:157], v[200:203], v[90:93]
	v_mfma_f32_16x16x32_bf16 v[78:81], v[136:139], v[224:227], v[78:81]
	v_mfma_f32_16x16x32_bf16 v[78:81], v[146:149], v[228:231], v[78:81]
	v_mfma_f32_16x16x32_bf16 v[74:77], v[150:153], v[224:227], v[74:77]
	v_mfma_f32_16x16x32_bf16 v[74:77], v[154:157], v[228:231], v[74:77]
	v_mfma_f32_16x16x32_bf16 v[118:121], v[158:161], v[180:183], v[118:121]
	v_mfma_f32_16x16x32_bf16 v[118:121], v[168:171], v[184:187], v[118:121]
	v_mfma_f32_16x16x32_bf16 v[114:117], v[172:175], v[180:183], v[114:117]
	v_mfma_f32_16x16x32_bf16 v[114:117], v[176:179], v[184:187], v[114:117]
	v_mfma_f32_16x16x32_bf16 v[102:105], v[158:161], v[188:191], v[102:105]
	v_mfma_f32_16x16x32_bf16 v[102:105], v[168:171], v[192:195], v[102:105]
	v_mfma_f32_16x16x32_bf16 v[98:101], v[172:175], v[188:191], v[98:101]
	v_mfma_f32_16x16x32_bf16 v[98:101], v[176:179], v[192:195], v[98:101]
	v_mfma_f32_16x16x32_bf16 v[86:89], v[158:161], v[196:199], v[86:89]
	v_mfma_f32_16x16x32_bf16 v[86:89], v[168:171], v[200:203], v[86:89]
	v_mfma_f32_16x16x32_bf16 v[82:85], v[172:175], v[196:199], v[82:85]
	v_mfma_f32_16x16x32_bf16 v[82:85], v[176:179], v[200:203], v[82:85]
	v_mfma_f32_16x16x32_bf16 v[70:73], v[158:161], v[224:227], v[70:73]
	v_mfma_f32_16x16x32_bf16 v[70:73], v[168:171], v[228:231], v[70:73]
	v_mfma_f32_16x16x32_bf16 v[66:69], v[172:175], v[224:227], v[66:69]
	v_mfma_f32_16x16x32_bf16 v[66:69], v[176:179], v[228:231], v[66:69]
	s_setprio 0
	s_barrier
	ds_read_b128 v[180:183], v145 offset:16384
	ds_read_b128 v[184:187], v145 offset:17408
	ds_read_b128 v[188:191], v145 offset:18432
	ds_read_b128 v[192:195], v145 offset:19456
	ds_read_b128 v[196:199], v145 offset:20480
	ds_read_b128 v[200:203], v145 offset:21504
	ds_read_b128 v[224:227], v145 offset:22528
	ds_read_b128 v[228:231], v145 offset:23552
	s_add_i32 s24, s24, s22
	v_lshl_add_u64 v[140:141], s[56:57], 0, v[0:1]
	s_mov_b32 m0, s24
	s_nop 0
	global_load_lds_dwordx4 v[140:141], off
	s_add_i32 m0, s24, 0x2000
	s_add_u32 s24, s56, 0x160000
	v_lshl_add_u64 v[232:233], s[56:57], 0, v[130:131]
	s_addc_u32 s25, s57, 0
	s_add_i32 s26, s26, s22
	global_load_lds_dwordx4 v[232:233], off
	v_lshl_add_u64 v[234:235], s[24:25], 0, v[0:1]
	s_mov_b32 m0, s26
	v_lshl_add_u64 v[236:237], s[58:59], 0, v[130:131]
	global_load_lds_dwordx4 v[234:235], off
	v_lshl_add_u64 v[234:235], s[24:25], 0, v[130:131]
	s_add_i32 m0, s26, 0x2000
	s_nop 0
	global_load_lds_dwordx4 v[234:235], off
	v_lshl_add_u64 v[234:235], s[58:59], 0, v[0:1]
	s_mov_b32 m0, s47
	s_nop 0
	global_load_lds_dwordx4 v[234:235], off
	s_mov_b32 m0, s62
	s_nop 0
	global_load_lds_dwordx4 v[236:237], off
	s_waitcnt vmcnt(8) lgkmcnt(0)
	s_barrier
; #define PG8_STAGE(bufoff, gbase, voff) do { _Pragma("unroll") for (int _i = 0; _i < 2; ++_i) \
;         __builtin_amdgcn_global_load_lds((const unsigned*)((const char*)(gbase) + (voff)[_i]), (PG8_LAS unsigned*)(lds + (bufoff) + ldsw + _i * 8192), 16, 0, 0); } while (0)
; #define PG8_LDA(dst, b, h) do { _Pragma("unroll") for (int m = 0; m < 4; ++m) _Pragma("unroll") for (int k = 0; k < 2; ++k) dst[m][k] = *(const PG8_LAS bf16x8*)(lds + PG8_SA(b, h) + aoff + m * 2048 + k * 1024); } while (0)
; #define PG8_LDB(dst, b, h) do { _Pragma("unroll") for (int n = 0; n < 2; ++n) _Pragma("unroll") for (int k = 0; k < 2; ++k) dst[n][k] = *(const PG8_LAS bf16x8*)(lds + PG8_SB(b, h) + boff + n * 2048 + k * 1024); } while (0)
; #define PG8_MMA(ai, bj, At, Bt) do { __builtin_amdgcn_s_setprio(1); _Pragma("unroll") for (int m = 0; m < 4; ++m) _Pragma("unroll") for (int n = 0; n < 2; ++n) _Pragma("unroll") for (int k = 0; k < 2; ++k) \
;         acc[ai][bj][m][n] = __builtin_amdgcn_mfma_f32_16x16x32_bf16(Bt[n][k], At[m][k], acc[ai][bj][m][n], 0, 0, 0); __builtin_amdgcn_s_setprio(0); } while (0)
; #define PG8_WAIT_V(n) asm volatile("s_waitcnt vmcnt(" #n ")" ::: "memory")
; #define PG8_WAIT_L(n) asm volatile("s_waitcnt lgkmcnt(" #n ")" ::: "memory")
; #define PG8_BAR __builtin_amdgcn_s_barrier()
; #define PG8_SCHED __builtin_amdgcn_sched_barrier(0)
; template <class Epi, class Sched, bool ALIGN_EPI = false, bool SP2 = false>
; __device__ __forceinline__ void gemm_phase(PG8_LAS unsigned char* lds, const Gemm g, const Sched S, const Epi E) {
;     ...
;             PG8_WAIT_V(8); PG8_WAIT_L(0); PG8_BAR; PG8_MMA(1, 0, At, B0); PG8_MMA(1, 1, At, B1); PG8_BAR; PG8_SCHED;
;             PG8_LDB(B0, 1, 0); PG8_LDB(B1, 1, 1); PG8_SCHED; PG8_LDA(At, 1, 0); PG8_STAGE(PG8_SA(0, 1), a2 + hstep, voffA);
;             PG8_WAIT_V(8); PG8_WAIT_L(0); PG8_BAR; PG8_MMA(0, 0, At, B0); PG8_MMA(0, 1, At, B1); PG8_BAR; PG8_SCHED;
	s_setprio 1
	v_mfma_f32_16x16x32_bf16 v[62:65], v[136:139], v[180:183], v[62:65]
	v_mfma_f32_16x16x32_bf16 v[62:65], v[146:149], v[184:187], v[62:65]
	v_mfma_f32_16x16x32_bf16 v[58:61], v[150:153], v[180:183], v[58:61]
	v_mfma_f32_16x16x32_bf16 v[58:61], v[154:157], v[184:187], v[58:61]
	v_mfma_f32_16x16x32_bf16 v[46:49], v[136:139], v[188:191], v[46:49]
	v_mfma_f32_16x16x32_bf16 v[46:49], v[146:149], v[192:195], v[46:49]
	v_mfma_f32_16x16x32_bf16 v[42:45], v[150:153], v[188:191], v[42:45]
	v_mfma_f32_16x16x32_bf16 v[42:45], v[154:157], v[192:195], v[42:45]
	v_mfma_f32_16x16x32_bf16 v[30:33], v[136:139], v[196:199], v[30:33]
	v_mfma_f32_16x16x32_bf16 v[30:33], v[146:149], v[200:203], v[30:33]
	v_mfma_f32_16x16x32_bf16 v[26:29], v[150:153], v[196:199], v[26:29]
	v_mfma_f32_16x16x32_bf16 v[26:29], v[154:157], v[200:203], v[26:29]
	v_mfma_f32_16x16x32_bf16 v[14:17], v[136:139], v[224:227], v[14:17]
	v_mfma_f32_16x16x32_bf16 v[14:17], v[146:149], v[228:231], v[14:17]
	v_mfma_f32_16x16x32_bf16 v[10:13], v[150:153], v[224:227], v[10:13]
	v_mfma_f32_16x16x32_bf16 v[10:13], v[154:157], v[228:231], v[10:13]
	v_mfma_f32_16x16x32_bf16 v[54:57], v[158:161], v[180:183], v[54:57]
	v_mfma_f32_16x16x32_bf16 v[54:57], v[168:171], v[184:187], v[54:57]
	v_mfma_f32_16x16x32_bf16 v[50:53], v[172:175], v[180:183], v[50:53]
	v_mfma_f32_16x16x32_bf16 v[50:53], v[176:179], v[184:187], v[50:53]
	v_mfma_f32_16x16x32_bf16 v[38:41], v[158:161], v[188:191], v[38:41]
	v_mfma_f32_16x16x32_bf16 v[38:41], v[168:171], v[192:195], v[38:41]
	v_mfma_f32_16x16x32_bf16 v[34:37], v[172:175], v[188:191], v[34:37]
	v_mfma_f32_16x16x32_bf16 v[34:37], v[176:179], v[192:195], v[34:37]
	v_mfma_f32_16x16x32_bf16 v[22:25], v[158:161], v[196:199], v[22:25]
	v_mfma_f32_16x16x32_bf16 v[22:25], v[168:171], v[200:203], v[22:25]
	v_mfma_f32_16x16x32_bf16 v[18:21], v[172:175], v[196:199], v[18:21]
	v_mfma_f32_16x16x32_bf16 v[18:21], v[176:179], v[200:203], v[18:21]
	v_mfma_f32_16x16x32_bf16 v[6:9], v[158:161], v[224:227], v[6:9]
	v_mfma_f32_16x16x32_bf16 v[6:9], v[168:171], v[228:231], v[6:9]
	v_mfma_f32_16x16x32_bf16 v[2:5], v[172:175], v[224:227], v[2:5]
	v_mfma_f32_16x16x32_bf16 v[2:5], v[176:179], v[228:231], v[2:5]
	s_setprio 0
	s_barrier
	ds_read_b128 v[180:183], v145 offset:32768
	ds_read_b128 v[184:187], v145 offset:33792
	ds_read_b128 v[188:191], v145 offset:34816
	ds_read_b128 v[192:195], v145 offset:35840
	ds_read_b128 v[196:199], v145 offset:36864
	ds_read_b128 v[200:203], v145 offset:37888
	ds_read_b128 v[224:227], v145 offset:38912
	ds_read_b128 v[228:231], v145 offset:39936
	s_add_i32 s26, 0, 0x18000
	s_add_i32 s27, 0, 0x1c000
	v_add_u32_e32 v154, s26, v143
	v_add_u32_e32 v167, s27, v143
	ds_read_b128 v[136:139], v154
	ds_read_b128 v[146:149], v154 offset:1024
	ds_read_b128 v[150:153], v154 offset:2048
	ds_read_b128 v[154:157], v154 offset:3072
	ds_read_b128 v[158:161], v167
	ds_read_b128 v[168:171], v167 offset:1024
	ds_read_b128 v[172:175], v167 offset:2048
	ds_read_b128 v[176:179], v167 offset:3072
	s_add_u32 s24, s58, 0x160000
	s_addc_u32 s25, s59, 0
	s_mov_b32 m0, s63
	v_lshl_add_u64 v[238:239], s[24:25], 0, v[0:1]
	global_load_lds_dwordx4 v[238:239], off
	v_lshl_add_u64 v[238:239], s[24:25], 0, v[130:131]
	s_mov_b32 m0, s64
	s_nop 0
	global_load_lds_dwordx4 v[238:239], off
	s_waitcnt vmcnt(8) lgkmcnt(0)
	s_barrier
	s_setprio 1
	v_mfma_f32_16x16x32_bf16 v[126:129], v[136:139], v[180:183], v[126:129]
	v_mfma_f32_16x16x32_bf16 v[126:129], v[146:149], v[184:187], v[126:129]
	v_mfma_f32_16x16x32_bf16 v[122:125], v[150:153], v[180:183], v[122:125]
	v_mfma_f32_16x16x32_bf16 v[122:125], v[154:157], v[184:187], v[122:125]
	v_mfma_f32_16x16x32_bf16 v[110:113], v[136:139], v[188:191], v[110:113]
	v_mfma_f32_16x16x32_bf16 v[110:113], v[146:149], v[192:195], v[110:113]
	v_mfma_f32_16x16x32_bf16 v[106:109], v[150:153], v[188:191], v[106:109]
	v_mfma_f32_16x16x32_bf16 v[106:109], v[154:157], v[192:195], v[106:109]
	v_mfma_f32_16x16x32_bf16 v[94:97], v[136:139], v[196:199], v[94:97]
	v_mfma_f32_16x16x32_bf16 v[94:97], v[146:149], v[200:203], v[94:97]
	v_mfma_f32_16x16x32_bf16 v[90:93], v[150:153], v[196:199], v[90:93]
	v_mfma_f32_16x16x32_bf16 v[90:93], v[154:157], v[200:203], v[90:93]
	v_mfma_f32_16x16x32_bf16 v[78:81], v[136:139], v[224:227], v[78:81]
	v_mfma_f32_16x16x32_bf16 v[78:81], v[146:149], v[228:231], v[78:81]
	v_mfma_f32_16x16x32_bf16 v[74:77], v[150:153], v[224:227], v[74:77]
	v_mfma_f32_16x16x32_bf16 v[74:77], v[154:157], v[228:231], v[74:77]
	v_mfma_f32_16x16x32_bf16 v[118:121], v[158:161], v[180:183], v[118:121]
	v_mfma_f32_16x16x32_bf16 v[118:121], v[168:171], v[184:187], v[118:121]
	v_mfma_f32_16x16x32_bf16 v[114:117], v[172:175], v[180:183], v[114:117]
	v_mfma_f32_16x16x32_bf16 v[114:117], v[176:179], v[184:187], v[114:117]
	v_mfma_f32_16x16x32_bf16 v[102:105], v[158:161], v[188:191], v[102:105]
	v_mfma_f32_16x16x32_bf16 v[102:105], v[168:171], v[192:195], v[102:105]
	v_mfma_f32_16x16x32_bf16 v[98:101], v[172:175], v[188:191], v[98:101]
	v_mfma_f32_16x16x32_bf16 v[98:101], v[176:179], v[192:195], v[98:101]
	v_mfma_f32_16x16x32_bf16 v[86:89], v[158:161], v[196:199], v[86:89]
	v_mfma_f32_16x16x32_bf16 v[86:89], v[168:171], v[200:203], v[86:89]
	v_mfma_f32_16x16x32_bf16 v[82:85], v[172:175], v[196:199], v[82:85]
	v_mfma_f32_16x16x32_bf16 v[82:85], v[176:179], v[200:203], v[82:85]
	v_mfma_f32_16x16x32_bf16 v[70:73], v[158:161], v[224:227], v[70:73]
	v_mfma_f32_16x16x32_bf16 v[70:73], v[168:171], v[228:231], v[70:73]
	v_mfma_f32_16x16x32_bf16 v[66:69], v[172:175], v[224:227], v[66:69]
	v_mfma_f32_16x16x32_bf16 v[66:69], v[176:179], v[228:231], v[66:69]
	s_setprio 0
	s_barrier
; #define PG8_STAGE(bufoff, gbase, voff) do { _Pragma("unroll") for (int _i = 0; _i < 2; ++_i) \
;         __builtin_amdgcn_global_load_lds((const unsigned*)((const char*)(gbase) + (voff)[_i]), (PG8_LAS unsigned*)(lds + (bufoff) + ldsw + _i * 8192), 16, 0, 0); } while (0)
; #define PG8_LDA(dst, b, h) do { _Pragma("unroll") for (int m = 0; m < 4; ++m) _Pragma("unroll") for (int k = 0; k < 2; ++k) dst[m][k] = *(const PG8_LAS bf16x8*)(lds + PG8_SA(b, h) + aoff + m * 2048 + k * 1024); } while (0)
; #define PG8_MMA(ai, bj, At, Bt) do { __builtin_amdgcn_s_setprio(1); _Pragma("unroll") for (int m = 0; m < 4; ++m) _Pragma("unroll") for (int n = 0; n < 2; ++n) _Pragma("unroll") for (int k = 0; k < 2; ++k) \
;         acc[ai][bj][m][n] = __builtin_amdgcn_mfma_f32_16x16x32_bf16(Bt[n][k], At[m][k], acc[ai][bj][m][n], 0, 0, 0); __builtin_amdgcn_s_setprio(0); } while (0)
; #define PG8_WAIT_V(n) asm volatile("s_waitcnt vmcnt(" #n ")" ::: "memory")
; #define PG8_WAIT_L(n) asm volatile("s_waitcnt lgkmcnt(" #n ")" ::: "memory")
; #define PG8_BAR __builtin_amdgcn_s_barrier()
; #define PG8_SCHED __builtin_amdgcn_sched_barrier(0)
; template <class Epi, class Sched, bool ALIGN_EPI = false, bool SP2 = false>
; __device__ __forceinline__ void gemm_phase(PG8_LAS unsigned char* lds, const Gemm g, const Sched S, const Epi E) {
;     ...
;             PG8_LDA(At, 1, 1); PG8_STAGE(PG8_SB(1, 0), b3, voffB); PG8_STAGE(PG8_SB(1, 1), b3 + hstep, voffB); PG8_STAGE(PG8_SA(1, 0), a3, voffA);
;             PG8_WAIT_V(8); PG8_WAIT_L(0); PG8_BAR; PG8_MMA(1, 0, At, B0); PG8_MMA(1, 1, At, B1); PG8_BAR; PG8_SCHED;
;     ...
;         if constexpr (ALIGN_EPI) { if (wr == 0) PG8_BAR; }
	ds_read_b128 v[180:183], v145 offset:49152
	ds_read_b128 v[184:187], v145 offset:50176
	ds_read_b128 v[188:191], v145 offset:51200
	ds_read_b128 v[192:195], v145 offset:52224
	ds_read_b128 v[196:199], v145 offset:53248
	ds_read_b128 v[200:203], v145 offset:54272
	ds_read_b128 v[224:227], v145 offset:55296
	ds_read_b128 v[228:231], v145 offset:56320
	s_add_i32 s24, s26, s22
	v_lshl_add_u64 v[140:141], v[140:141], 0, s[28:29]
	s_mov_b32 m0, s24
	s_nop 0
	global_load_lds_dwordx4 v[140:141], off
	s_add_i32 m0, s24, 0x2000
	s_add_u32 s24, s56, 0x160080
	v_lshl_add_u64 v[140:141], v[232:233], 0, s[28:29]
	s_addc_u32 s25, s57, 0
	s_add_i32 s26, s27, s22
	global_load_lds_dwordx4 v[140:141], off
	v_lshl_add_u64 v[140:141], s[24:25], 0, v[0:1]
	s_mov_b32 m0, s26
	s_nop 0
	global_load_lds_dwordx4 v[140:141], off
	v_lshl_add_u64 v[140:141], s[24:25], 0, v[130:131]
	s_add_i32 m0, s26, 0x2000
	s_nop 0
	global_load_lds_dwordx4 v[140:141], off
	v_lshl_add_u64 v[140:141], v[234:235], 0, s[28:29]
	s_mov_b32 m0, s65
	s_nop 0
	global_load_lds_dwordx4 v[140:141], off
	v_lshl_add_u64 v[140:141], v[236:237], 0, s[28:29]
	s_mov_b32 m0, s66
	s_nop 0
	global_load_lds_dwordx4 v[140:141], off
	s_waitcnt vmcnt(8) lgkmcnt(0)
	s_barrier
	s_setprio 1
	v_mfma_f32_16x16x32_bf16 v[62:65], v[136:139], v[180:183], v[62:65]
	v_mfma_f32_16x16x32_bf16 v[62:65], v[146:149], v[184:187], v[62:65]
	v_mfma_f32_16x16x32_bf16 v[58:61], v[150:153], v[180:183], v[58:61]
	v_mfma_f32_16x16x32_bf16 v[58:61], v[154:157], v[184:187], v[58:61]
	v_mfma_f32_16x16x32_bf16 v[46:49], v[136:139], v[188:191], v[46:49]
	v_mfma_f32_16x16x32_bf16 v[46:49], v[146:149], v[192:195], v[46:49]
	v_mfma_f32_16x16x32_bf16 v[42:45], v[150:153], v[188:191], v[42:45]
	v_mfma_f32_16x16x32_bf16 v[42:45], v[154:157], v[192:195], v[42:45]
	v_mfma_f32_16x16x32_bf16 v[30:33], v[136:139], v[196:199], v[30:33]
	v_mfma_f32_16x16x32_bf16 v[30:33], v[146:149], v[200:203], v[30:33]
	v_mfma_f32_16x16x32_bf16 v[26:29], v[150:153], v[196:199], v[26:29]
	v_mfma_f32_16x16x32_bf16 v[26:29], v[154:157], v[200:203], v[26:29]
	v_mfma_f32_16x16x32_bf16 v[14:17], v[136:139], v[224:227], v[14:17]
	v_mfma_f32_16x16x32_bf16 v[14:17], v[146:149], v[228:231], v[14:17]
	v_mfma_f32_16x16x32_bf16 v[10:13], v[150:153], v[224:227], v[10:13]
	v_mfma_f32_16x16x32_bf16 v[10:13], v[154:157], v[228:231], v[10:13]
	v_mfma_f32_16x16x32_bf16 v[54:57], v[158:161], v[180:183], v[54:57]
	v_mfma_f32_16x16x32_bf16 v[54:57], v[168:171], v[184:187], v[54:57]
	v_mfma_f32_16x16x32_bf16 v[50:53], v[172:175], v[180:183], v[50:53]
	v_mfma_f32_16x16x32_bf16 v[50:53], v[176:179], v[184:187], v[50:53]
	v_mfma_f32_16x16x32_bf16 v[38:41], v[158:161], v[188:191], v[38:41]
	v_mfma_f32_16x16x32_bf16 v[38:41], v[168:171], v[192:195], v[38:41]
	v_mfma_f32_16x16x32_bf16 v[34:37], v[172:175], v[188:191], v[34:37]
	v_mfma_f32_16x16x32_bf16 v[34:37], v[176:179], v[192:195], v[34:37]
	v_mfma_f32_16x16x32_bf16 v[22:25], v[158:161], v[196:199], v[22:25]
	v_mfma_f32_16x16x32_bf16 v[22:25], v[168:171], v[200:203], v[22:25]
	v_mfma_f32_16x16x32_bf16 v[18:21], v[172:175], v[196:199], v[18:21]
	v_mfma_f32_16x16x32_bf16 v[18:21], v[176:179], v[200:203], v[18:21]
	v_mfma_f32_16x16x32_bf16 v[6:9], v[158:161], v[224:227], v[6:9]
	v_mfma_f32_16x16x32_bf16 v[6:9], v[168:171], v[228:231], v[6:9]
	v_mfma_f32_16x16x32_bf16 v[2:5], v[172:175], v[224:227], v[2:5]
	v_mfma_f32_16x16x32_bf16 v[2:5], v[176:179], v[228:231], v[2:5]
	s_setprio 0
	s_barrier
	s_add_i32 s15, s15, 2
	s_add_u32 s5, s5, 0x100
	s_addc_u32 s14, s14, 0
	s_cmpk_gt_u32 s15, 0x55
	s_mov_b64 s[50:51], s[52:53]
	s_cbranch_scc0 .LBB0_272
	s_and_b64 vcc, exec, s[42:43]
	s_cbranch_vccz .LBB0_275
	s_barrier

; #define PG8_STAGE(bufoff, gbase, voff) do { _Pragma("unroll") for (int _i = 0; _i < 2; ++_i) \
;         __builtin_amdgcn_global_load_lds((const unsigned*)((const char*)(gbase) + (voff)[_i]), (PG8_LAS unsigned*)(lds + (bufoff) + ldsw + _i * 8192), 16, 0, 0); } while (0)
; #define PG8_LDA(dst, b, h) do { _Pragma("unroll") for (int m = 0; m < 4; ++m) _Pragma("unroll") for (int k = 0; k < 2; ++k) dst[m][k] = *(const PG8_LAS bf16x8*)(lds + PG8_SA(b, h) + aoff + m * 2048 + k * 1024); } while (0)
; #define PG8_LDB(dst, b, h) do { _Pragma("unroll") for (int n = 0; n < 2; ++n) _Pragma("unroll") for (int k = 0; k < 2; ++k) dst[n][k] = *(const PG8_LAS bf16x8*)(lds + PG8_SB(b, h) + boff + n * 2048 + k * 1024); } while (0)
; #define PG8_MMA(ai, bj, At, Bt) do { __builtin_amdgcn_s_setprio(1); _Pragma("unroll") for (int m = 0; m < 4; ++m) _Pragma("unroll") for (int n = 0; n < 2; ++n) _Pragma("unroll") for (int k = 0; k < 2; ++k) \
;         acc[ai][bj][m][n] = __builtin_amdgcn_mfma_f32_16x16x32_bf16(Bt[n][k], At[m][k], acc[ai][bj][m][n], 0, 0, 0); __builtin_amdgcn_s_setprio(0); } while (0)
; #define PG8_WAIT_V(n) asm volatile("s_waitcnt vmcnt(" #n ")" ::: "memory")
; #define PG8_WAIT_L(n) asm volatile("s_waitcnt lgkmcnt(" #n ")" ::: "memory")
; template <class Epi, class Sched, bool ALIGN_EPI = false, bool SP2 = false>
; __device__ __forceinline__ void gemm_phase(PG8_LAS unsigned char* lds, const Gemm g, const Sched S, const Epi E) {
;     ...
;             const bool last = (t == nt - 2);
;             const char* a1 = cA + (size_t)(t + 1) * kstep;
;             const char* a2 = last ? nA : cA + (size_t)(t + 2) * kstep; const char* b2 = last ? nB : cB + (size_t)(t + 2) * kstep;
;             const char* a3 = a2 + kstep; const char* b3 = b2 + kstep;
;             if (last && has_next) S.a_ready(nxt);
;             if constexpr (SP2) {
;             PG8_LDB(B0, 0, 0); PG8_LDB(B1, 0, 1); PG8_SCHED; PG8_LDA(At, 0, 0); PG8_STAGE(PG8_SA(1, 1), a1 + hstep, voffA);
;             PG8_WAIT_V(8); PG8_WAIT_L(0); PG8_BAR; PG8_MMA(0, 0, At, B0); PG8_MMA(0, 1, At, B1); PG8_BAR; PG8_SCHED;
;             PG8_LDA(At, 0, 1); PG8_STAGE(PG8_SB(0, 0), b2, voffB); PG8_STAGE(PG8_SB(0, 1), b2 + hstep, voffB); PG8_STAGE(PG8_SA(0, 0), a2, voffA);
;             PG8_WAIT_V(8); PG8_WAIT_L(0); PG8_BAR; PG8_MMA(1, 0, At, B0); PG8_MMA(1, 1, At, B1); PG8_BAR; PG8_SCHED;
.LBB0_404:
	ds_read_b128 v[194:197], v171
	ds_read_b128 v[198:201], v171 offset:1024
	ds_read_b128 v[224:227], v171 offset:2048
	ds_read_b128 v[228:231], v171 offset:3072
	ds_read_b128 v[232:235], v171 offset:4096
	ds_read_b128 v[236:239], v171 offset:5120
	ds_read_b128 v[240:243], v171 offset:6144
	ds_read_b128 v[244:247], v171 offset:7168
	s_add_u32 s25, s0, 0xfff80080
	s_addc_u32 s26, s1, -1
	s_add_i32 s27, 0, 0x10000
	s_cmp_eq_u32 s24, 28
	s_cselect_b32 s67, s53, s26
	s_cselect_b32 s66, vcc_lo, s25
	v_add_u32_e32 v152, s27, v155
	s_cselect_b32 s65, s45, s15
	s_cselect_b32 s64, vcc_hi, s14
	s_add_i32 s25, 0, 0x14000
	ds_read_b128 v[130:133], v152
	ds_read_b128 v[134:137], v152 offset:1024
	ds_read_b128 v[148:151], v152 offset:2048
	ds_read_b128 v[174:177], v152 offset:3072
	v_add_u32_e32 v152, s25, v155
	ds_read_b128 v[178:181], v152
	ds_read_b128 v[182:185], v152 offset:1024
	ds_read_b128 v[186:189], v152 offset:2048
	ds_read_b128 v[190:193], v152 offset:3072
	v_lshl_add_u64 v[152:153], s[0:1], 0, v[144:145]
	s_add_i32 m0, s21, 0xc000
	s_nop 0
	global_load_lds_dwordx4 v[152:153], off
	v_lshl_add_u64 v[152:153], s[0:1], 0, v[146:147]
	s_add_i32 m0, s21, 0xe000
	s_nop 0
	global_load_lds_dwordx4 v[152:153], off
	s_waitcnt vmcnt(8) lgkmcnt(0)
	s_barrier
	s_setprio 1
	v_mfma_f32_16x16x32_bf16 v[126:129], v[130:133], v[194:197], v[126:129]
	v_mfma_f32_16x16x32_bf16 v[126:129], v[134:137], v[198:201], v[126:129]
	v_mfma_f32_16x16x32_bf16 v[122:125], v[148:151], v[194:197], v[122:125]
	v_mfma_f32_16x16x32_bf16 v[122:125], v[174:177], v[198:201], v[122:125]
	v_mfma_f32_16x16x32_bf16 v[118:121], v[130:133], v[224:227], v[118:121]
	v_mfma_f32_16x16x32_bf16 v[118:121], v[134:137], v[228:231], v[118:121]
	v_mfma_f32_16x16x32_bf16 v[110:113], v[148:151], v[224:227], v[110:113]
	v_mfma_f32_16x16x32_bf16 v[110:113], v[174:177], v[228:231], v[110:113]
	v_mfma_f32_16x16x32_bf16 v[102:105], v[130:133], v[232:235], v[102:105]
	v_mfma_f32_16x16x32_bf16 v[102:105], v[134:137], v[236:239], v[102:105]
	v_mfma_f32_16x16x32_bf16 v[94:97], v[148:151], v[232:235], v[94:97]
	v_mfma_f32_16x16x32_bf16 v[94:97], v[174:177], v[236:239], v[94:97]
	v_mfma_f32_16x16x32_bf16 v[86:89], v[130:133], v[240:243], v[86:89]
	v_mfma_f32_16x16x32_bf16 v[86:89], v[134:137], v[244:247], v[86:89]
	v_mfma_f32_16x16x32_bf16 v[78:81], v[148:151], v[240:243], v[78:81]
	v_mfma_f32_16x16x32_bf16 v[78:81], v[174:177], v[244:247], v[78:81]
	v_mfma_f32_16x16x32_bf16 v[114:117], v[178:181], v[194:197], v[114:117]
	v_mfma_f32_16x16x32_bf16 v[114:117], v[182:185], v[198:201], v[114:117]
	v_mfma_f32_16x16x32_bf16 v[106:109], v[186:189], v[194:197], v[106:109]
	v_mfma_f32_16x16x32_bf16 v[106:109], v[190:193], v[198:201], v[106:109]
	v_mfma_f32_16x16x32_bf16 v[98:101], v[178:181], v[224:227], v[98:101]
	v_mfma_f32_16x16x32_bf16 v[98:101], v[182:185], v[228:231], v[98:101]
	v_mfma_f32_16x16x32_bf16 v[90:93], v[186:189], v[224:227], v[90:93]
	v_mfma_f32_16x16x32_bf16 v[90:93], v[190:193], v[228:231], v[90:93]
	v_mfma_f32_16x16x32_bf16 v[82:85], v[178:181], v[232:235], v[82:85]
	v_mfma_f32_16x16x32_bf16 v[82:85], v[182:185], v[236:239], v[82:85]
	v_mfma_f32_16x16x32_bf16 v[74:77], v[186:189], v[232:235], v[74:77]
	v_mfma_f32_16x16x32_bf16 v[74:77], v[190:193], v[236:239], v[74:77]
	v_mfma_f32_16x16x32_bf16 v[70:73], v[178:181], v[240:243], v[70:73]
	v_mfma_f32_16x16x32_bf16 v[70:73], v[182:185], v[244:247], v[70:73]
	v_mfma_f32_16x16x32_bf16 v[66:69], v[186:189], v[240:243], v[66:69]
	v_mfma_f32_16x16x32_bf16 v[66:69], v[190:193], v[244:247], v[66:69]
	s_setprio 0
	s_barrier
	ds_read_b128 v[194:197], v171 offset:16384
	ds_read_b128 v[198:201], v171 offset:17408
	ds_read_b128 v[224:227], v171 offset:18432
	ds_read_b128 v[228:231], v171 offset:19456
	ds_read_b128 v[232:235], v171 offset:20480
	ds_read_b128 v[236:239], v171 offset:21504
	ds_read_b128 v[240:243], v171 offset:22528
	ds_read_b128 v[244:247], v171 offset:23552
	s_add_i32 s26, s27, s16
	v_lshl_add_u64 v[152:153], s[64:65], 0, v[0:1]
	s_mov_b32 m0, s26
	s_nop 0
	global_load_lds_dwordx4 v[152:153], off
	s_add_i32 m0, s26, 0x2000
	s_add_u32 s26, s64, 0x80000
	v_lshl_add_u64 v[202:203], s[64:65], 0, v[138:139]
	s_addc_u32 s27, s65, 0
	s_add_i32 s25, s25, s16
	global_load_lds_dwordx4 v[202:203], off
	v_lshl_add_u64 v[248:249], s[26:27], 0, v[0:1]
	s_mov_b32 m0, s25
	v_lshl_add_u64 v[250:251], s[66:67], 0, v[140:141]
	global_load_lds_dwordx4 v[248:249], off
	v_lshl_add_u64 v[248:249], s[26:27], 0, v[138:139]
	s_add_i32 m0, s25, 0x2000
	s_nop 0
	global_load_lds_dwordx4 v[248:249], off
	v_lshl_add_u64 v[248:249], s[66:67], 0, v[142:143]
	s_mov_b32 m0, s21
	s_nop 0
	global_load_lds_dwordx4 v[248:249], off
	s_mov_b32 m0, s22
	s_nop 0
	global_load_lds_dwordx4 v[250:251], off
	s_waitcnt vmcnt(8) lgkmcnt(0)
	s_barrier
; #define PG8_STAGE(bufoff, gbase, voff) do { _Pragma("unroll") for (int _i = 0; _i < 2; ++_i) \
;         __builtin_amdgcn_global_load_lds((const unsigned*)((const char*)(gbase) + (voff)[_i]), (PG8_LAS unsigned*)(lds + (bufoff) + ldsw + _i * 8192), 16, 0, 0); } while (0)
; #define PG8_LDA(dst, b, h) do { _Pragma("unroll") for (int m = 0; m < 4; ++m) _Pragma("unroll") for (int k = 0; k < 2; ++k) dst[m][k] = *(const PG8_LAS bf16x8*)(lds + PG8_SA(b, h) + aoff + m * 2048 + k * 1024); } while (0)
; #define PG8_LDB(dst, b, h) do { _Pragma("unroll") for (int n = 0; n < 2; ++n) _Pragma("unroll") for (int k = 0; k < 2; ++k) dst[n][k] = *(const PG8_LAS bf16x8*)(lds + PG8_SB(b, h) + boff + n * 2048 + k * 1024); } while (0)
; #define PG8_MMA(ai, bj, At, Bt) do { __builtin_amdgcn_s_setprio(1); _Pragma("unroll") for (int m = 0; m < 4; ++m) _Pragma("unroll") for (int n = 0; n < 2; ++n) _Pragma("unroll") for (int k = 0; k < 2; ++k) \
;         acc[ai][bj][m][n] = __builtin_amdgcn_mfma_f32_16x16x32_bf16(Bt[n][k], At[m][k], acc[ai][bj][m][n], 0, 0, 0); __builtin_amdgcn_s_setprio(0); } while (0)
; #define PG8_WAIT_V(n) asm volatile("s_waitcnt vmcnt(" #n ")" ::: "memory")
; #define PG8_WAIT_L(n) asm volatile("s_waitcnt lgkmcnt(" #n ")" ::: "memory")
; #define PG8_BAR __builtin_amdgcn_s_barrier()
; #define PG8_SCHED __builtin_amdgcn_sched_barrier(0)
; template <class Epi, class Sched, bool ALIGN_EPI = false, bool SP2 = false>
; __device__ __forceinline__ void gemm_phase(PG8_LAS unsigned char* lds, const Gemm g, const Sched S, const Epi E) {
;     ...
;             PG8_WAIT_V(8); PG8_WAIT_L(0); PG8_BAR; PG8_MMA(1, 0, At, B0); PG8_MMA(1, 1, At, B1); PG8_BAR; PG8_SCHED;
;             PG8_LDB(B0, 1, 0); PG8_LDB(B1, 1, 1); PG8_SCHED; PG8_LDA(At, 1, 0); PG8_STAGE(PG8_SA(0, 1), a2 + hstep, voffA);
;             PG8_WAIT_V(8); PG8_WAIT_L(0); PG8_BAR; PG8_MMA(0, 0, At, B0); PG8_MMA(0, 1, At, B1); PG8_BAR; PG8_SCHED;
	s_setprio 1
	v_mfma_f32_16x16x32_bf16 v[62:65], v[130:133], v[194:197], v[62:65]
	v_mfma_f32_16x16x32_bf16 v[62:65], v[134:137], v[198:201], v[62:65]
	v_mfma_f32_16x16x32_bf16 v[58:61], v[148:151], v[194:197], v[58:61]
	v_mfma_f32_16x16x32_bf16 v[58:61], v[174:177], v[198:201], v[58:61]
	v_mfma_f32_16x16x32_bf16 v[54:57], v[130:133], v[224:227], v[54:57]
	v_mfma_f32_16x16x32_bf16 v[54:57], v[134:137], v[228:231], v[54:57]
	v_mfma_f32_16x16x32_bf16 v[46:49], v[148:151], v[224:227], v[46:49]
	v_mfma_f32_16x16x32_bf16 v[46:49], v[174:177], v[228:231], v[46:49]
	v_mfma_f32_16x16x32_bf16 v[38:41], v[130:133], v[232:235], v[38:41]
	v_mfma_f32_16x16x32_bf16 v[38:41], v[134:137], v[236:239], v[38:41]
	v_mfma_f32_16x16x32_bf16 v[30:33], v[148:151], v[232:235], v[30:33]
	v_mfma_f32_16x16x32_bf16 v[30:33], v[174:177], v[236:239], v[30:33]
	v_mfma_f32_16x16x32_bf16 v[22:25], v[130:133], v[240:243], v[22:25]
	v_mfma_f32_16x16x32_bf16 v[22:25], v[134:137], v[244:247], v[22:25]
	v_mfma_f32_16x16x32_bf16 v[14:17], v[148:151], v[240:243], v[14:17]
	v_mfma_f32_16x16x32_bf16 v[14:17], v[174:177], v[244:247], v[14:17]
	v_mfma_f32_16x16x32_bf16 v[50:53], v[178:181], v[194:197], v[50:53]
	v_mfma_f32_16x16x32_bf16 v[50:53], v[182:185], v[198:201], v[50:53]
	v_mfma_f32_16x16x32_bf16 v[42:45], v[186:189], v[194:197], v[42:45]
	v_mfma_f32_16x16x32_bf16 v[42:45], v[190:193], v[198:201], v[42:45]
	v_mfma_f32_16x16x32_bf16 v[34:37], v[178:181], v[224:227], v[34:37]
	v_mfma_f32_16x16x32_bf16 v[34:37], v[182:185], v[228:231], v[34:37]
	v_mfma_f32_16x16x32_bf16 v[26:29], v[186:189], v[224:227], v[26:29]
	v_mfma_f32_16x16x32_bf16 v[26:29], v[190:193], v[228:231], v[26:29]
	v_mfma_f32_16x16x32_bf16 v[18:21], v[178:181], v[232:235], v[18:21]
	v_mfma_f32_16x16x32_bf16 v[18:21], v[182:185], v[236:239], v[18:21]
	v_mfma_f32_16x16x32_bf16 v[10:13], v[186:189], v[232:235], v[10:13]
	v_mfma_f32_16x16x32_bf16 v[10:13], v[190:193], v[236:239], v[10:13]
	v_mfma_f32_16x16x32_bf16 v[6:9], v[178:181], v[240:243], v[6:9]
	v_mfma_f32_16x16x32_bf16 v[6:9], v[182:185], v[244:247], v[6:9]
	v_mfma_f32_16x16x32_bf16 v[2:5], v[186:189], v[240:243], v[2:5]
	v_mfma_f32_16x16x32_bf16 v[2:5], v[190:193], v[244:247], v[2:5]
	s_setprio 0
	s_barrier
	ds_read_b128 v[194:197], v171 offset:32768
	ds_read_b128 v[198:201], v171 offset:33792
	ds_read_b128 v[224:227], v171 offset:34816
	ds_read_b128 v[228:231], v171 offset:35840
	ds_read_b128 v[232:235], v171 offset:36864
	ds_read_b128 v[236:239], v171 offset:37888
	ds_read_b128 v[240:243], v171 offset:38912
	ds_read_b128 v[244:247], v171 offset:39936
	s_add_i32 s25, 0, 0x18000
	v_add_u32_e32 v173, s25, v155
	s_add_i32 s30, 0, 0x1c000
	ds_read_b128 v[130:133], v173
	ds_read_b128 v[134:137], v173 offset:1024
	ds_read_b128 v[148:151], v173 offset:2048
	ds_read_b128 v[174:177], v173 offset:3072
	v_add_u32_e32 v173, s30, v155
	ds_read_b128 v[178:181], v173
	ds_read_b128 v[182:185], v173 offset:1024
	ds_read_b128 v[186:189], v173 offset:2048
	ds_read_b128 v[190:193], v173 offset:3072
	s_add_u32 s26, s66, 0x80000
	s_addc_u32 s27, s67, 0
	s_mov_b32 m0, s47
	v_lshl_add_u64 v[214:215], s[26:27], 0, v[142:143]
	global_load_lds_dwordx4 v[214:215], off
	v_lshl_add_u64 v[214:215], s[26:27], 0, v[140:141]
	s_mov_b32 m0, s62
	s_nop 0
	global_load_lds_dwordx4 v[214:215], off
	s_waitcnt vmcnt(8) lgkmcnt(0)
	s_barrier
	s_setprio 1
	v_mfma_f32_16x16x32_bf16 v[126:129], v[130:133], v[194:197], v[126:129]
	v_mfma_f32_16x16x32_bf16 v[126:129], v[134:137], v[198:201], v[126:129]
	v_mfma_f32_16x16x32_bf16 v[122:125], v[148:151], v[194:197], v[122:125]
	v_mfma_f32_16x16x32_bf16 v[122:125], v[174:177], v[198:201], v[122:125]
	v_mfma_f32_16x16x32_bf16 v[118:121], v[130:133], v[224:227], v[118:121]
	v_mfma_f32_16x16x32_bf16 v[118:121], v[134:137], v[228:231], v[118:121]
	v_mfma_f32_16x16x32_bf16 v[110:113], v[148:151], v[224:227], v[110:113]
	v_mfma_f32_16x16x32_bf16 v[110:113], v[174:177], v[228:231], v[110:113]
	v_mfma_f32_16x16x32_bf16 v[102:105], v[130:133], v[232:235], v[102:105]
	v_mfma_f32_16x16x32_bf16 v[102:105], v[134:137], v[236:239], v[102:105]
	v_mfma_f32_16x16x32_bf16 v[94:97], v[148:151], v[232:235], v[94:97]
	v_mfma_f32_16x16x32_bf16 v[94:97], v[174:177], v[236:239], v[94:97]
	v_mfma_f32_16x16x32_bf16 v[86:89], v[130:133], v[240:243], v[86:89]
	v_mfma_f32_16x16x32_bf16 v[86:89], v[134:137], v[244:247], v[86:89]
	v_mfma_f32_16x16x32_bf16 v[78:81], v[148:151], v[240:243], v[78:81]
	v_mfma_f32_16x16x32_bf16 v[78:81], v[174:177], v[244:247], v[78:81]
	v_mfma_f32_16x16x32_bf16 v[114:117], v[178:181], v[194:197], v[114:117]
	v_mfma_f32_16x16x32_bf16 v[114:117], v[182:185], v[198:201], v[114:117]
	v_mfma_f32_16x16x32_bf16 v[106:109], v[186:189], v[194:197], v[106:109]
	v_mfma_f32_16x16x32_bf16 v[106:109], v[190:193], v[198:201], v[106:109]
	v_mfma_f32_16x16x32_bf16 v[98:101], v[178:181], v[224:227], v[98:101]
	v_mfma_f32_16x16x32_bf16 v[98:101], v[182:185], v[228:231], v[98:101]
	v_mfma_f32_16x16x32_bf16 v[90:93], v[186:189], v[224:227], v[90:93]
	v_mfma_f32_16x16x32_bf16 v[90:93], v[190:193], v[228:231], v[90:93]
	v_mfma_f32_16x16x32_bf16 v[82:85], v[178:181], v[232:235], v[82:85]
	v_mfma_f32_16x16x32_bf16 v[82:85], v[182:185], v[236:239], v[82:85]
	v_mfma_f32_16x16x32_bf16 v[74:77], v[186:189], v[232:235], v[74:77]
	v_mfma_f32_16x16x32_bf16 v[74:77], v[190:193], v[236:239], v[74:77]
	v_mfma_f32_16x16x32_bf16 v[70:73], v[178:181], v[240:243], v[70:73]
	v_mfma_f32_16x16x32_bf16 v[70:73], v[182:185], v[244:247], v[70:73]
	v_mfma_f32_16x16x32_bf16 v[66:69], v[186:189], v[240:243], v[66:69]
	v_mfma_f32_16x16x32_bf16 v[66:69], v[190:193], v[244:247], v[66:69]
	s_setprio 0
	s_barrier
; #define PG8_STAGE(bufoff, gbase, voff) do { _Pragma("unroll") for (int _i = 0; _i < 2; ++_i) \
;         __builtin_amdgcn_global_load_lds((const unsigned*)((const char*)(gbase) + (voff)[_i]), (PG8_LAS unsigned*)(lds + (bufoff) + ldsw + _i * 8192), 16, 0, 0); } while (0)
; #define PG8_LDA(dst, b, h) do { _Pragma("unroll") for (int m = 0; m < 4; ++m) _Pragma("unroll") for (int k = 0; k < 2; ++k) dst[m][k] = *(const PG8_LAS bf16x8*)(lds + PG8_SA(b, h) + aoff + m * 2048 + k * 1024); } while (0)
; #define PG8_MMA(ai, bj, At, Bt) do { __builtin_amdgcn_s_setprio(1); _Pragma("unroll") for (int m = 0; m < 4; ++m) _Pragma("unroll") for (int n = 0; n < 2; ++n) _Pragma("unroll") for (int k = 0; k < 2; ++k) \
;         acc[ai][bj][m][n] = __builtin_amdgcn_mfma_f32_16x16x32_bf16(Bt[n][k], At[m][k], acc[ai][bj][m][n], 0, 0, 0); __builtin_amdgcn_s_setprio(0); } while (0)
; #define PG8_WAIT_V(n) asm volatile("s_waitcnt vmcnt(" #n ")" ::: "memory")
; #define PG8_WAIT_L(n) asm volatile("s_waitcnt lgkmcnt(" #n ")" ::: "memory")
; #define PG8_BAR __builtin_amdgcn_s_barrier()
; #define PG8_SCHED __builtin_amdgcn_sched_barrier(0)
; template <class Epi, class Sched, bool ALIGN_EPI = false, bool SP2 = false>
; __device__ __forceinline__ void gemm_phase(PG8_LAS unsigned char* lds, const Gemm g, const Sched S, const Epi E) {
;     ...
;             PG8_LDA(At, 1, 1); PG8_STAGE(PG8_SB(1, 0), b3, voffB); PG8_STAGE(PG8_SB(1, 1), b3 + hstep, voffB); PG8_STAGE(PG8_SA(1, 0), a3, voffA);
;             PG8_WAIT_V(8); PG8_WAIT_L(0); PG8_BAR; PG8_MMA(1, 0, At, B0); PG8_MMA(1, 1, At, B1); PG8_BAR; PG8_SCHED;
;     ...
;         if constexpr (ALIGN_EPI) { if (wr == 0) PG8_BAR; }
	ds_read_b128 v[194:197], v171 offset:49152
	ds_read_b128 v[198:201], v171 offset:50176
	ds_read_b128 v[224:227], v171 offset:51200
	ds_read_b128 v[228:231], v171 offset:52224
	ds_read_b128 v[232:235], v171 offset:53248
	ds_read_b128 v[236:239], v171 offset:54272
	ds_read_b128 v[240:243], v171 offset:55296
	ds_read_b128 v[244:247], v171 offset:56320
	s_add_i32 s25, s25, s16
	v_lshl_add_u64 v[152:153], v[152:153], 0, s[28:29]
	s_mov_b32 m0, s25
	s_nop 0
	global_load_lds_dwordx4 v[152:153], off
	s_add_i32 m0, s25, 0x2000
	s_add_u32 s26, s64, 0x80080
	v_lshl_add_u64 v[152:153], v[202:203], 0, s[28:29]
	s_addc_u32 s27, s65, 0
	s_add_i32 s25, s30, s16
	global_load_lds_dwordx4 v[152:153], off
	v_lshl_add_u64 v[152:153], s[26:27], 0, v[0:1]
	s_mov_b32 m0, s25
	s_nop 0
	global_load_lds_dwordx4 v[152:153], off
	v_lshl_add_u64 v[152:153], s[26:27], 0, v[138:139]
	s_add_i32 m0, s25, 0x2000
	s_nop 0
	global_load_lds_dwordx4 v[152:153], off
	v_lshl_add_u64 v[152:153], v[248:249], 0, s[28:29]
	s_mov_b32 m0, s63
	s_nop 0
	global_load_lds_dwordx4 v[152:153], off
	v_lshl_add_u64 v[152:153], v[250:251], 0, s[28:29]
	s_mov_b32 m0, s74
	s_nop 0
	global_load_lds_dwordx4 v[152:153], off
	s_waitcnt vmcnt(8) lgkmcnt(0)
	s_barrier
	s_setprio 1
	v_mfma_f32_16x16x32_bf16 v[62:65], v[130:133], v[194:197], v[62:65]
	v_mfma_f32_16x16x32_bf16 v[62:65], v[134:137], v[198:201], v[62:65]
	v_mfma_f32_16x16x32_bf16 v[58:61], v[148:151], v[194:197], v[58:61]
	v_mfma_f32_16x16x32_bf16 v[58:61], v[174:177], v[198:201], v[58:61]
	v_mfma_f32_16x16x32_bf16 v[54:57], v[130:133], v[224:227], v[54:57]
	v_mfma_f32_16x16x32_bf16 v[54:57], v[134:137], v[228:231], v[54:57]
	v_mfma_f32_16x16x32_bf16 v[46:49], v[148:151], v[224:227], v[46:49]
	v_mfma_f32_16x16x32_bf16 v[46:49], v[174:177], v[228:231], v[46:49]
	v_mfma_f32_16x16x32_bf16 v[38:41], v[130:133], v[232:235], v[38:41]
	v_mfma_f32_16x16x32_bf16 v[38:41], v[134:137], v[236:239], v[38:41]
	v_mfma_f32_16x16x32_bf16 v[30:33], v[148:151], v[232:235], v[30:33]
	v_mfma_f32_16x16x32_bf16 v[30:33], v[174:177], v[236:239], v[30:33]
	v_mfma_f32_16x16x32_bf16 v[22:25], v[130:133], v[240:243], v[22:25]
	v_mfma_f32_16x16x32_bf16 v[22:25], v[134:137], v[244:247], v[22:25]
	v_mfma_f32_16x16x32_bf16 v[14:17], v[148:151], v[240:243], v[14:17]
	v_mfma_f32_16x16x32_bf16 v[14:17], v[174:177], v[244:247], v[14:17]
	v_mfma_f32_16x16x32_bf16 v[50:53], v[178:181], v[194:197], v[50:53]
	v_mfma_f32_16x16x32_bf16 v[50:53], v[182:185], v[198:201], v[50:53]
	v_mfma_f32_16x16x32_bf16 v[42:45], v[186:189], v[194:197], v[42:45]
	v_mfma_f32_16x16x32_bf16 v[42:45], v[190:193], v[198:201], v[42:45]
	v_mfma_f32_16x16x32_bf16 v[34:37], v[178:181], v[224:227], v[34:37]
	v_mfma_f32_16x16x32_bf16 v[34:37], v[182:185], v[228:231], v[34:37]
	v_mfma_f32_16x16x32_bf16 v[26:29], v[186:189], v[224:227], v[26:29]
	v_mfma_f32_16x16x32_bf16 v[26:29], v[190:193], v[228:231], v[26:29]
	v_mfma_f32_16x16x32_bf16 v[18:21], v[178:181], v[232:235], v[18:21]
	v_mfma_f32_16x16x32_bf16 v[18:21], v[182:185], v[236:239], v[18:21]
	v_mfma_f32_16x16x32_bf16 v[10:13], v[186:189], v[232:235], v[10:13]
	v_mfma_f32_16x16x32_bf16 v[10:13], v[190:193], v[236:239], v[10:13]
	v_mfma_f32_16x16x32_bf16 v[6:9], v[178:181], v[240:243], v[6:9]
	v_mfma_f32_16x16x32_bf16 v[6:9], v[182:185], v[244:247], v[6:9]
	v_mfma_f32_16x16x32_bf16 v[2:5], v[186:189], v[240:243], v[2:5]
	v_mfma_f32_16x16x32_bf16 v[2:5], v[190:193], v[244:247], v[2:5]
	s_setprio 0
	s_barrier
	s_add_i32 s24, s24, 2
	s_add_u32 s0, s0, 0x100
	s_addc_u32 s1, s1, 0
	s_add_u32 s14, s14, 0x100
	s_addc_u32 s15, s15, 0
	s_cmp_gt_u32 s24, 29
	s_cbranch_scc0 .LBB0_404
	s_and_b64 vcc, exec, s[8:9]
	s_cbranch_vccz .LBB0_407
	s_barrier

; #define PG8_STAGE(bufoff, gbase, voff) do { _Pragma("unroll") for (int _i = 0; _i < 2; ++_i) \
;         __builtin_amdgcn_global_load_lds((const unsigned*)((const char*)(gbase) + (voff)[_i]), (PG8_LAS unsigned*)(lds + (bufoff) + ldsw + _i * 8192), 16, 0, 0); } while (0)
; #define PG8_LDA(dst, b, h) do { _Pragma("unroll") for (int m = 0; m < 4; ++m) _Pragma("unroll") for (int k = 0; k < 2; ++k) dst[m][k] = *(const PG8_LAS bf16x8*)(lds + PG8_SA(b, h) + aoff + m * 2048 + k * 1024); } while (0)
; #define PG8_LDB(dst, b, h) do { _Pragma("unroll") for (int n = 0; n < 2; ++n) _Pragma("unroll") for (int k = 0; k < 2; ++k) dst[n][k] = *(const PG8_LAS bf16x8*)(lds + PG8_SB(b, h) + boff + n * 2048 + k * 1024); } while (0)
; #define PG8_MMA(ai, bj, At, Bt) do { __builtin_amdgcn_s_setprio(1); _Pragma("unroll") for (int m = 0; m < 4; ++m) _Pragma("unroll") for (int n = 0; n < 2; ++n) _Pragma("unroll") for (int k = 0; k < 2; ++k) \
;         acc[ai][bj][m][n] = __builtin_amdgcn_mfma_f32_16x16x32_bf16(Bt[n][k], At[m][k], acc[ai][bj][m][n], 0, 0, 0); __builtin_amdgcn_s_setprio(0); } while (0)
; #define PG8_WAIT_V(n) asm volatile("s_waitcnt vmcnt(" #n ")" ::: "memory")
; #define PG8_WAIT_L(n) asm volatile("s_waitcnt lgkmcnt(" #n ")" ::: "memory")
; template <class Epi, class Sched, bool ALIGN_EPI = false, bool SP2 = false>
; __device__ __forceinline__ void gemm_phase(PG8_LAS unsigned char* lds, const Gemm g, const Sched S, const Epi E) {
;     ...
;             const bool last = (t == nt - 2);
;             const char* a1 = cA + (size_t)(t + 1) * kstep;
;             const char* a2 = last ? nA : cA + (size_t)(t + 2) * kstep; const char* b2 = last ? nB : cB + (size_t)(t + 2) * kstep;
;             const char* a3 = a2 + kstep; const char* b3 = b2 + kstep;
;             if (last && has_next) S.a_ready(nxt);
;             if constexpr (SP2) {
;             PG8_LDB(B0, 0, 0); PG8_LDB(B1, 0, 1); PG8_SCHED; PG8_LDA(At, 0, 0); PG8_STAGE(PG8_SA(1, 1), a1 + hstep, voffA);
;             PG8_WAIT_V(8); PG8_WAIT_L(0); PG8_BAR; PG8_MMA(0, 0, At, B0); PG8_MMA(0, 1, At, B1); PG8_BAR; PG8_SCHED;
;             PG8_LDA(At, 0, 1); PG8_STAGE(PG8_SB(0, 0), b2, voffB); PG8_STAGE(PG8_SB(0, 1), b2 + hstep, voffB); PG8_STAGE(PG8_SA(0, 0), a2, voffA);
;             PG8_WAIT_V(8); PG8_WAIT_L(0); PG8_BAR; PG8_MMA(1, 0, At, B0); PG8_MMA(1, 1, At, B1); PG8_BAR; PG8_SCHED;
.LBB0_654:
	ds_read_b128 v[180:183], v145
	ds_read_b128 v[184:187], v145 offset:1024
	ds_read_b128 v[188:191], v145 offset:2048
	ds_read_b128 v[192:195], v145 offset:3072
	ds_read_b128 v[196:199], v145 offset:4096
	ds_read_b128 v[200:203], v145 offset:5120
	ds_read_b128 v[224:227], v145 offset:6144
	ds_read_b128 v[228:231], v145 offset:7168
	s_add_u32 s64, s58, 0x100
	s_addc_u32 s65, s59, 0
	s_add_i32 s25, 0, 0x10000
	s_cmp_eq_u32 s24, 12
	s_cselect_b32 vcc_hi, s45, s65
	s_cselect_b32 vcc_lo, s77, s64
	v_add_u32_e32 v140, s25, v143
	s_cselect_b32 s67, s43, s15
	s_cselect_b32 s66, s36, s14
	s_add_i32 s30, 0, 0x14000
	ds_read_b128 v[136:139], v140
	ds_read_b128 v[146:149], v140 offset:1024
	ds_read_b128 v[150:153], v140 offset:2048
	ds_read_b128 v[154:157], v140 offset:3072
	v_add_u32_e32 v140, s30, v143
	ds_read_b128 v[158:161], v140
	ds_read_b128 v[168:171], v140 offset:1024
	ds_read_b128 v[172:175], v140 offset:2048
	ds_read_b128 v[176:179], v140 offset:3072
	v_lshl_add_u64 v[140:141], s[58:59], 0, v[132:133]
	s_add_i32 m0, s21, 0xc000
	s_nop 0
	global_load_lds_dwordx4 v[140:141], off
	v_lshl_add_u64 v[140:141], s[58:59], 0, v[134:135]
	s_add_i32 m0, s21, 0xe000
	s_nop 0
	global_load_lds_dwordx4 v[140:141], off
	s_waitcnt vmcnt(8) lgkmcnt(0)
	s_barrier
	s_setprio 1
	v_mfma_f32_16x16x32_bf16 v[126:129], v[136:139], v[180:183], v[126:129]
	v_mfma_f32_16x16x32_bf16 v[126:129], v[146:149], v[184:187], v[126:129]
	v_mfma_f32_16x16x32_bf16 v[122:125], v[150:153], v[180:183], v[122:125]
	v_mfma_f32_16x16x32_bf16 v[122:125], v[154:157], v[184:187], v[122:125]
	v_mfma_f32_16x16x32_bf16 v[110:113], v[136:139], v[188:191], v[110:113]
	v_mfma_f32_16x16x32_bf16 v[110:113], v[146:149], v[192:195], v[110:113]
	v_mfma_f32_16x16x32_bf16 v[106:109], v[150:153], v[188:191], v[106:109]
	v_mfma_f32_16x16x32_bf16 v[106:109], v[154:157], v[192:195], v[106:109]
	v_mfma_f32_16x16x32_bf16 v[94:97], v[136:139], v[196:199], v[94:97]
	v_mfma_f32_16x16x32_bf16 v[94:97], v[146:149], v[200:203], v[94:97]
	v_mfma_f32_16x16x32_bf16 v[90:93], v[150:153], v[196:199], v[90:93]
	v_mfma_f32_16x16x32_bf16 v[90:93], v[154:157], v[200:203], v[90:93]
	v_mfma_f32_16x16x32_bf16 v[78:81], v[136:139], v[224:227], v[78:81]
	v_mfma_f32_16x16x32_bf16 v[78:81], v[146:149], v[228:231], v[78:81]
	v_mfma_f32_16x16x32_bf16 v[74:77], v[150:153], v[224:227], v[74:77]
	v_mfma_f32_16x16x32_bf16 v[74:77], v[154:157], v[228:231], v[74:77]
	v_mfma_f32_16x16x32_bf16 v[118:121], v[158:161], v[180:183], v[118:121]
	v_mfma_f32_16x16x32_bf16 v[118:121], v[168:171], v[184:187], v[118:121]
	v_mfma_f32_16x16x32_bf16 v[114:117], v[172:175], v[180:183], v[114:117]
	v_mfma_f32_16x16x32_bf16 v[114:117], v[176:179], v[184:187], v[114:117]
	v_mfma_f32_16x16x32_bf16 v[102:105], v[158:161], v[188:191], v[102:105]
	v_mfma_f32_16x16x32_bf16 v[102:105], v[168:171], v[192:195], v[102:105]
	v_mfma_f32_16x16x32_bf16 v[98:101], v[172:175], v[188:191], v[98:101]
	v_mfma_f32_16x16x32_bf16 v[98:101], v[176:179], v[192:195], v[98:101]
	v_mfma_f32_16x16x32_bf16 v[86:89], v[158:161], v[196:199], v[86:89]
	v_mfma_f32_16x16x32_bf16 v[86:89], v[168:171], v[200:203], v[86:89]
	v_mfma_f32_16x16x32_bf16 v[82:85], v[172:175], v[196:199], v[82:85]
	v_mfma_f32_16x16x32_bf16 v[82:85], v[176:179], v[200:203], v[82:85]
	v_mfma_f32_16x16x32_bf16 v[70:73], v[158:161], v[224:227], v[70:73]
	v_mfma_f32_16x16x32_bf16 v[70:73], v[168:171], v[228:231], v[70:73]
	v_mfma_f32_16x16x32_bf16 v[66:69], v[172:175], v[224:227], v[66:69]
	v_mfma_f32_16x16x32_bf16 v[66:69], v[176:179], v[228:231], v[66:69]
	s_setprio 0
	s_barrier
	ds_read_b128 v[180:183], v145 offset:16384
	ds_read_b128 v[184:187], v145 offset:17408
	ds_read_b128 v[188:191], v145 offset:18432
	ds_read_b128 v[192:195], v145 offset:19456
	ds_read_b128 v[196:199], v145 offset:20480
	ds_read_b128 v[200:203], v145 offset:21504
	ds_read_b128 v[224:227], v145 offset:22528
	ds_read_b128 v[228:231], v145 offset:23552
	s_add_i32 s25, s25, s16
	v_lshl_add_u64 v[140:141], s[66:67], 0, v[0:1]
	s_mov_b32 m0, s25
	s_nop 0
	global_load_lds_dwordx4 v[140:141], off
	s_add_i32 m0, s25, 0x2000
	s_add_u32 s26, s66, 0x40000
	v_lshl_add_u64 v[214:215], s[66:67], 0, v[130:131]
	s_addc_u32 s27, s67, 0
	s_add_i32 s25, s30, s16
	global_load_lds_dwordx4 v[214:215], off
	v_lshl_add_u64 v[232:233], s[26:27], 0, v[0:1]
	s_mov_b32 m0, s25
	v_lshl_add_u64 v[234:235], vcc, 0, v[130:131]
	global_load_lds_dwordx4 v[232:233], off
	v_lshl_add_u64 v[232:233], s[26:27], 0, v[130:131]
	s_add_i32 m0, s25, 0x2000
	s_nop 0
	global_load_lds_dwordx4 v[232:233], off
	v_lshl_add_u64 v[232:233], vcc, 0, v[0:1]
	s_mov_b32 m0, s21
	s_nop 0
	global_load_lds_dwordx4 v[232:233], off
	s_mov_b32 m0, s22
	s_nop 0
	global_load_lds_dwordx4 v[234:235], off
	s_waitcnt vmcnt(8) lgkmcnt(0)
	s_barrier
; #define PG8_STAGE(bufoff, gbase, voff) do { _Pragma("unroll") for (int _i = 0; _i < 2; ++_i) \
;         __builtin_amdgcn_global_load_lds((const unsigned*)((const char*)(gbase) + (voff)[_i]), (PG8_LAS unsigned*)(lds + (bufoff) + ldsw + _i * 8192), 16, 0, 0); } while (0)
; #define PG8_LDA(dst, b, h) do { _Pragma("unroll") for (int m = 0; m < 4; ++m) _Pragma("unroll") for (int k = 0; k < 2; ++k) dst[m][k] = *(const PG8_LAS bf16x8*)(lds + PG8_SA(b, h) + aoff + m * 2048 + k * 1024); } while (0)
; #define PG8_LDB(dst, b, h) do { _Pragma("unroll") for (int n = 0; n < 2; ++n) _Pragma("unroll") for (int k = 0; k < 2; ++k) dst[n][k] = *(const PG8_LAS bf16x8*)(lds + PG8_SB(b, h) + boff + n * 2048 + k * 1024); } while (0)
; #define PG8_MMA(ai, bj, At, Bt) do { __builtin_amdgcn_s_setprio(1); _Pragma("unroll") for (int m = 0; m < 4; ++m) _Pragma("unroll") for (int n = 0; n < 2; ++n) _Pragma("unroll") for (int k = 0; k < 2; ++k) \
;         acc[ai][bj][m][n] = __builtin_amdgcn_mfma_f32_16x16x32_bf16(Bt[n][k], At[m][k], acc[ai][bj][m][n], 0, 0, 0); __builtin_amdgcn_s_setprio(0); } while (0)
; #define PG8_WAIT_V(n) asm volatile("s_waitcnt vmcnt(" #n ")" ::: "memory")
; #define PG8_WAIT_L(n) asm volatile("s_waitcnt lgkmcnt(" #n ")" ::: "memory")
; #define PG8_BAR __builtin_amdgcn_s_barrier()
; #define PG8_SCHED __builtin_amdgcn_sched_barrier(0)
; template <class Epi, class Sched, bool ALIGN_EPI = false, bool SP2 = false>
; __device__ __forceinline__ void gemm_phase(PG8_LAS unsigned char* lds, const Gemm g, const Sched S, const Epi E) {
;     ...
;             PG8_WAIT_V(8); PG8_WAIT_L(0); PG8_BAR; PG8_MMA(1, 0, At, B0); PG8_MMA(1, 1, At, B1); PG8_BAR; PG8_SCHED;
;             PG8_LDB(B0, 1, 0); PG8_LDB(B1, 1, 1); PG8_SCHED; PG8_LDA(At, 1, 0); PG8_STAGE(PG8_SA(0, 1), a2 + hstep, voffA);
;             PG8_WAIT_V(8); PG8_WAIT_L(0); PG8_BAR; PG8_MMA(0, 0, At, B0); PG8_MMA(0, 1, At, B1); PG8_BAR; PG8_SCHED;
	s_setprio 1
	v_mfma_f32_16x16x32_bf16 v[62:65], v[136:139], v[180:183], v[62:65]
	v_mfma_f32_16x16x32_bf16 v[62:65], v[146:149], v[184:187], v[62:65]
	v_mfma_f32_16x16x32_bf16 v[58:61], v[150:153], v[180:183], v[58:61]
	v_mfma_f32_16x16x32_bf16 v[58:61], v[154:157], v[184:187], v[58:61]
	v_mfma_f32_16x16x32_bf16 v[46:49], v[136:139], v[188:191], v[46:49]
	v_mfma_f32_16x16x32_bf16 v[46:49], v[146:149], v[192:195], v[46:49]
	v_mfma_f32_16x16x32_bf16 v[42:45], v[150:153], v[188:191], v[42:45]
	v_mfma_f32_16x16x32_bf16 v[42:45], v[154:157], v[192:195], v[42:45]
	v_mfma_f32_16x16x32_bf16 v[30:33], v[136:139], v[196:199], v[30:33]
	v_mfma_f32_16x16x32_bf16 v[30:33], v[146:149], v[200:203], v[30:33]
	v_mfma_f32_16x16x32_bf16 v[26:29], v[150:153], v[196:199], v[26:29]
	v_mfma_f32_16x16x32_bf16 v[26:29], v[154:157], v[200:203], v[26:29]
	v_mfma_f32_16x16x32_bf16 v[14:17], v[136:139], v[224:227], v[14:17]
	v_mfma_f32_16x16x32_bf16 v[14:17], v[146:149], v[228:231], v[14:17]
	v_mfma_f32_16x16x32_bf16 v[10:13], v[150:153], v[224:227], v[10:13]
	v_mfma_f32_16x16x32_bf16 v[10:13], v[154:157], v[228:231], v[10:13]
	v_mfma_f32_16x16x32_bf16 v[54:57], v[158:161], v[180:183], v[54:57]
	v_mfma_f32_16x16x32_bf16 v[54:57], v[168:171], v[184:187], v[54:57]
	v_mfma_f32_16x16x32_bf16 v[50:53], v[172:175], v[180:183], v[50:53]
	v_mfma_f32_16x16x32_bf16 v[50:53], v[176:179], v[184:187], v[50:53]
	v_mfma_f32_16x16x32_bf16 v[38:41], v[158:161], v[188:191], v[38:41]
	v_mfma_f32_16x16x32_bf16 v[38:41], v[168:171], v[192:195], v[38:41]
	v_mfma_f32_16x16x32_bf16 v[34:37], v[172:175], v[188:191], v[34:37]
	v_mfma_f32_16x16x32_bf16 v[34:37], v[176:179], v[192:195], v[34:37]
	v_mfma_f32_16x16x32_bf16 v[22:25], v[158:161], v[196:199], v[22:25]
	v_mfma_f32_16x16x32_bf16 v[22:25], v[168:171], v[200:203], v[22:25]
	v_mfma_f32_16x16x32_bf16 v[18:21], v[172:175], v[196:199], v[18:21]
	v_mfma_f32_16x16x32_bf16 v[18:21], v[176:179], v[200:203], v[18:21]
	v_mfma_f32_16x16x32_bf16 v[6:9], v[158:161], v[224:227], v[6:9]
	v_mfma_f32_16x16x32_bf16 v[6:9], v[168:171], v[228:231], v[6:9]
	v_mfma_f32_16x16x32_bf16 v[2:5], v[172:175], v[224:227], v[2:5]
	v_mfma_f32_16x16x32_bf16 v[2:5], v[176:179], v[228:231], v[2:5]
	s_setprio 0
	s_barrier
	ds_read_b128 v[180:183], v145 offset:32768
	ds_read_b128 v[184:187], v145 offset:33792
	ds_read_b128 v[188:191], v145 offset:34816
	ds_read_b128 v[192:195], v145 offset:35840
	ds_read_b128 v[196:199], v145 offset:36864
	ds_read_b128 v[200:203], v145 offset:37888
	ds_read_b128 v[224:227], v145 offset:38912
	ds_read_b128 v[228:231], v145 offset:39936
	s_add_i32 s25, 0, 0x18000
	s_add_i32 s30, 0, 0x1c000
	v_add_u32_e32 v154, s25, v143
	v_add_u32_e32 v167, s30, v143
	ds_read_b128 v[136:139], v154
	ds_read_b128 v[146:149], v154 offset:1024
	ds_read_b128 v[150:153], v154 offset:2048
	ds_read_b128 v[154:157], v154 offset:3072
	ds_read_b128 v[158:161], v167
	ds_read_b128 v[168:171], v167 offset:1024
	ds_read_b128 v[172:175], v167 offset:2048
	ds_read_b128 v[176:179], v167 offset:3072
	s_add_u32 s26, vcc_lo, 0x40000
	s_addc_u32 s27, vcc_hi, 0
	s_mov_b32 m0, s47
	v_lshl_add_u64 v[236:237], s[26:27], 0, v[0:1]
	global_load_lds_dwordx4 v[236:237], off
	v_lshl_add_u64 v[236:237], s[26:27], 0, v[130:131]
	s_mov_b32 m0, s62
	s_nop 0
	global_load_lds_dwordx4 v[236:237], off
	s_waitcnt vmcnt(8) lgkmcnt(0)
	s_barrier
	s_setprio 1
	v_mfma_f32_16x16x32_bf16 v[126:129], v[136:139], v[180:183], v[126:129]
	v_mfma_f32_16x16x32_bf16 v[126:129], v[146:149], v[184:187], v[126:129]
	v_mfma_f32_16x16x32_bf16 v[122:125], v[150:153], v[180:183], v[122:125]
	v_mfma_f32_16x16x32_bf16 v[122:125], v[154:157], v[184:187], v[122:125]
	v_mfma_f32_16x16x32_bf16 v[110:113], v[136:139], v[188:191], v[110:113]
	v_mfma_f32_16x16x32_bf16 v[110:113], v[146:149], v[192:195], v[110:113]
	v_mfma_f32_16x16x32_bf16 v[106:109], v[150:153], v[188:191], v[106:109]
	v_mfma_f32_16x16x32_bf16 v[106:109], v[154:157], v[192:195], v[106:109]
	v_mfma_f32_16x16x32_bf16 v[94:97], v[136:139], v[196:199], v[94:97]
	v_mfma_f32_16x16x32_bf16 v[94:97], v[146:149], v[200:203], v[94:97]
	v_mfma_f32_16x16x32_bf16 v[90:93], v[150:153], v[196:199], v[90:93]
	v_mfma_f32_16x16x32_bf16 v[90:93], v[154:157], v[200:203], v[90:93]
	v_mfma_f32_16x16x32_bf16 v[78:81], v[136:139], v[224:227], v[78:81]
	v_mfma_f32_16x16x32_bf16 v[78:81], v[146:149], v[228:231], v[78:81]
	v_mfma_f32_16x16x32_bf16 v[74:77], v[150:153], v[224:227], v[74:77]
	v_mfma_f32_16x16x32_bf16 v[74:77], v[154:157], v[228:231], v[74:77]
	v_mfma_f32_16x16x32_bf16 v[118:121], v[158:161], v[180:183], v[118:121]
	v_mfma_f32_16x16x32_bf16 v[118:121], v[168:171], v[184:187], v[118:121]
	v_mfma_f32_16x16x32_bf16 v[114:117], v[172:175], v[180:183], v[114:117]
	v_mfma_f32_16x16x32_bf16 v[114:117], v[176:179], v[184:187], v[114:117]
	v_mfma_f32_16x16x32_bf16 v[102:105], v[158:161], v[188:191], v[102:105]
	v_mfma_f32_16x16x32_bf16 v[102:105], v[168:171], v[192:195], v[102:105]
	v_mfma_f32_16x16x32_bf16 v[98:101], v[172:175], v[188:191], v[98:101]
	v_mfma_f32_16x16x32_bf16 v[98:101], v[176:179], v[192:195], v[98:101]
	v_mfma_f32_16x16x32_bf16 v[86:89], v[158:161], v[196:199], v[86:89]
	v_mfma_f32_16x16x32_bf16 v[86:89], v[168:171], v[200:203], v[86:89]
	v_mfma_f32_16x16x32_bf16 v[82:85], v[172:175], v[196:199], v[82:85]
	v_mfma_f32_16x16x32_bf16 v[82:85], v[176:179], v[200:203], v[82:85]
	v_mfma_f32_16x16x32_bf16 v[70:73], v[158:161], v[224:227], v[70:73]
	v_mfma_f32_16x16x32_bf16 v[70:73], v[168:171], v[228:231], v[70:73]
	v_mfma_f32_16x16x32_bf16 v[66:69], v[172:175], v[224:227], v[66:69]
	v_mfma_f32_16x16x32_bf16 v[66:69], v[176:179], v[228:231], v[66:69]
	s_setprio 0
	s_barrier
; #define PG8_STAGE(bufoff, gbase, voff) do { _Pragma("unroll") for (int _i = 0; _i < 2; ++_i) \
;         __builtin_amdgcn_global_load_lds((const unsigned*)((const char*)(gbase) + (voff)[_i]), (PG8_LAS unsigned*)(lds + (bufoff) + ldsw + _i * 8192), 16, 0, 0); } while (0)
; #define PG8_LDA(dst, b, h) do { _Pragma("unroll") for (int m = 0; m < 4; ++m) _Pragma("unroll") for (int k = 0; k < 2; ++k) dst[m][k] = *(const PG8_LAS bf16x8*)(lds + PG8_SA(b, h) + aoff + m * 2048 + k * 1024); } while (0)
; #define PG8_MMA(ai, bj, At, Bt) do { __builtin_amdgcn_s_setprio(1); _Pragma("unroll") for (int m = 0; m < 4; ++m) _Pragma("unroll") for (int n = 0; n < 2; ++n) _Pragma("unroll") for (int k = 0; k < 2; ++k) \
;         acc[ai][bj][m][n] = __builtin_amdgcn_mfma_f32_16x16x32_bf16(Bt[n][k], At[m][k], acc[ai][bj][m][n], 0, 0, 0); __builtin_amdgcn_s_setprio(0); } while (0)
; #define PG8_WAIT_V(n) asm volatile("s_waitcnt vmcnt(" #n ")" ::: "memory")
; #define PG8_WAIT_L(n) asm volatile("s_waitcnt lgkmcnt(" #n ")" ::: "memory")
; #define PG8_BAR __builtin_amdgcn_s_barrier()
; #define PG8_SCHED __builtin_amdgcn_sched_barrier(0)
; template <class Epi, class Sched, bool ALIGN_EPI = false, bool SP2 = false>
; __device__ __forceinline__ void gemm_phase(PG8_LAS unsigned char* lds, const Gemm g, const Sched S, const Epi E) {
;     ...
;             PG8_LDA(At, 1, 1); PG8_STAGE(PG8_SB(1, 0), b3, voffB); PG8_STAGE(PG8_SB(1, 1), b3 + hstep, voffB); PG8_STAGE(PG8_SA(1, 0), a3, voffA);
;             PG8_WAIT_V(8); PG8_WAIT_L(0); PG8_BAR; PG8_MMA(1, 0, At, B0); PG8_MMA(1, 1, At, B1); PG8_BAR; PG8_SCHED;
;     ...
;         if constexpr (ALIGN_EPI) { if (wr == 0) PG8_BAR; }
	ds_read_b128 v[180:183], v145 offset:49152
	ds_read_b128 v[184:187], v145 offset:50176
	ds_read_b128 v[188:191], v145 offset:51200
	ds_read_b128 v[192:195], v145 offset:52224
	ds_read_b128 v[196:199], v145 offset:53248
	ds_read_b128 v[200:203], v145 offset:54272
	ds_read_b128 v[224:227], v145 offset:55296
	ds_read_b128 v[228:231], v145 offset:56320
	s_add_i32 s25, s25, s16
	v_lshl_add_u64 v[140:141], v[140:141], 0, s[28:29]
	s_mov_b32 m0, s25
	s_nop 0
	global_load_lds_dwordx4 v[140:141], off
	s_add_i32 m0, s25, 0x2000
	s_add_u32 s26, s66, 0x40080
	v_lshl_add_u64 v[140:141], v[214:215], 0, s[28:29]
	s_addc_u32 s27, s67, 0
	s_add_i32 s25, s30, s16
	global_load_lds_dwordx4 v[140:141], off
	v_lshl_add_u64 v[140:141], s[26:27], 0, v[0:1]
	s_mov_b32 m0, s25
	s_nop 0
	global_load_lds_dwordx4 v[140:141], off
	v_lshl_add_u64 v[140:141], s[26:27], 0, v[130:131]
	s_add_i32 m0, s25, 0x2000
	s_nop 0
	global_load_lds_dwordx4 v[140:141], off
	v_lshl_add_u64 v[140:141], v[232:233], 0, s[28:29]
	s_mov_b32 m0, s63
	s_nop 0
	global_load_lds_dwordx4 v[140:141], off
	v_lshl_add_u64 v[140:141], v[234:235], 0, s[28:29]
	s_mov_b32 m0, s74
	s_nop 0
	global_load_lds_dwordx4 v[140:141], off
	s_waitcnt vmcnt(8) lgkmcnt(0)
	s_barrier
	s_setprio 1
	v_mfma_f32_16x16x32_bf16 v[62:65], v[136:139], v[180:183], v[62:65]
	v_mfma_f32_16x16x32_bf16 v[62:65], v[146:149], v[184:187], v[62:65]
	v_mfma_f32_16x16x32_bf16 v[58:61], v[150:153], v[180:183], v[58:61]
	v_mfma_f32_16x16x32_bf16 v[58:61], v[154:157], v[184:187], v[58:61]
	v_mfma_f32_16x16x32_bf16 v[46:49], v[136:139], v[188:191], v[46:49]
	v_mfma_f32_16x16x32_bf16 v[46:49], v[146:149], v[192:195], v[46:49]
	v_mfma_f32_16x16x32_bf16 v[42:45], v[150:153], v[188:191], v[42:45]
	v_mfma_f32_16x16x32_bf16 v[42:45], v[154:157], v[192:195], v[42:45]
	v_mfma_f32_16x16x32_bf16 v[30:33], v[136:139], v[196:199], v[30:33]
	v_mfma_f32_16x16x32_bf16 v[30:33], v[146:149], v[200:203], v[30:33]
	v_mfma_f32_16x16x32_bf16 v[26:29], v[150:153], v[196:199], v[26:29]
	v_mfma_f32_16x16x32_bf16 v[26:29], v[154:157], v[200:203], v[26:29]
	v_mfma_f32_16x16x32_bf16 v[14:17], v[136:139], v[224:227], v[14:17]
	v_mfma_f32_16x16x32_bf16 v[14:17], v[146:149], v[228:231], v[14:17]
	v_mfma_f32_16x16x32_bf16 v[10:13], v[150:153], v[224:227], v[10:13]
	v_mfma_f32_16x16x32_bf16 v[10:13], v[154:157], v[228:231], v[10:13]
	v_mfma_f32_16x16x32_bf16 v[54:57], v[158:161], v[180:183], v[54:57]
	v_mfma_f32_16x16x32_bf16 v[54:57], v[168:171], v[184:187], v[54:57]
	v_mfma_f32_16x16x32_bf16 v[50:53], v[172:175], v[180:183], v[50:53]
	v_mfma_f32_16x16x32_bf16 v[50:53], v[176:179], v[184:187], v[50:53]
	v_mfma_f32_16x16x32_bf16 v[38:41], v[158:161], v[188:191], v[38:41]
	v_mfma_f32_16x16x32_bf16 v[38:41], v[168:171], v[192:195], v[38:41]
	v_mfma_f32_16x16x32_bf16 v[34:37], v[172:175], v[188:191], v[34:37]
	v_mfma_f32_16x16x32_bf16 v[34:37], v[176:179], v[192:195], v[34:37]
	v_mfma_f32_16x16x32_bf16 v[22:25], v[158:161], v[196:199], v[22:25]
	v_mfma_f32_16x16x32_bf16 v[22:25], v[168:171], v[200:203], v[22:25]
	v_mfma_f32_16x16x32_bf16 v[18:21], v[172:175], v[196:199], v[18:21]
	v_mfma_f32_16x16x32_bf16 v[18:21], v[176:179], v[200:203], v[18:21]
	v_mfma_f32_16x16x32_bf16 v[6:9], v[158:161], v[224:227], v[6:9]
	v_mfma_f32_16x16x32_bf16 v[6:9], v[168:171], v[228:231], v[6:9]
	v_mfma_f32_16x16x32_bf16 v[2:5], v[172:175], v[224:227], v[2:5]
	v_mfma_f32_16x16x32_bf16 v[2:5], v[176:179], v[228:231], v[2:5]
	s_setprio 0
	s_barrier
	s_add_i32 s24, s24, 2
	s_add_u32 s14, s14, 0x100
	s_addc_u32 s15, s15, 0
	s_cmp_gt_u32 s24, 13
	s_mov_b64 s[58:59], s[64:65]
	s_cbranch_scc0 .LBB0_654
	s_and_b64 vcc, exec, s[8:9]
	s_cbranch_vccz .LBB0_657
	s_barrier

; #define PG8_STAGE(bufoff, gbase, voff) do { _Pragma("unroll") for (int _i = 0; _i < 2; ++_i) \
;         __builtin_amdgcn_global_load_lds((const unsigned*)((const char*)(gbase) + (voff)[_i]), (PG8_LAS unsigned*)(lds + (bufoff) + ldsw + _i * 8192), 16, 0, 0); } while (0)
; #define PG8_LDA(dst, b, h) do { _Pragma("unroll") for (int m = 0; m < 4; ++m) _Pragma("unroll") for (int k = 0; k < 2; ++k) dst[m][k] = *(const PG8_LAS bf16x8*)(lds + PG8_SA(b, h) + aoff + m * 2048 + k * 1024); } while (0)
; #define PG8_LDB(dst, b, h) do { _Pragma("unroll") for (int n = 0; n < 2; ++n) _Pragma("unroll") for (int k = 0; k < 2; ++k) dst[n][k] = *(const PG8_LAS bf16x8*)(lds + PG8_SB(b, h) + boff + n * 2048 + k * 1024); } while (0)
; #define PG8_MMA(ai, bj, At, Bt) do { __builtin_amdgcn_s_setprio(1); _Pragma("unroll") for (int m = 0; m < 4; ++m) _Pragma("unroll") for (int n = 0; n < 2; ++n) _Pragma("unroll") for (int k = 0; k < 2; ++k) \
;         acc[ai][bj][m][n] = __builtin_amdgcn_mfma_f32_16x16x32_bf16(Bt[n][k], At[m][k], acc[ai][bj][m][n], 0, 0, 0); __builtin_amdgcn_s_setprio(0); } while (0)
; #define PG8_WAIT_V(n) asm volatile("s_waitcnt vmcnt(" #n ")" ::: "memory")
; #define PG8_WAIT_L(n) asm volatile("s_waitcnt lgkmcnt(" #n ")" ::: "memory")
; template <class Epi, class Sched, bool ALIGN_EPI = false, bool SP2 = false>
; __device__ __forceinline__ void gemm_phase(PG8_LAS unsigned char* lds, const Gemm g, const Sched S, const Epi E) {
;     ...
;             const bool last = (t == nt - 2);
;             const char* a1 = cA + (size_t)(t + 1) * kstep;
;             const char* a2 = last ? nA : cA + (size_t)(t + 2) * kstep; const char* b2 = last ? nB : cB + (size_t)(t + 2) * kstep;
;             const char* a3 = a2 + kstep; const char* b3 = b2 + kstep;
;             if (last && has_next) S.a_ready(nxt);
;             if constexpr (SP2) {
;             PG8_LDB(B0, 0, 0); PG8_LDB(B1, 0, 1); PG8_SCHED; PG8_LDA(At, 0, 0); PG8_STAGE(PG8_SA(1, 1), a1 + hstep, voffA);
;             PG8_WAIT_V(8); PG8_WAIT_L(0); PG8_BAR; PG8_MMA(0, 0, At, B0); PG8_MMA(0, 1, At, B1); PG8_BAR; PG8_SCHED;
;             PG8_LDA(At, 0, 1); PG8_STAGE(PG8_SB(0, 0), b2, voffB); PG8_STAGE(PG8_SB(0, 1), b2 + hstep, voffB); PG8_STAGE(PG8_SA(0, 0), a2, voffA);
;             PG8_WAIT_V(8); PG8_WAIT_L(0); PG8_BAR; PG8_MMA(1, 0, At, B0); PG8_MMA(1, 1, At, B1); PG8_BAR; PG8_SCHED;
.LBB0_726:
	ds_read_b128 v[180:183], v143
	ds_read_b128 v[184:187], v143 offset:1024
	ds_read_b128 v[188:191], v143 offset:2048
	ds_read_b128 v[192:195], v143 offset:3072
	ds_read_b128 v[196:199], v143 offset:4096
	ds_read_b128 v[200:203], v143 offset:5120
	ds_read_b128 v[224:227], v143 offset:6144
	ds_read_b128 v[228:231], v143 offset:7168
	s_add_u32 s25, s40, 0xfff80080
	s_addc_u32 s26, s41, -1
	s_add_i32 s27, 0, 0x10000
	s_cmp_eq_u32 s24, 28
	s_cselect_b32 s45, s57, s26
	s_cselect_b32 s44, s66, s25
	s_cselect_b32 s43, s53, s15
	s_cselect_b32 s42, s67, s14
	s_add_i32 s25, 0, 0x14000
	v_add_u32_e32 v152, s27, v141
	v_add_u32_e32 v160, s25, v141
	ds_read_b128 v[136:139], v152
	ds_read_b128 v[144:147], v152 offset:1024
	ds_read_b128 v[148:151], v152 offset:2048
	ds_read_b128 v[152:155], v152 offset:3072
	ds_read_b128 v[156:159], v160
	ds_read_b128 v[168:171], v160 offset:1024
	ds_read_b128 v[172:175], v160 offset:2048
	ds_read_b128 v[176:179], v160 offset:3072
	v_lshl_add_u64 v[160:161], s[40:41], 0, v[132:133]
	s_add_i32 m0, s21, 0xc000
	s_nop 0
	global_load_lds_dwordx4 v[160:161], off
	v_lshl_add_u64 v[160:161], s[40:41], 0, v[134:135]
	s_add_i32 m0, s21, 0xe000
	s_nop 0
	global_load_lds_dwordx4 v[160:161], off
	s_waitcnt vmcnt(8) lgkmcnt(0)
	s_barrier
	s_setprio 1
	v_mfma_f32_16x16x32_bf16 v[126:129], v[136:139], v[180:183], v[126:129]
	v_mfma_f32_16x16x32_bf16 v[126:129], v[144:147], v[184:187], v[126:129]
	v_mfma_f32_16x16x32_bf16 v[122:125], v[148:151], v[180:183], v[122:125]
	v_mfma_f32_16x16x32_bf16 v[122:125], v[152:155], v[184:187], v[122:125]
	v_mfma_f32_16x16x32_bf16 v[114:117], v[136:139], v[188:191], v[114:117]
	v_mfma_f32_16x16x32_bf16 v[114:117], v[144:147], v[192:195], v[114:117]
	v_mfma_f32_16x16x32_bf16 v[106:109], v[148:151], v[188:191], v[106:109]
	v_mfma_f32_16x16x32_bf16 v[106:109], v[152:155], v[192:195], v[106:109]
	v_mfma_f32_16x16x32_bf16 v[98:101], v[136:139], v[196:199], v[98:101]
	v_mfma_f32_16x16x32_bf16 v[98:101], v[144:147], v[200:203], v[98:101]
	v_mfma_f32_16x16x32_bf16 v[90:93], v[148:151], v[196:199], v[90:93]
	v_mfma_f32_16x16x32_bf16 v[90:93], v[152:155], v[200:203], v[90:93]
	v_mfma_f32_16x16x32_bf16 v[82:85], v[136:139], v[224:227], v[82:85]
	v_mfma_f32_16x16x32_bf16 v[82:85], v[144:147], v[228:231], v[82:85]
	v_mfma_f32_16x16x32_bf16 v[74:77], v[148:151], v[224:227], v[74:77]
	v_mfma_f32_16x16x32_bf16 v[74:77], v[152:155], v[228:231], v[74:77]
	v_mfma_f32_16x16x32_bf16 v[118:121], v[156:159], v[180:183], v[118:121]
	v_mfma_f32_16x16x32_bf16 v[118:121], v[168:171], v[184:187], v[118:121]
	v_mfma_f32_16x16x32_bf16 v[110:113], v[172:175], v[180:183], v[110:113]
	v_mfma_f32_16x16x32_bf16 v[110:113], v[176:179], v[184:187], v[110:113]
	v_mfma_f32_16x16x32_bf16 v[102:105], v[156:159], v[188:191], v[102:105]
	v_mfma_f32_16x16x32_bf16 v[102:105], v[168:171], v[192:195], v[102:105]
	v_mfma_f32_16x16x32_bf16 v[94:97], v[172:175], v[188:191], v[94:97]
	v_mfma_f32_16x16x32_bf16 v[94:97], v[176:179], v[192:195], v[94:97]
	v_mfma_f32_16x16x32_bf16 v[86:89], v[156:159], v[196:199], v[86:89]
	v_mfma_f32_16x16x32_bf16 v[86:89], v[168:171], v[200:203], v[86:89]
	v_mfma_f32_16x16x32_bf16 v[78:81], v[172:175], v[196:199], v[78:81]
	v_mfma_f32_16x16x32_bf16 v[78:81], v[176:179], v[200:203], v[78:81]
	v_mfma_f32_16x16x32_bf16 v[70:73], v[156:159], v[224:227], v[70:73]
	v_mfma_f32_16x16x32_bf16 v[70:73], v[168:171], v[228:231], v[70:73]
	v_mfma_f32_16x16x32_bf16 v[66:69], v[172:175], v[224:227], v[66:69]
	v_mfma_f32_16x16x32_bf16 v[66:69], v[176:179], v[228:231], v[66:69]
	s_setprio 0
	s_barrier
	ds_read_b128 v[180:183], v143 offset:16384
	ds_read_b128 v[184:187], v143 offset:17408
	ds_read_b128 v[188:191], v143 offset:18432
	ds_read_b128 v[192:195], v143 offset:19456
	ds_read_b128 v[196:199], v143 offset:20480
	ds_read_b128 v[200:203], v143 offset:21504
	ds_read_b128 v[224:227], v143 offset:22528
	ds_read_b128 v[228:231], v143 offset:23552
	s_add_i32 s26, s27, s16
	v_lshl_add_u64 v[160:161], s[42:43], 0, v[0:1]
	s_mov_b32 m0, s26
	s_nop 0
	global_load_lds_dwordx4 v[160:161], off
	s_add_i32 m0, s26, 0x2000
	s_add_u32 s26, s42, 0x80000
	v_lshl_add_u64 v[232:233], s[42:43], 0, v[130:131]
	s_addc_u32 s27, s43, 0
	s_add_i32 s25, s25, s16
	global_load_lds_dwordx4 v[232:233], off
	v_lshl_add_u64 v[234:235], s[26:27], 0, v[0:1]
	s_mov_b32 m0, s25
	v_lshl_add_u64 v[236:237], s[44:45], 0, v[130:131]
	global_load_lds_dwordx4 v[234:235], off
	v_lshl_add_u64 v[234:235], s[26:27], 0, v[130:131]
	s_add_i32 m0, s25, 0x2000
	s_nop 0
	global_load_lds_dwordx4 v[234:235], off
	v_lshl_add_u64 v[234:235], s[44:45], 0, v[0:1]
	s_mov_b32 m0, s21
	s_nop 0
	global_load_lds_dwordx4 v[234:235], off
	s_mov_b32 m0, s22
	s_nop 0
	global_load_lds_dwordx4 v[236:237], off
	s_waitcnt vmcnt(8) lgkmcnt(0)
	s_barrier
; #define PG8_STAGE(bufoff, gbase, voff) do { _Pragma("unroll") for (int _i = 0; _i < 2; ++_i) \
;         __builtin_amdgcn_global_load_lds((const unsigned*)((const char*)(gbase) + (voff)[_i]), (PG8_LAS unsigned*)(lds + (bufoff) + ldsw + _i * 8192), 16, 0, 0); } while (0)
; #define PG8_LDA(dst, b, h) do { _Pragma("unroll") for (int m = 0; m < 4; ++m) _Pragma("unroll") for (int k = 0; k < 2; ++k) dst[m][k] = *(const PG8_LAS bf16x8*)(lds + PG8_SA(b, h) + aoff + m * 2048 + k * 1024); } while (0)
; #define PG8_LDB(dst, b, h) do { _Pragma("unroll") for (int n = 0; n < 2; ++n) _Pragma("unroll") for (int k = 0; k < 2; ++k) dst[n][k] = *(const PG8_LAS bf16x8*)(lds + PG8_SB(b, h) + boff + n * 2048 + k * 1024); } while (0)
; #define PG8_MMA(ai, bj, At, Bt) do { __builtin_amdgcn_s_setprio(1); _Pragma("unroll") for (int m = 0; m < 4; ++m) _Pragma("unroll") for (int n = 0; n < 2; ++n) _Pragma("unroll") for (int k = 0; k < 2; ++k) \
;         acc[ai][bj][m][n] = __builtin_amdgcn_mfma_f32_16x16x32_bf16(Bt[n][k], At[m][k], acc[ai][bj][m][n], 0, 0, 0); __builtin_amdgcn_s_setprio(0); } while (0)
; #define PG8_WAIT_V(n) asm volatile("s_waitcnt vmcnt(" #n ")" ::: "memory")
; #define PG8_WAIT_L(n) asm volatile("s_waitcnt lgkmcnt(" #n ")" ::: "memory")
; #define PG8_BAR __builtin_amdgcn_s_barrier()
; #define PG8_SCHED __builtin_amdgcn_sched_barrier(0)
; template <class Epi, class Sched, bool ALIGN_EPI = false, bool SP2 = false>
; __device__ __forceinline__ void gemm_phase(PG8_LAS unsigned char* lds, const Gemm g, const Sched S, const Epi E) {
;     ...
;             PG8_WAIT_V(8); PG8_WAIT_L(0); PG8_BAR; PG8_MMA(1, 0, At, B0); PG8_MMA(1, 1, At, B1); PG8_BAR; PG8_SCHED;
;             PG8_LDB(B0, 1, 0); PG8_LDB(B1, 1, 1); PG8_SCHED; PG8_LDA(At, 1, 0); PG8_STAGE(PG8_SA(0, 1), a2 + hstep, voffA);
;             PG8_WAIT_V(8); PG8_WAIT_L(0); PG8_BAR; PG8_MMA(0, 0, At, B0); PG8_MMA(0, 1, At, B1); PG8_BAR; PG8_SCHED;
	s_setprio 1
	v_mfma_f32_16x16x32_bf16 v[62:65], v[136:139], v[180:183], v[62:65]
	v_mfma_f32_16x16x32_bf16 v[62:65], v[144:147], v[184:187], v[62:65]
	v_mfma_f32_16x16x32_bf16 v[58:61], v[148:151], v[180:183], v[58:61]
	v_mfma_f32_16x16x32_bf16 v[58:61], v[152:155], v[184:187], v[58:61]
	v_mfma_f32_16x16x32_bf16 v[50:53], v[136:139], v[188:191], v[50:53]
	v_mfma_f32_16x16x32_bf16 v[50:53], v[144:147], v[192:195], v[50:53]
	v_mfma_f32_16x16x32_bf16 v[42:45], v[148:151], v[188:191], v[42:45]
	v_mfma_f32_16x16x32_bf16 v[42:45], v[152:155], v[192:195], v[42:45]
	v_mfma_f32_16x16x32_bf16 v[34:37], v[136:139], v[196:199], v[34:37]
	v_mfma_f32_16x16x32_bf16 v[34:37], v[144:147], v[200:203], v[34:37]
	v_mfma_f32_16x16x32_bf16 v[26:29], v[148:151], v[196:199], v[26:29]
	v_mfma_f32_16x16x32_bf16 v[26:29], v[152:155], v[200:203], v[26:29]
	v_mfma_f32_16x16x32_bf16 v[18:21], v[136:139], v[224:227], v[18:21]
	v_mfma_f32_16x16x32_bf16 v[18:21], v[144:147], v[228:231], v[18:21]
	v_mfma_f32_16x16x32_bf16 v[10:13], v[148:151], v[224:227], v[10:13]
	v_mfma_f32_16x16x32_bf16 v[10:13], v[152:155], v[228:231], v[10:13]
	v_mfma_f32_16x16x32_bf16 v[54:57], v[156:159], v[180:183], v[54:57]
	v_mfma_f32_16x16x32_bf16 v[54:57], v[168:171], v[184:187], v[54:57]
	v_mfma_f32_16x16x32_bf16 v[46:49], v[172:175], v[180:183], v[46:49]
	v_mfma_f32_16x16x32_bf16 v[46:49], v[176:179], v[184:187], v[46:49]
	v_mfma_f32_16x16x32_bf16 v[38:41], v[156:159], v[188:191], v[38:41]
	v_mfma_f32_16x16x32_bf16 v[38:41], v[168:171], v[192:195], v[38:41]
	v_mfma_f32_16x16x32_bf16 v[30:33], v[172:175], v[188:191], v[30:33]
	v_mfma_f32_16x16x32_bf16 v[30:33], v[176:179], v[192:195], v[30:33]
	v_mfma_f32_16x16x32_bf16 v[22:25], v[156:159], v[196:199], v[22:25]
	v_mfma_f32_16x16x32_bf16 v[22:25], v[168:171], v[200:203], v[22:25]
	v_mfma_f32_16x16x32_bf16 v[14:17], v[172:175], v[196:199], v[14:17]
	v_mfma_f32_16x16x32_bf16 v[14:17], v[176:179], v[200:203], v[14:17]
	v_mfma_f32_16x16x32_bf16 v[6:9], v[156:159], v[224:227], v[6:9]
	v_mfma_f32_16x16x32_bf16 v[6:9], v[168:171], v[228:231], v[6:9]
	v_mfma_f32_16x16x32_bf16 v[2:5], v[172:175], v[224:227], v[2:5]
	v_mfma_f32_16x16x32_bf16 v[2:5], v[176:179], v[228:231], v[2:5]
	s_setprio 0
	s_barrier
	ds_read_b128 v[180:183], v143 offset:32768
	ds_read_b128 v[184:187], v143 offset:33792
	ds_read_b128 v[188:191], v143 offset:34816
	ds_read_b128 v[192:195], v143 offset:35840
	ds_read_b128 v[196:199], v143 offset:36864
	ds_read_b128 v[200:203], v143 offset:37888
	ds_read_b128 v[224:227], v143 offset:38912
	ds_read_b128 v[228:231], v143 offset:39936
	s_add_i32 s25, 0, 0x18000
	s_add_i32 s30, 0, 0x1c000
	v_add_u32_e32 v152, s25, v141
	v_add_u32_e32 v167, s30, v141
	ds_read_b128 v[136:139], v152
	ds_read_b128 v[144:147], v152 offset:1024
	ds_read_b128 v[148:151], v152 offset:2048
	ds_read_b128 v[152:155], v152 offset:3072
	ds_read_b128 v[156:159], v167
	ds_read_b128 v[168:171], v167 offset:1024
	ds_read_b128 v[172:175], v167 offset:2048
	ds_read_b128 v[176:179], v167 offset:3072
	s_add_u32 s26, s44, 0x80000
	s_addc_u32 s27, s45, 0
	s_mov_b32 m0, s47
	v_lshl_add_u64 v[238:239], s[26:27], 0, v[0:1]
	global_load_lds_dwordx4 v[238:239], off
	v_lshl_add_u64 v[238:239], s[26:27], 0, v[130:131]
	s_mov_b32 m0, s62
	s_nop 0
	global_load_lds_dwordx4 v[238:239], off
	s_waitcnt vmcnt(8) lgkmcnt(0)
	s_barrier
	s_setprio 1
	v_mfma_f32_16x16x32_bf16 v[126:129], v[136:139], v[180:183], v[126:129]
	v_mfma_f32_16x16x32_bf16 v[126:129], v[144:147], v[184:187], v[126:129]
	v_mfma_f32_16x16x32_bf16 v[122:125], v[148:151], v[180:183], v[122:125]
	v_mfma_f32_16x16x32_bf16 v[122:125], v[152:155], v[184:187], v[122:125]
	v_mfma_f32_16x16x32_bf16 v[114:117], v[136:139], v[188:191], v[114:117]
	v_mfma_f32_16x16x32_bf16 v[114:117], v[144:147], v[192:195], v[114:117]
	v_mfma_f32_16x16x32_bf16 v[106:109], v[148:151], v[188:191], v[106:109]
	v_mfma_f32_16x16x32_bf16 v[106:109], v[152:155], v[192:195], v[106:109]
	v_mfma_f32_16x16x32_bf16 v[98:101], v[136:139], v[196:199], v[98:101]
	v_mfma_f32_16x16x32_bf16 v[98:101], v[144:147], v[200:203], v[98:101]
	v_mfma_f32_16x16x32_bf16 v[90:93], v[148:151], v[196:199], v[90:93]
	v_mfma_f32_16x16x32_bf16 v[90:93], v[152:155], v[200:203], v[90:93]
	v_mfma_f32_16x16x32_bf16 v[82:85], v[136:139], v[224:227], v[82:85]
	v_mfma_f32_16x16x32_bf16 v[82:85], v[144:147], v[228:231], v[82:85]
	v_mfma_f32_16x16x32_bf16 v[74:77], v[148:151], v[224:227], v[74:77]
	v_mfma_f32_16x16x32_bf16 v[74:77], v[152:155], v[228:231], v[74:77]
	v_mfma_f32_16x16x32_bf16 v[118:121], v[156:159], v[180:183], v[118:121]
	v_mfma_f32_16x16x32_bf16 v[118:121], v[168:171], v[184:187], v[118:121]
	v_mfma_f32_16x16x32_bf16 v[110:113], v[172:175], v[180:183], v[110:113]
	v_mfma_f32_16x16x32_bf16 v[110:113], v[176:179], v[184:187], v[110:113]
	v_mfma_f32_16x16x32_bf16 v[102:105], v[156:159], v[188:191], v[102:105]
	v_mfma_f32_16x16x32_bf16 v[102:105], v[168:171], v[192:195], v[102:105]
	v_mfma_f32_16x16x32_bf16 v[94:97], v[172:175], v[188:191], v[94:97]
	v_mfma_f32_16x16x32_bf16 v[94:97], v[176:179], v[192:195], v[94:97]
	v_mfma_f32_16x16x32_bf16 v[86:89], v[156:159], v[196:199], v[86:89]
	v_mfma_f32_16x16x32_bf16 v[86:89], v[168:171], v[200:203], v[86:89]
	v_mfma_f32_16x16x32_bf16 v[78:81], v[172:175], v[196:199], v[78:81]
	v_mfma_f32_16x16x32_bf16 v[78:81], v[176:179], v[200:203], v[78:81]
	v_mfma_f32_16x16x32_bf16 v[70:73], v[156:159], v[224:227], v[70:73]
	v_mfma_f32_16x16x32_bf16 v[70:73], v[168:171], v[228:231], v[70:73]
	v_mfma_f32_16x16x32_bf16 v[66:69], v[172:175], v[224:227], v[66:69]
	v_mfma_f32_16x16x32_bf16 v[66:69], v[176:179], v[228:231], v[66:69]
	s_setprio 0
	s_barrier
; #define PG8_STAGE(bufoff, gbase, voff) do { _Pragma("unroll") for (int _i = 0; _i < 2; ++_i) \
;         __builtin_amdgcn_global_load_lds((const unsigned*)((const char*)(gbase) + (voff)[_i]), (PG8_LAS unsigned*)(lds + (bufoff) + ldsw + _i * 8192), 16, 0, 0); } while (0)
; #define PG8_LDA(dst, b, h) do { _Pragma("unroll") for (int m = 0; m < 4; ++m) _Pragma("unroll") for (int k = 0; k < 2; ++k) dst[m][k] = *(const PG8_LAS bf16x8*)(lds + PG8_SA(b, h) + aoff + m * 2048 + k * 1024); } while (0)
; #define PG8_MMA(ai, bj, At, Bt) do { __builtin_amdgcn_s_setprio(1); _Pragma("unroll") for (int m = 0; m < 4; ++m) _Pragma("unroll") for (int n = 0; n < 2; ++n) _Pragma("unroll") for (int k = 0; k < 2; ++k) \
;         acc[ai][bj][m][n] = __builtin_amdgcn_mfma_f32_16x16x32_bf16(Bt[n][k], At[m][k], acc[ai][bj][m][n], 0, 0, 0); __builtin_amdgcn_s_setprio(0); } while (0)
; #define PG8_WAIT_V(n) asm volatile("s_waitcnt vmcnt(" #n ")" ::: "memory")
; #define PG8_WAIT_L(n) asm volatile("s_waitcnt lgkmcnt(" #n ")" ::: "memory")
; #define PG8_BAR __builtin_amdgcn_s_barrier()
; #define PG8_SCHED __builtin_amdgcn_sched_barrier(0)
; template <class Epi, class Sched, bool ALIGN_EPI = false, bool SP2 = false>
; __device__ __forceinline__ void gemm_phase(PG8_LAS unsigned char* lds, const Gemm g, const Sched S, const Epi E) {
;     ...
;             PG8_LDA(At, 1, 1); PG8_STAGE(PG8_SB(1, 0), b3, voffB); PG8_STAGE(PG8_SB(1, 1), b3 + hstep, voffB); PG8_STAGE(PG8_SA(1, 0), a3, voffA);
;             PG8_WAIT_V(8); PG8_WAIT_L(0); PG8_BAR; PG8_MMA(1, 0, At, B0); PG8_MMA(1, 1, At, B1); PG8_BAR; PG8_SCHED;
;     ...
;         if constexpr (ALIGN_EPI) { if (wr == 0) PG8_BAR; }
	ds_read_b128 v[180:183], v143 offset:49152
	ds_read_b128 v[184:187], v143 offset:50176
	ds_read_b128 v[188:191], v143 offset:51200
	ds_read_b128 v[192:195], v143 offset:52224
	ds_read_b128 v[196:199], v143 offset:53248
	ds_read_b128 v[200:203], v143 offset:54272
	ds_read_b128 v[224:227], v143 offset:55296
	ds_read_b128 v[228:231], v143 offset:56320
	s_add_i32 s25, s25, s16
	v_lshl_add_u64 v[160:161], v[160:161], 0, s[28:29]
	s_mov_b32 m0, s25
	s_nop 0
	global_load_lds_dwordx4 v[160:161], off
	s_add_i32 m0, s25, 0x2000
	s_add_u32 s26, s42, 0x80080
	v_lshl_add_u64 v[160:161], v[232:233], 0, s[28:29]
	s_addc_u32 s27, s43, 0
	s_add_i32 s25, s30, s16
	global_load_lds_dwordx4 v[160:161], off
	v_lshl_add_u64 v[160:161], s[26:27], 0, v[0:1]
	s_mov_b32 m0, s25
	s_nop 0
	global_load_lds_dwordx4 v[160:161], off
	v_lshl_add_u64 v[160:161], s[26:27], 0, v[130:131]
	s_add_i32 m0, s25, 0x2000
	s_nop 0
	global_load_lds_dwordx4 v[160:161], off
	v_lshl_add_u64 v[160:161], v[234:235], 0, s[28:29]
	s_mov_b32 m0, s63
	s_nop 0
	global_load_lds_dwordx4 v[160:161], off
	v_lshl_add_u64 v[160:161], v[236:237], 0, s[28:29]
	s_mov_b32 m0, s74
	s_nop 0
	global_load_lds_dwordx4 v[160:161], off
	s_waitcnt vmcnt(8) lgkmcnt(0)
	s_barrier
	s_setprio 1
	v_mfma_f32_16x16x32_bf16 v[62:65], v[136:139], v[180:183], v[62:65]
	v_mfma_f32_16x16x32_bf16 v[62:65], v[144:147], v[184:187], v[62:65]
	v_mfma_f32_16x16x32_bf16 v[58:61], v[148:151], v[180:183], v[58:61]
	v_mfma_f32_16x16x32_bf16 v[58:61], v[152:155], v[184:187], v[58:61]
	v_mfma_f32_16x16x32_bf16 v[50:53], v[136:139], v[188:191], v[50:53]
	v_mfma_f32_16x16x32_bf16 v[50:53], v[144:147], v[192:195], v[50:53]
	v_mfma_f32_16x16x32_bf16 v[42:45], v[148:151], v[188:191], v[42:45]
	v_mfma_f32_16x16x32_bf16 v[42:45], v[152:155], v[192:195], v[42:45]
	v_mfma_f32_16x16x32_bf16 v[34:37], v[136:139], v[196:199], v[34:37]
	v_mfma_f32_16x16x32_bf16 v[34:37], v[144:147], v[200:203], v[34:37]
	v_mfma_f32_16x16x32_bf16 v[26:29], v[148:151], v[196:199], v[26:29]
	v_mfma_f32_16x16x32_bf16 v[26:29], v[152:155], v[200:203], v[26:29]
	v_mfma_f32_16x16x32_bf16 v[18:21], v[136:139], v[224:227], v[18:21]
	v_mfma_f32_16x16x32_bf16 v[18:21], v[144:147], v[228:231], v[18:21]
	v_mfma_f32_16x16x32_bf16 v[10:13], v[148:151], v[224:227], v[10:13]
	v_mfma_f32_16x16x32_bf16 v[10:13], v[152:155], v[228:231], v[10:13]
	v_mfma_f32_16x16x32_bf16 v[54:57], v[156:159], v[180:183], v[54:57]
	v_mfma_f32_16x16x32_bf16 v[54:57], v[168:171], v[184:187], v[54:57]
	v_mfma_f32_16x16x32_bf16 v[46:49], v[172:175], v[180:183], v[46:49]
	v_mfma_f32_16x16x32_bf16 v[46:49], v[176:179], v[184:187], v[46:49]
	v_mfma_f32_16x16x32_bf16 v[38:41], v[156:159], v[188:191], v[38:41]
	v_mfma_f32_16x16x32_bf16 v[38:41], v[168:171], v[192:195], v[38:41]
	v_mfma_f32_16x16x32_bf16 v[30:33], v[172:175], v[188:191], v[30:33]
	v_mfma_f32_16x16x32_bf16 v[30:33], v[176:179], v[192:195], v[30:33]
	v_mfma_f32_16x16x32_bf16 v[22:25], v[156:159], v[196:199], v[22:25]
	v_mfma_f32_16x16x32_bf16 v[22:25], v[168:171], v[200:203], v[22:25]
	v_mfma_f32_16x16x32_bf16 v[14:17], v[172:175], v[196:199], v[14:17]
	v_mfma_f32_16x16x32_bf16 v[14:17], v[176:179], v[200:203], v[14:17]
	v_mfma_f32_16x16x32_bf16 v[6:9], v[156:159], v[224:227], v[6:9]
	v_mfma_f32_16x16x32_bf16 v[6:9], v[168:171], v[228:231], v[6:9]
	v_mfma_f32_16x16x32_bf16 v[2:5], v[172:175], v[224:227], v[2:5]
	v_mfma_f32_16x16x32_bf16 v[2:5], v[176:179], v[228:231], v[2:5]
	s_setprio 0
	s_barrier
	s_add_i32 s24, s24, 2
	s_add_u32 s40, s40, 0x100
	s_addc_u32 s41, s41, 0
	s_add_u32 s14, s14, 0x100
	s_addc_u32 s15, s15, 0
	s_cmp_gt_u32 s24, 29
	s_cbranch_scc0 .LBB0_726
	s_and_b64 vcc, exec, s[8:9]
	s_cbranch_vccz .LBB0_729
	s_barrier

; #define PG8_STAGE(bufoff, gbase, voff) do { _Pragma("unroll") for (int _i = 0; _i < 2; ++_i) \
;         __builtin_amdgcn_global_load_lds((const unsigned*)((const char*)(gbase) + (voff)[_i]), (PG8_LAS unsigned*)(lds + (bufoff) + ldsw + _i * 8192), 16, 0, 0); } while (0)
; #define PG8_LDA(dst, b, h) do { _Pragma("unroll") for (int m = 0; m < 4; ++m) _Pragma("unroll") for (int k = 0; k < 2; ++k) dst[m][k] = *(const PG8_LAS bf16x8*)(lds + PG8_SA(b, h) + aoff + m * 2048 + k * 1024); } while (0)
; #define PG8_LDB(dst, b, h) do { _Pragma("unroll") for (int n = 0; n < 2; ++n) _Pragma("unroll") for (int k = 0; k < 2; ++k) dst[n][k] = *(const PG8_LAS bf16x8*)(lds + PG8_SB(b, h) + boff + n * 2048 + k * 1024); } while (0)
; #define PG8_MMA(ai, bj, At, Bt) do { __builtin_amdgcn_s_setprio(1); _Pragma("unroll") for (int m = 0; m < 4; ++m) _Pragma("unroll") for (int n = 0; n < 2; ++n) _Pragma("unroll") for (int k = 0; k < 2; ++k) \
;         acc[ai][bj][m][n] = __builtin_amdgcn_mfma_f32_16x16x32_bf16(Bt[n][k], At[m][k], acc[ai][bj][m][n], 0, 0, 0); __builtin_amdgcn_s_setprio(0); } while (0)
; #define PG8_WAIT_V(n) asm volatile("s_waitcnt vmcnt(" #n ")" ::: "memory")
; #define PG8_WAIT_L(n) asm volatile("s_waitcnt lgkmcnt(" #n ")" ::: "memory")
; template <class Epi, class Sched, bool ALIGN_EPI = false, bool SP2 = false>
; __device__ __forceinline__ void gemm_phase(PG8_LAS unsigned char* lds, const Gemm g, const Sched S, const Epi E) {
;     ...
;             const bool last = (t == nt - 2);
;             const char* a1 = cA + (size_t)(t + 1) * kstep;
;             const char* a2 = last ? nA : cA + (size_t)(t + 2) * kstep; const char* b2 = last ? nB : cB + (size_t)(t + 2) * kstep;
;             const char* a3 = a2 + kstep; const char* b3 = b2 + kstep;
;             if (last && has_next) S.a_ready(nxt);
;             if constexpr (SP2) {
;             PG8_LDB(B0, 0, 0); PG8_LDB(B1, 0, 1); PG8_SCHED; PG8_LDA(At, 0, 0); PG8_STAGE(PG8_SA(1, 1), a1 + hstep, voffA);
;             PG8_WAIT_V(8); PG8_WAIT_L(0); PG8_BAR; PG8_MMA(0, 0, At, B0); PG8_MMA(0, 1, At, B1); PG8_BAR; PG8_SCHED;
;             PG8_LDA(At, 0, 1); PG8_STAGE(PG8_SB(0, 0), b2, voffB); PG8_STAGE(PG8_SB(0, 1), b2 + hstep, voffB); PG8_STAGE(PG8_SA(0, 0), a2, voffA);
;             PG8_WAIT_V(8); PG8_WAIT_L(0); PG8_BAR; PG8_MMA(1, 0, At, B0); PG8_MMA(1, 1, At, B1); PG8_BAR; PG8_SCHED;
.LBB0_922:
	ds_read_b128 v[184:187], v145
	ds_read_b128 v[188:191], v145 offset:1024
	ds_read_b128 v[192:195], v145 offset:2048
	ds_read_b128 v[196:199], v145 offset:3072
	ds_read_b128 v[200:203], v145 offset:4096
	ds_read_b128 v[224:227], v145 offset:5120
	ds_read_b128 v[228:231], v145 offset:6144
	ds_read_b128 v[232:235], v145 offset:7168
	s_add_u32 s25, s56, 0xfffe0080
	s_addc_u32 s26, s57, -1
	s_add_i32 s27, 0, 0x10000
	s_cmp_eq_u32 s24, 4
	s_cselect_b32 s65, s5, s26
	s_cselect_b32 s64, s41, s25
	v_add_u32_e32 v140, s27, v143
	s_cselect_b32 s59, s43, s15
	s_cselect_b32 s58, s75, s14
	s_add_i32 s25, 0, 0x14000
	ds_read_b128 v[146:149], v140
	ds_read_b128 v[150:153], v140 offset:1024
	ds_read_b128 v[154:157], v140 offset:2048
	ds_read_b128 v[158:161], v140 offset:3072
	v_add_u32_e32 v140, s25, v143
	ds_read_b128 v[168:171], v140
	ds_read_b128 v[172:175], v140 offset:1024
	ds_read_b128 v[176:179], v140 offset:2048
	ds_read_b128 v[180:183], v140 offset:3072
	v_lshl_add_u64 v[140:141], s[56:57], 0, v[136:137]
	s_add_i32 m0, s21, 0xc000
	s_nop 0
	global_load_lds_dwordx4 v[140:141], off
	v_lshl_add_u64 v[140:141], s[56:57], 0, v[138:139]
	s_add_i32 m0, s21, 0xe000
	s_nop 0
	global_load_lds_dwordx4 v[140:141], off
	s_waitcnt vmcnt(8) lgkmcnt(0)
	s_barrier
	s_setprio 1
	v_mfma_f32_16x16x32_bf16 v[126:129], v[146:149], v[184:187], v[126:129]
	v_mfma_f32_16x16x32_bf16 v[126:129], v[150:153], v[188:191], v[126:129]
	v_mfma_f32_16x16x32_bf16 v[122:125], v[154:157], v[184:187], v[122:125]
	v_mfma_f32_16x16x32_bf16 v[122:125], v[158:161], v[188:191], v[122:125]
	v_mfma_f32_16x16x32_bf16 v[118:121], v[146:149], v[192:195], v[118:121]
	v_mfma_f32_16x16x32_bf16 v[118:121], v[150:153], v[196:199], v[118:121]
	v_mfma_f32_16x16x32_bf16 v[110:113], v[154:157], v[192:195], v[110:113]
	v_mfma_f32_16x16x32_bf16 v[110:113], v[158:161], v[196:199], v[110:113]
	v_mfma_f32_16x16x32_bf16 v[102:105], v[146:149], v[200:203], v[102:105]
	v_mfma_f32_16x16x32_bf16 v[102:105], v[150:153], v[224:227], v[102:105]
	v_mfma_f32_16x16x32_bf16 v[94:97], v[154:157], v[200:203], v[94:97]
	v_mfma_f32_16x16x32_bf16 v[94:97], v[158:161], v[224:227], v[94:97]
	v_mfma_f32_16x16x32_bf16 v[86:89], v[146:149], v[228:231], v[86:89]
	v_mfma_f32_16x16x32_bf16 v[86:89], v[150:153], v[232:235], v[86:89]
	v_mfma_f32_16x16x32_bf16 v[78:81], v[154:157], v[228:231], v[78:81]
	v_mfma_f32_16x16x32_bf16 v[78:81], v[158:161], v[232:235], v[78:81]
	v_mfma_f32_16x16x32_bf16 v[114:117], v[168:171], v[184:187], v[114:117]
	v_mfma_f32_16x16x32_bf16 v[114:117], v[172:175], v[188:191], v[114:117]
	v_mfma_f32_16x16x32_bf16 v[106:109], v[176:179], v[184:187], v[106:109]
	v_mfma_f32_16x16x32_bf16 v[106:109], v[180:183], v[188:191], v[106:109]
	v_mfma_f32_16x16x32_bf16 v[98:101], v[168:171], v[192:195], v[98:101]
	v_mfma_f32_16x16x32_bf16 v[98:101], v[172:175], v[196:199], v[98:101]
	v_mfma_f32_16x16x32_bf16 v[90:93], v[176:179], v[192:195], v[90:93]
	v_mfma_f32_16x16x32_bf16 v[90:93], v[180:183], v[196:199], v[90:93]
	v_mfma_f32_16x16x32_bf16 v[82:85], v[168:171], v[200:203], v[82:85]
	v_mfma_f32_16x16x32_bf16 v[82:85], v[172:175], v[224:227], v[82:85]
	v_mfma_f32_16x16x32_bf16 v[74:77], v[176:179], v[200:203], v[74:77]
	v_mfma_f32_16x16x32_bf16 v[74:77], v[180:183], v[224:227], v[74:77]
	v_mfma_f32_16x16x32_bf16 v[70:73], v[168:171], v[228:231], v[70:73]
	v_mfma_f32_16x16x32_bf16 v[70:73], v[172:175], v[232:235], v[70:73]
	v_mfma_f32_16x16x32_bf16 v[66:69], v[176:179], v[228:231], v[66:69]
	v_mfma_f32_16x16x32_bf16 v[66:69], v[180:183], v[232:235], v[66:69]
	s_setprio 0
	s_barrier
	ds_read_b128 v[184:187], v145 offset:16384
	ds_read_b128 v[188:191], v145 offset:17408
	ds_read_b128 v[192:195], v145 offset:18432
	ds_read_b128 v[196:199], v145 offset:19456
	ds_read_b128 v[200:203], v145 offset:20480
	ds_read_b128 v[224:227], v145 offset:21504
	ds_read_b128 v[228:231], v145 offset:22528
	ds_read_b128 v[232:235], v145 offset:23552
	s_add_i32 s26, s27, s16
	v_lshl_add_u64 v[140:141], s[58:59], 0, v[0:1]
	s_mov_b32 m0, s26
	s_nop 0
	global_load_lds_dwordx4 v[140:141], off
	s_add_i32 m0, s26, 0x2000
	s_add_u32 s26, s58, 0x20000
	v_lshl_add_u64 v[236:237], s[58:59], 0, v[130:131]
	s_addc_u32 s27, s59, 0
	s_add_i32 s25, s25, s16
	global_load_lds_dwordx4 v[236:237], off
	v_lshl_add_u64 v[238:239], s[26:27], 0, v[0:1]
	s_mov_b32 m0, s25
	v_lshl_add_u64 v[240:241], s[64:65], 0, v[132:133]
	global_load_lds_dwordx4 v[238:239], off
	v_lshl_add_u64 v[238:239], s[26:27], 0, v[130:131]
	s_add_i32 m0, s25, 0x2000
	s_nop 0
	global_load_lds_dwordx4 v[238:239], off
	v_lshl_add_u64 v[238:239], s[64:65], 0, v[134:135]
	s_mov_b32 m0, s21
	s_nop 0
	global_load_lds_dwordx4 v[238:239], off
	s_mov_b32 m0, s22
	s_nop 0
	global_load_lds_dwordx4 v[240:241], off
	s_waitcnt vmcnt(8) lgkmcnt(0)
	s_barrier
; #define PG8_STAGE(bufoff, gbase, voff) do { _Pragma("unroll") for (int _i = 0; _i < 2; ++_i) \
;         __builtin_amdgcn_global_load_lds((const unsigned*)((const char*)(gbase) + (voff)[_i]), (PG8_LAS unsigned*)(lds + (bufoff) + ldsw + _i * 8192), 16, 0, 0); } while (0)
; #define PG8_LDA(dst, b, h) do { _Pragma("unroll") for (int m = 0; m < 4; ++m) _Pragma("unroll") for (int k = 0; k < 2; ++k) dst[m][k] = *(const PG8_LAS bf16x8*)(lds + PG8_SA(b, h) + aoff + m * 2048 + k * 1024); } while (0)
; #define PG8_LDB(dst, b, h) do { _Pragma("unroll") for (int n = 0; n < 2; ++n) _Pragma("unroll") for (int k = 0; k < 2; ++k) dst[n][k] = *(const PG8_LAS bf16x8*)(lds + PG8_SB(b, h) + boff + n * 2048 + k * 1024); } while (0)
; #define PG8_MMA(ai, bj, At, Bt) do { __builtin_amdgcn_s_setprio(1); _Pragma("unroll") for (int m = 0; m < 4; ++m) _Pragma("unroll") for (int n = 0; n < 2; ++n) _Pragma("unroll") for (int k = 0; k < 2; ++k) \
;         acc[ai][bj][m][n] = __builtin_amdgcn_mfma_f32_16x16x32_bf16(Bt[n][k], At[m][k], acc[ai][bj][m][n], 0, 0, 0); __builtin_amdgcn_s_setprio(0); } while (0)
; #define PG8_WAIT_V(n) asm volatile("s_waitcnt vmcnt(" #n ")" ::: "memory")
; #define PG8_WAIT_L(n) asm volatile("s_waitcnt lgkmcnt(" #n ")" ::: "memory")
; #define PG8_BAR __builtin_amdgcn_s_barrier()
; #define PG8_SCHED __builtin_amdgcn_sched_barrier(0)
; template <class Epi, class Sched, bool ALIGN_EPI = false, bool SP2 = false>
; __device__ __forceinline__ void gemm_phase(PG8_LAS unsigned char* lds, const Gemm g, const Sched S, const Epi E) {
;     ...
;             PG8_WAIT_V(8); PG8_WAIT_L(0); PG8_BAR; PG8_MMA(1, 0, At, B0); PG8_MMA(1, 1, At, B1); PG8_BAR; PG8_SCHED;
;             PG8_LDB(B0, 1, 0); PG8_LDB(B1, 1, 1); PG8_SCHED; PG8_LDA(At, 1, 0); PG8_STAGE(PG8_SA(0, 1), a2 + hstep, voffA);
;             PG8_WAIT_V(8); PG8_WAIT_L(0); PG8_BAR; PG8_MMA(0, 0, At, B0); PG8_MMA(0, 1, At, B1); PG8_BAR; PG8_SCHED;
	s_setprio 1
	v_mfma_f32_16x16x32_bf16 v[62:65], v[146:149], v[184:187], v[62:65]
	v_mfma_f32_16x16x32_bf16 v[62:65], v[150:153], v[188:191], v[62:65]
	v_mfma_f32_16x16x32_bf16 v[58:61], v[154:157], v[184:187], v[58:61]
	v_mfma_f32_16x16x32_bf16 v[58:61], v[158:161], v[188:191], v[58:61]
	v_mfma_f32_16x16x32_bf16 v[54:57], v[146:149], v[192:195], v[54:57]
	v_mfma_f32_16x16x32_bf16 v[54:57], v[150:153], v[196:199], v[54:57]
	v_mfma_f32_16x16x32_bf16 v[46:49], v[154:157], v[192:195], v[46:49]
	v_mfma_f32_16x16x32_bf16 v[46:49], v[158:161], v[196:199], v[46:49]
	v_mfma_f32_16x16x32_bf16 v[38:41], v[146:149], v[200:203], v[38:41]
	v_mfma_f32_16x16x32_bf16 v[38:41], v[150:153], v[224:227], v[38:41]
	v_mfma_f32_16x16x32_bf16 v[30:33], v[154:157], v[200:203], v[30:33]
	v_mfma_f32_16x16x32_bf16 v[30:33], v[158:161], v[224:227], v[30:33]
	v_mfma_f32_16x16x32_bf16 v[22:25], v[146:149], v[228:231], v[22:25]
	v_mfma_f32_16x16x32_bf16 v[22:25], v[150:153], v[232:235], v[22:25]
	v_mfma_f32_16x16x32_bf16 v[14:17], v[154:157], v[228:231], v[14:17]
	v_mfma_f32_16x16x32_bf16 v[14:17], v[158:161], v[232:235], v[14:17]
	v_mfma_f32_16x16x32_bf16 v[50:53], v[168:171], v[184:187], v[50:53]
	v_mfma_f32_16x16x32_bf16 v[50:53], v[172:175], v[188:191], v[50:53]
	v_mfma_f32_16x16x32_bf16 v[42:45], v[176:179], v[184:187], v[42:45]
	v_mfma_f32_16x16x32_bf16 v[42:45], v[180:183], v[188:191], v[42:45]
	v_mfma_f32_16x16x32_bf16 v[34:37], v[168:171], v[192:195], v[34:37]
	v_mfma_f32_16x16x32_bf16 v[34:37], v[172:175], v[196:199], v[34:37]
	v_mfma_f32_16x16x32_bf16 v[26:29], v[176:179], v[192:195], v[26:29]
	v_mfma_f32_16x16x32_bf16 v[26:29], v[180:183], v[196:199], v[26:29]
	v_mfma_f32_16x16x32_bf16 v[18:21], v[168:171], v[200:203], v[18:21]
	v_mfma_f32_16x16x32_bf16 v[18:21], v[172:175], v[224:227], v[18:21]
	v_mfma_f32_16x16x32_bf16 v[10:13], v[176:179], v[200:203], v[10:13]
	v_mfma_f32_16x16x32_bf16 v[10:13], v[180:183], v[224:227], v[10:13]
	v_mfma_f32_16x16x32_bf16 v[6:9], v[168:171], v[228:231], v[6:9]
	v_mfma_f32_16x16x32_bf16 v[6:9], v[172:175], v[232:235], v[6:9]
	v_mfma_f32_16x16x32_bf16 v[2:5], v[176:179], v[228:231], v[2:5]
	v_mfma_f32_16x16x32_bf16 v[2:5], v[180:183], v[232:235], v[2:5]
	s_setprio 0
	s_barrier
	ds_read_b128 v[184:187], v145 offset:32768
	ds_read_b128 v[188:191], v145 offset:33792
	ds_read_b128 v[192:195], v145 offset:34816
	ds_read_b128 v[196:199], v145 offset:35840
	ds_read_b128 v[200:203], v145 offset:36864
	ds_read_b128 v[224:227], v145 offset:37888
	ds_read_b128 v[228:231], v145 offset:38912
	ds_read_b128 v[232:235], v145 offset:39936
	s_add_i32 s25, 0, 0x18000
	s_add_i32 s30, 0, 0x1c000
	v_add_u32_e32 v158, s25, v143
	v_add_u32_e32 v167, s30, v143
	ds_read_b128 v[146:149], v158
	ds_read_b128 v[150:153], v158 offset:1024
	ds_read_b128 v[154:157], v158 offset:2048
	ds_read_b128 v[158:161], v158 offset:3072
	ds_read_b128 v[168:171], v167
	ds_read_b128 v[172:175], v167 offset:1024
	ds_read_b128 v[176:179], v167 offset:2048
	ds_read_b128 v[180:183], v167 offset:3072
	s_add_u32 s26, s64, 0x20000
	s_addc_u32 s27, s65, 0
	s_mov_b32 m0, s47
	v_lshl_add_u64 v[242:243], s[26:27], 0, v[134:135]
	global_load_lds_dwordx4 v[242:243], off
	v_lshl_add_u64 v[242:243], s[26:27], 0, v[132:133]
	s_mov_b32 m0, s62
	s_nop 0
	global_load_lds_dwordx4 v[242:243], off
	s_waitcnt vmcnt(8) lgkmcnt(0)
	s_barrier
	s_setprio 1
	v_mfma_f32_16x16x32_bf16 v[126:129], v[146:149], v[184:187], v[126:129]
	v_mfma_f32_16x16x32_bf16 v[126:129], v[150:153], v[188:191], v[126:129]
	v_mfma_f32_16x16x32_bf16 v[122:125], v[154:157], v[184:187], v[122:125]
	v_mfma_f32_16x16x32_bf16 v[122:125], v[158:161], v[188:191], v[122:125]
	v_mfma_f32_16x16x32_bf16 v[118:121], v[146:149], v[192:195], v[118:121]
	v_mfma_f32_16x16x32_bf16 v[118:121], v[150:153], v[196:199], v[118:121]
	v_mfma_f32_16x16x32_bf16 v[110:113], v[154:157], v[192:195], v[110:113]
	v_mfma_f32_16x16x32_bf16 v[110:113], v[158:161], v[196:199], v[110:113]
	v_mfma_f32_16x16x32_bf16 v[102:105], v[146:149], v[200:203], v[102:105]
	v_mfma_f32_16x16x32_bf16 v[102:105], v[150:153], v[224:227], v[102:105]
	v_mfma_f32_16x16x32_bf16 v[94:97], v[154:157], v[200:203], v[94:97]
	v_mfma_f32_16x16x32_bf16 v[94:97], v[158:161], v[224:227], v[94:97]
	v_mfma_f32_16x16x32_bf16 v[86:89], v[146:149], v[228:231], v[86:89]
	v_mfma_f32_16x16x32_bf16 v[86:89], v[150:153], v[232:235], v[86:89]
	v_mfma_f32_16x16x32_bf16 v[78:81], v[154:157], v[228:231], v[78:81]
	v_mfma_f32_16x16x32_bf16 v[78:81], v[158:161], v[232:235], v[78:81]
	v_mfma_f32_16x16x32_bf16 v[114:117], v[168:171], v[184:187], v[114:117]
	v_mfma_f32_16x16x32_bf16 v[114:117], v[172:175], v[188:191], v[114:117]
	v_mfma_f32_16x16x32_bf16 v[106:109], v[176:179], v[184:187], v[106:109]
	v_mfma_f32_16x16x32_bf16 v[106:109], v[180:183], v[188:191], v[106:109]
	v_mfma_f32_16x16x32_bf16 v[98:101], v[168:171], v[192:195], v[98:101]
	v_mfma_f32_16x16x32_bf16 v[98:101], v[172:175], v[196:199], v[98:101]
	v_mfma_f32_16x16x32_bf16 v[90:93], v[176:179], v[192:195], v[90:93]
	v_mfma_f32_16x16x32_bf16 v[90:93], v[180:183], v[196:199], v[90:93]
	v_mfma_f32_16x16x32_bf16 v[82:85], v[168:171], v[200:203], v[82:85]
	v_mfma_f32_16x16x32_bf16 v[82:85], v[172:175], v[224:227], v[82:85]
	v_mfma_f32_16x16x32_bf16 v[74:77], v[176:179], v[200:203], v[74:77]
	v_mfma_f32_16x16x32_bf16 v[74:77], v[180:183], v[224:227], v[74:77]
	v_mfma_f32_16x16x32_bf16 v[70:73], v[168:171], v[228:231], v[70:73]
	v_mfma_f32_16x16x32_bf16 v[70:73], v[172:175], v[232:235], v[70:73]
	v_mfma_f32_16x16x32_bf16 v[66:69], v[176:179], v[228:231], v[66:69]
	v_mfma_f32_16x16x32_bf16 v[66:69], v[180:183], v[232:235], v[66:69]
	s_setprio 0
	s_barrier
; #define PG8_STAGE(bufoff, gbase, voff) do { _Pragma("unroll") for (int _i = 0; _i < 2; ++_i) \
;         __builtin_amdgcn_global_load_lds((const unsigned*)((const char*)(gbase) + (voff)[_i]), (PG8_LAS unsigned*)(lds + (bufoff) + ldsw + _i * 8192), 16, 0, 0); } while (0)
; #define PG8_LDA(dst, b, h) do { _Pragma("unroll") for (int m = 0; m < 4; ++m) _Pragma("unroll") for (int k = 0; k < 2; ++k) dst[m][k] = *(const PG8_LAS bf16x8*)(lds + PG8_SA(b, h) + aoff + m * 2048 + k * 1024); } while (0)
; #define PG8_MMA(ai, bj, At, Bt) do { __builtin_amdgcn_s_setprio(1); _Pragma("unroll") for (int m = 0; m < 4; ++m) _Pragma("unroll") for (int n = 0; n < 2; ++n) _Pragma("unroll") for (int k = 0; k < 2; ++k) \
;         acc[ai][bj][m][n] = __builtin_amdgcn_mfma_f32_16x16x32_bf16(Bt[n][k], At[m][k], acc[ai][bj][m][n], 0, 0, 0); __builtin_amdgcn_s_setprio(0); } while (0)
; #define PG8_WAIT_V(n) asm volatile("s_waitcnt vmcnt(" #n ")" ::: "memory")
; #define PG8_WAIT_L(n) asm volatile("s_waitcnt lgkmcnt(" #n ")" ::: "memory")
; #define PG8_BAR __builtin_amdgcn_s_barrier()
; #define PG8_SCHED __builtin_amdgcn_sched_barrier(0)
; template <class Epi, class Sched, bool ALIGN_EPI = false, bool SP2 = false>
; __device__ __forceinline__ void gemm_phase(PG8_LAS unsigned char* lds, const Gemm g, const Sched S, const Epi E) {
;     ...
;             PG8_LDA(At, 1, 1); PG8_STAGE(PG8_SB(1, 0), b3, voffB); PG8_STAGE(PG8_SB(1, 1), b3 + hstep, voffB); PG8_STAGE(PG8_SA(1, 0), a3, voffA);
;             PG8_WAIT_V(8); PG8_WAIT_L(0); PG8_BAR; PG8_MMA(1, 0, At, B0); PG8_MMA(1, 1, At, B1); PG8_BAR; PG8_SCHED;
;     ...
;         if constexpr (ALIGN_EPI) { if (wr == 0) PG8_BAR; }
	ds_read_b128 v[184:187], v145 offset:49152
	ds_read_b128 v[188:191], v145 offset:50176
	ds_read_b128 v[192:195], v145 offset:51200
	ds_read_b128 v[196:199], v145 offset:52224
	ds_read_b128 v[200:203], v145 offset:53248
	ds_read_b128 v[224:227], v145 offset:54272
	ds_read_b128 v[228:231], v145 offset:55296
	ds_read_b128 v[232:235], v145 offset:56320
	s_add_i32 s25, s25, s16
	v_lshl_add_u64 v[140:141], v[140:141], 0, s[28:29]
	s_mov_b32 m0, s25
	s_nop 0
	global_load_lds_dwordx4 v[140:141], off
	s_add_i32 m0, s25, 0x2000
	s_add_u32 s26, s58, 0x20080
	v_lshl_add_u64 v[140:141], v[236:237], 0, s[28:29]
	s_addc_u32 s27, s59, 0
	s_add_i32 s25, s30, s16
	global_load_lds_dwordx4 v[140:141], off
	v_lshl_add_u64 v[140:141], s[26:27], 0, v[0:1]
	s_mov_b32 m0, s25
	s_nop 0
	global_load_lds_dwordx4 v[140:141], off
	v_lshl_add_u64 v[140:141], s[26:27], 0, v[130:131]
	s_add_i32 m0, s25, 0x2000
	s_nop 0
	global_load_lds_dwordx4 v[140:141], off
	v_lshl_add_u64 v[140:141], v[238:239], 0, s[28:29]
	s_mov_b32 m0, s63
	s_nop 0
	global_load_lds_dwordx4 v[140:141], off
	v_lshl_add_u64 v[140:141], v[240:241], 0, s[28:29]
	s_mov_b32 m0, s66
	s_nop 0
	global_load_lds_dwordx4 v[140:141], off
	s_waitcnt vmcnt(8) lgkmcnt(0)
	s_barrier
	s_setprio 1
	v_mfma_f32_16x16x32_bf16 v[62:65], v[146:149], v[184:187], v[62:65]
	v_mfma_f32_16x16x32_bf16 v[62:65], v[150:153], v[188:191], v[62:65]
	v_mfma_f32_16x16x32_bf16 v[58:61], v[154:157], v[184:187], v[58:61]
	v_mfma_f32_16x16x32_bf16 v[58:61], v[158:161], v[188:191], v[58:61]
	v_mfma_f32_16x16x32_bf16 v[54:57], v[146:149], v[192:195], v[54:57]
	v_mfma_f32_16x16x32_bf16 v[54:57], v[150:153], v[196:199], v[54:57]
	v_mfma_f32_16x16x32_bf16 v[46:49], v[154:157], v[192:195], v[46:49]
	v_mfma_f32_16x16x32_bf16 v[46:49], v[158:161], v[196:199], v[46:49]
	v_mfma_f32_16x16x32_bf16 v[38:41], v[146:149], v[200:203], v[38:41]
	v_mfma_f32_16x16x32_bf16 v[38:41], v[150:153], v[224:227], v[38:41]
	v_mfma_f32_16x16x32_bf16 v[30:33], v[154:157], v[200:203], v[30:33]
	v_mfma_f32_16x16x32_bf16 v[30:33], v[158:161], v[224:227], v[30:33]
	v_mfma_f32_16x16x32_bf16 v[22:25], v[146:149], v[228:231], v[22:25]
	v_mfma_f32_16x16x32_bf16 v[22:25], v[150:153], v[232:235], v[22:25]
	v_mfma_f32_16x16x32_bf16 v[14:17], v[154:157], v[228:231], v[14:17]
	v_mfma_f32_16x16x32_bf16 v[14:17], v[158:161], v[232:235], v[14:17]
	v_mfma_f32_16x16x32_bf16 v[50:53], v[168:171], v[184:187], v[50:53]
	v_mfma_f32_16x16x32_bf16 v[50:53], v[172:175], v[188:191], v[50:53]
	v_mfma_f32_16x16x32_bf16 v[42:45], v[176:179], v[184:187], v[42:45]
	v_mfma_f32_16x16x32_bf16 v[42:45], v[180:183], v[188:191], v[42:45]
	v_mfma_f32_16x16x32_bf16 v[34:37], v[168:171], v[192:195], v[34:37]
	v_mfma_f32_16x16x32_bf16 v[34:37], v[172:175], v[196:199], v[34:37]
	v_mfma_f32_16x16x32_bf16 v[26:29], v[176:179], v[192:195], v[26:29]
	v_mfma_f32_16x16x32_bf16 v[26:29], v[180:183], v[196:199], v[26:29]
	v_mfma_f32_16x16x32_bf16 v[18:21], v[168:171], v[200:203], v[18:21]
	v_mfma_f32_16x16x32_bf16 v[18:21], v[172:175], v[224:227], v[18:21]
	v_mfma_f32_16x16x32_bf16 v[10:13], v[176:179], v[200:203], v[10:13]
	v_mfma_f32_16x16x32_bf16 v[10:13], v[180:183], v[224:227], v[10:13]
	v_mfma_f32_16x16x32_bf16 v[6:9], v[168:171], v[228:231], v[6:9]
	v_mfma_f32_16x16x32_bf16 v[6:9], v[172:175], v[232:235], v[6:9]
	v_mfma_f32_16x16x32_bf16 v[2:5], v[176:179], v[228:231], v[2:5]
	v_mfma_f32_16x16x32_bf16 v[2:5], v[180:183], v[232:235], v[2:5]
	s_setprio 0
	s_barrier
	s_add_i32 s24, s24, 2
	s_add_u32 s56, s56, 0x100
	s_addc_u32 s57, s57, 0
	s_add_u32 s14, s14, 0x100
	s_addc_u32 s15, s15, 0
	s_cmp_gt_u32 s24, 5
	s_cbranch_scc0 .LBB0_922
	s_and_b64 vcc, exec, s[38:39]
	s_cbranch_vccz .LBB0_925
	s_barrier

; #define PG8_STAGE(bufoff, gbase, voff) do { _Pragma("unroll") for (int _i = 0; _i < 2; ++_i) \
;         __builtin_amdgcn_global_load_lds((const unsigned*)((const char*)(gbase) + (voff)[_i]), (PG8_LAS unsigned*)(lds + (bufoff) + ldsw + _i * 8192), 16, 0, 0); } while (0)
; #define PG8_LDA(dst, b, h) do { _Pragma("unroll") for (int m = 0; m < 4; ++m) _Pragma("unroll") for (int k = 0; k < 2; ++k) dst[m][k] = *(const PG8_LAS bf16x8*)(lds + PG8_SA(b, h) + aoff + m * 2048 + k * 1024); } while (0)
; #define PG8_LDB(dst, b, h) do { _Pragma("unroll") for (int n = 0; n < 2; ++n) _Pragma("unroll") for (int k = 0; k < 2; ++k) dst[n][k] = *(const PG8_LAS bf16x8*)(lds + PG8_SB(b, h) + boff + n * 2048 + k * 1024); } while (0)
; #define PG8_MMA(ai, bj, At, Bt) do { __builtin_amdgcn_s_setprio(1); _Pragma("unroll") for (int m = 0; m < 4; ++m) _Pragma("unroll") for (int n = 0; n < 2; ++n) _Pragma("unroll") for (int k = 0; k < 2; ++k) \
;         acc[ai][bj][m][n] = __builtin_amdgcn_mfma_f32_16x16x32_bf16(Bt[n][k], At[m][k], acc[ai][bj][m][n], 0, 0, 0); __builtin_amdgcn_s_setprio(0); } while (0)
; #define PG8_WAIT_V(n) asm volatile("s_waitcnt vmcnt(" #n ")" ::: "memory")
; #define PG8_WAIT_L(n) asm volatile("s_waitcnt lgkmcnt(" #n ")" ::: "memory")
; template <class Epi, class Sched, bool ALIGN_EPI = false, bool SP2 = false>
; __device__ __forceinline__ void gemm_phase(PG8_LAS unsigned char* lds, const Gemm g, const Sched S, const Epi E) {
;     ...
;             const bool last = (t == nt - 2);
;             const char* a1 = cA + (size_t)(t + 1) * kstep;
;             const char* a2 = last ? nA : cA + (size_t)(t + 2) * kstep; const char* b2 = last ? nB : cB + (size_t)(t + 2) * kstep;
;             const char* a3 = a2 + kstep; const char* b3 = b2 + kstep;
;             if (last && has_next) S.a_ready(nxt);
;             if constexpr (SP2) {
;             PG8_LDB(B0, 0, 0); PG8_LDB(B1, 0, 1); PG8_SCHED; PG8_LDA(At, 0, 0); PG8_STAGE(PG8_SA(1, 1), a1 + hstep, voffA);
;             PG8_WAIT_V(8); PG8_WAIT_L(0); PG8_BAR; PG8_MMA(0, 0, At, B0); PG8_MMA(0, 1, At, B1); PG8_BAR; PG8_SCHED;
;             PG8_LDA(At, 0, 1); PG8_STAGE(PG8_SB(0, 0), b2, voffB); PG8_STAGE(PG8_SB(0, 1), b2 + hstep, voffB); PG8_STAGE(PG8_SA(0, 0), a2, voffA);
;             PG8_WAIT_V(8); PG8_WAIT_L(0); PG8_BAR; PG8_MMA(1, 0, At, B0); PG8_MMA(1, 1, At, B1); PG8_BAR; PG8_SCHED;
.LBB0_2074:
	ds_read_b128 v[180:183], v145
	ds_read_b128 v[184:187], v145 offset:1024
	ds_read_b128 v[188:191], v145 offset:2048
	ds_read_b128 v[192:195], v145 offset:3072
	ds_read_b128 v[196:199], v145 offset:4096
	ds_read_b128 v[200:203], v145 offset:5120
	ds_read_b128 v[224:227], v145 offset:6144
	ds_read_b128 v[228:231], v145 offset:7168
	s_add_u32 s56, s52, 0x100
	s_addc_u32 s57, s53, 0
	s_add_i32 s25, 0, 0x10000
	s_cmp_eq_u32 s24, 28
	s_cselect_b32 s65, s43, s57
	s_cselect_b32 s64, s74, s56
	v_add_u32_e32 v140, s25, v143
	s_cselect_b32 s59, s41, s15
	s_cselect_b32 s58, s75, s14
	s_add_i32 s30, 0, 0x14000
	ds_read_b128 v[136:139], v140
	ds_read_b128 v[146:149], v140 offset:1024
	ds_read_b128 v[150:153], v140 offset:2048
	ds_read_b128 v[154:157], v140 offset:3072
	v_add_u32_e32 v140, s30, v143
	ds_read_b128 v[158:161], v140
	ds_read_b128 v[168:171], v140 offset:1024
	ds_read_b128 v[172:175], v140 offset:2048
	ds_read_b128 v[176:179], v140 offset:3072
	v_lshl_add_u64 v[140:141], s[52:53], 0, v[132:133]
	s_add_i32 m0, s21, 0xc000
	s_nop 0
	global_load_lds_dwordx4 v[140:141], off
	v_lshl_add_u64 v[140:141], s[52:53], 0, v[134:135]
	s_add_i32 m0, s21, 0xe000
	s_nop 0
	global_load_lds_dwordx4 v[140:141], off
	s_waitcnt vmcnt(8) lgkmcnt(0)
	s_barrier
	s_setprio 1
	v_mfma_f32_16x16x32_bf16 v[126:129], v[136:139], v[180:183], v[126:129]
	v_mfma_f32_16x16x32_bf16 v[126:129], v[146:149], v[184:187], v[126:129]
	v_mfma_f32_16x16x32_bf16 v[122:125], v[150:153], v[180:183], v[122:125]
	v_mfma_f32_16x16x32_bf16 v[122:125], v[154:157], v[184:187], v[122:125]
	v_mfma_f32_16x16x32_bf16 v[110:113], v[136:139], v[188:191], v[110:113]
	v_mfma_f32_16x16x32_bf16 v[110:113], v[146:149], v[192:195], v[110:113]
	v_mfma_f32_16x16x32_bf16 v[106:109], v[150:153], v[188:191], v[106:109]
	v_mfma_f32_16x16x32_bf16 v[106:109], v[154:157], v[192:195], v[106:109]
	v_mfma_f32_16x16x32_bf16 v[94:97], v[136:139], v[196:199], v[94:97]
	v_mfma_f32_16x16x32_bf16 v[94:97], v[146:149], v[200:203], v[94:97]
	v_mfma_f32_16x16x32_bf16 v[90:93], v[150:153], v[196:199], v[90:93]
	v_mfma_f32_16x16x32_bf16 v[90:93], v[154:157], v[200:203], v[90:93]
	v_mfma_f32_16x16x32_bf16 v[78:81], v[136:139], v[224:227], v[78:81]
	v_mfma_f32_16x16x32_bf16 v[78:81], v[146:149], v[228:231], v[78:81]
	v_mfma_f32_16x16x32_bf16 v[74:77], v[150:153], v[224:227], v[74:77]
	v_mfma_f32_16x16x32_bf16 v[74:77], v[154:157], v[228:231], v[74:77]
	v_mfma_f32_16x16x32_bf16 v[118:121], v[158:161], v[180:183], v[118:121]
	v_mfma_f32_16x16x32_bf16 v[118:121], v[168:171], v[184:187], v[118:121]
	v_mfma_f32_16x16x32_bf16 v[114:117], v[172:175], v[180:183], v[114:117]
	v_mfma_f32_16x16x32_bf16 v[114:117], v[176:179], v[184:187], v[114:117]
	v_mfma_f32_16x16x32_bf16 v[102:105], v[158:161], v[188:191], v[102:105]
	v_mfma_f32_16x16x32_bf16 v[102:105], v[168:171], v[192:195], v[102:105]
	v_mfma_f32_16x16x32_bf16 v[98:101], v[172:175], v[188:191], v[98:101]
	v_mfma_f32_16x16x32_bf16 v[98:101], v[176:179], v[192:195], v[98:101]
	v_mfma_f32_16x16x32_bf16 v[86:89], v[158:161], v[196:199], v[86:89]
	v_mfma_f32_16x16x32_bf16 v[86:89], v[168:171], v[200:203], v[86:89]
	v_mfma_f32_16x16x32_bf16 v[82:85], v[172:175], v[196:199], v[82:85]
	v_mfma_f32_16x16x32_bf16 v[82:85], v[176:179], v[200:203], v[82:85]
	v_mfma_f32_16x16x32_bf16 v[70:73], v[158:161], v[224:227], v[70:73]
	v_mfma_f32_16x16x32_bf16 v[70:73], v[168:171], v[228:231], v[70:73]
	v_mfma_f32_16x16x32_bf16 v[66:69], v[172:175], v[224:227], v[66:69]
	v_mfma_f32_16x16x32_bf16 v[66:69], v[176:179], v[228:231], v[66:69]
	s_setprio 0
	s_barrier
	ds_read_b128 v[180:183], v145 offset:16384
	ds_read_b128 v[184:187], v145 offset:17408
	ds_read_b128 v[188:191], v145 offset:18432
	ds_read_b128 v[192:195], v145 offset:19456
	ds_read_b128 v[196:199], v145 offset:20480
	ds_read_b128 v[200:203], v145 offset:21504
	ds_read_b128 v[224:227], v145 offset:22528
	ds_read_b128 v[228:231], v145 offset:23552
	s_add_i32 s25, s25, s16
	v_lshl_add_u64 v[140:141], s[58:59], 0, v[0:1]
	s_mov_b32 m0, s25
	s_nop 0
	global_load_lds_dwordx4 v[140:141], off
	s_add_i32 m0, s25, 0x2000
	s_add_u32 s26, s58, 0x80000
	v_lshl_add_u64 v[232:233], s[58:59], 0, v[130:131]
	s_addc_u32 s27, s59, 0
	s_add_i32 s25, s30, s16
	global_load_lds_dwordx4 v[232:233], off
	v_lshl_add_u64 v[234:235], s[26:27], 0, v[0:1]
	s_mov_b32 m0, s25
	v_lshl_add_u64 v[236:237], s[64:65], 0, v[130:131]
	global_load_lds_dwordx4 v[234:235], off
	v_lshl_add_u64 v[234:235], s[26:27], 0, v[130:131]
	s_add_i32 m0, s25, 0x2000
	s_nop 0
	global_load_lds_dwordx4 v[234:235], off
	v_lshl_add_u64 v[234:235], s[64:65], 0, v[0:1]
	s_mov_b32 m0, s21
	s_nop 0
	global_load_lds_dwordx4 v[234:235], off
	s_mov_b32 m0, s22
	s_nop 0
	global_load_lds_dwordx4 v[236:237], off
	s_waitcnt vmcnt(8) lgkmcnt(0)
	s_barrier
; #define PG8_STAGE(bufoff, gbase, voff) do { _Pragma("unroll") for (int _i = 0; _i < 2; ++_i) \
;         __builtin_amdgcn_global_load_lds((const unsigned*)((const char*)(gbase) + (voff)[_i]), (PG8_LAS unsigned*)(lds + (bufoff) + ldsw + _i * 8192), 16, 0, 0); } while (0)
; #define PG8_LDA(dst, b, h) do { _Pragma("unroll") for (int m = 0; m < 4; ++m) _Pragma("unroll") for (int k = 0; k < 2; ++k) dst[m][k] = *(const PG8_LAS bf16x8*)(lds + PG8_SA(b, h) + aoff + m * 2048 + k * 1024); } while (0)
; #define PG8_LDB(dst, b, h) do { _Pragma("unroll") for (int n = 0; n < 2; ++n) _Pragma("unroll") for (int k = 0; k < 2; ++k) dst[n][k] = *(const PG8_LAS bf16x8*)(lds + PG8_SB(b, h) + boff + n * 2048 + k * 1024); } while (0)
; #define PG8_MMA(ai, bj, At, Bt) do { __builtin_amdgcn_s_setprio(1); _Pragma("unroll") for (int m = 0; m < 4; ++m) _Pragma("unroll") for (int n = 0; n < 2; ++n) _Pragma("unroll") for (int k = 0; k < 2; ++k) \
;         acc[ai][bj][m][n] = __builtin_amdgcn_mfma_f32_16x16x32_bf16(Bt[n][k], At[m][k], acc[ai][bj][m][n], 0, 0, 0); __builtin_amdgcn_s_setprio(0); } while (0)
; #define PG8_WAIT_V(n) asm volatile("s_waitcnt vmcnt(" #n ")" ::: "memory")
; #define PG8_WAIT_L(n) asm volatile("s_waitcnt lgkmcnt(" #n ")" ::: "memory")
; #define PG8_BAR __builtin_amdgcn_s_barrier()
; #define PG8_SCHED __builtin_amdgcn_sched_barrier(0)
; template <class Epi, class Sched, bool ALIGN_EPI = false, bool SP2 = false>
; __device__ __forceinline__ void gemm_phase(PG8_LAS unsigned char* lds, const Gemm g, const Sched S, const Epi E) {
;     ...
;             PG8_WAIT_V(8); PG8_WAIT_L(0); PG8_BAR; PG8_MMA(0, 0, At, B0); PG8_MMA(0, 1, At, B1); PG8_BAR; PG8_SCHED;
;             PG8_LDA(At, 0, 1); PG8_STAGE(PG8_SB(0, 0), b2, voffB); PG8_STAGE(PG8_SB(0, 1), b2 + hstep, voffB); PG8_STAGE(PG8_SA(0, 0), a2, voffA);
;             PG8_WAIT_V(8); PG8_WAIT_L(0); PG8_BAR; PG8_MMA(1, 0, At, B0); PG8_MMA(1, 1, At, B1); PG8_BAR; PG8_SCHED;
;             PG8_LDB(B0, 1, 0); PG8_LDB(B1, 1, 1); PG8_SCHED; PG8_LDA(At, 1, 0); PG8_STAGE(PG8_SA(0, 1), a2 + hstep, voffA);
;             PG8_WAIT_V(8); PG8_WAIT_L(0); PG8_BAR; PG8_MMA(0, 0, At, B0); PG8_MMA(0, 1, At, B1); PG8_BAR; PG8_SCHED;
	s_setprio 1
	v_mfma_f32_16x16x32_bf16 v[62:65], v[136:139], v[180:183], v[62:65]
	v_mfma_f32_16x16x32_bf16 v[62:65], v[146:149], v[184:187], v[62:65]
	v_mfma_f32_16x16x32_bf16 v[58:61], v[150:153], v[180:183], v[58:61]
	v_mfma_f32_16x16x32_bf16 v[58:61], v[154:157], v[184:187], v[58:61]
	v_mfma_f32_16x16x32_bf16 v[46:49], v[136:139], v[188:191], v[46:49]
	v_mfma_f32_16x16x32_bf16 v[46:49], v[146:149], v[192:195], v[46:49]
	v_mfma_f32_16x16x32_bf16 v[42:45], v[150:153], v[188:191], v[42:45]
	v_mfma_f32_16x16x32_bf16 v[42:45], v[154:157], v[192:195], v[42:45]
	v_mfma_f32_16x16x32_bf16 v[30:33], v[136:139], v[196:199], v[30:33]
	v_mfma_f32_16x16x32_bf16 v[30:33], v[146:149], v[200:203], v[30:33]
	v_mfma_f32_16x16x32_bf16 v[26:29], v[150:153], v[196:199], v[26:29]
	v_mfma_f32_16x16x32_bf16 v[26:29], v[154:157], v[200:203], v[26:29]
	v_mfma_f32_16x16x32_bf16 v[14:17], v[136:139], v[224:227], v[14:17]
	v_mfma_f32_16x16x32_bf16 v[14:17], v[146:149], v[228:231], v[14:17]
	v_mfma_f32_16x16x32_bf16 v[10:13], v[150:153], v[224:227], v[10:13]
	v_mfma_f32_16x16x32_bf16 v[10:13], v[154:157], v[228:231], v[10:13]
	v_mfma_f32_16x16x32_bf16 v[54:57], v[158:161], v[180:183], v[54:57]
	v_mfma_f32_16x16x32_bf16 v[54:57], v[168:171], v[184:187], v[54:57]
	v_mfma_f32_16x16x32_bf16 v[50:53], v[172:175], v[180:183], v[50:53]
	v_mfma_f32_16x16x32_bf16 v[50:53], v[176:179], v[184:187], v[50:53]
	v_mfma_f32_16x16x32_bf16 v[38:41], v[158:161], v[188:191], v[38:41]
	v_mfma_f32_16x16x32_bf16 v[38:41], v[168:171], v[192:195], v[38:41]
	v_mfma_f32_16x16x32_bf16 v[34:37], v[172:175], v[188:191], v[34:37]
	v_mfma_f32_16x16x32_bf16 v[34:37], v[176:179], v[192:195], v[34:37]
	v_mfma_f32_16x16x32_bf16 v[22:25], v[158:161], v[196:199], v[22:25]
	v_mfma_f32_16x16x32_bf16 v[22:25], v[168:171], v[200:203], v[22:25]
	v_mfma_f32_16x16x32_bf16 v[18:21], v[172:175], v[196:199], v[18:21]
	v_mfma_f32_16x16x32_bf16 v[18:21], v[176:179], v[200:203], v[18:21]
	v_mfma_f32_16x16x32_bf16 v[6:9], v[158:161], v[224:227], v[6:9]
	v_mfma_f32_16x16x32_bf16 v[6:9], v[168:171], v[228:231], v[6:9]
	v_mfma_f32_16x16x32_bf16 v[2:5], v[172:175], v[224:227], v[2:5]
	v_mfma_f32_16x16x32_bf16 v[2:5], v[176:179], v[228:231], v[2:5]
	s_setprio 0
	s_barrier
	ds_read_b128 v[180:183], v145 offset:32768
	ds_read_b128 v[184:187], v145 offset:33792
	ds_read_b128 v[188:191], v145 offset:34816
	ds_read_b128 v[192:195], v145 offset:35840
	ds_read_b128 v[196:199], v145 offset:36864
	ds_read_b128 v[200:203], v145 offset:37888
	ds_read_b128 v[224:227], v145 offset:38912
	ds_read_b128 v[228:231], v145 offset:39936
	s_add_i32 s25, 0, 0x18000
	s_add_i32 s30, 0, 0x1c000
	v_add_u32_e32 v154, s25, v143
	v_add_u32_e32 v167, s30, v143
	ds_read_b128 v[136:139], v154
	ds_read_b128 v[146:149], v154 offset:1024
	ds_read_b128 v[150:153], v154 offset:2048
	ds_read_b128 v[154:157], v154 offset:3072
	ds_read_b128 v[158:161], v167
	ds_read_b128 v[168:171], v167 offset:1024
	ds_read_b128 v[172:175], v167 offset:2048
	ds_read_b128 v[176:179], v167 offset:3072
	s_add_u32 s26, s64, 0x80000
	s_addc_u32 s27, s65, 0
	s_mov_b32 m0, s47
	v_lshl_add_u64 v[238:239], s[26:27], 0, v[0:1]
	global_load_lds_dwordx4 v[238:239], off
	v_lshl_add_u64 v[238:239], s[26:27], 0, v[130:131]
	s_mov_b32 m0, s62
	s_nop 0
	global_load_lds_dwordx4 v[238:239], off
	s_waitcnt vmcnt(8) lgkmcnt(0)
	s_barrier
	s_setprio 1
	v_mfma_f32_16x16x32_bf16 v[126:129], v[136:139], v[180:183], v[126:129]
	v_mfma_f32_16x16x32_bf16 v[126:129], v[146:149], v[184:187], v[126:129]
	v_mfma_f32_16x16x32_bf16 v[122:125], v[150:153], v[180:183], v[122:125]
	v_mfma_f32_16x16x32_bf16 v[122:125], v[154:157], v[184:187], v[122:125]
	v_mfma_f32_16x16x32_bf16 v[110:113], v[136:139], v[188:191], v[110:113]
	v_mfma_f32_16x16x32_bf16 v[110:113], v[146:149], v[192:195], v[110:113]
	v_mfma_f32_16x16x32_bf16 v[106:109], v[150:153], v[188:191], v[106:109]
	v_mfma_f32_16x16x32_bf16 v[106:109], v[154:157], v[192:195], v[106:109]
	v_mfma_f32_16x16x32_bf16 v[94:97], v[136:139], v[196:199], v[94:97]
	v_mfma_f32_16x16x32_bf16 v[94:97], v[146:149], v[200:203], v[94:97]
	v_mfma_f32_16x16x32_bf16 v[90:93], v[150:153], v[196:199], v[90:93]
	v_mfma_f32_16x16x32_bf16 v[90:93], v[154:157], v[200:203], v[90:93]
	v_mfma_f32_16x16x32_bf16 v[78:81], v[136:139], v[224:227], v[78:81]
	v_mfma_f32_16x16x32_bf16 v[78:81], v[146:149], v[228:231], v[78:81]
	v_mfma_f32_16x16x32_bf16 v[74:77], v[150:153], v[224:227], v[74:77]
	v_mfma_f32_16x16x32_bf16 v[74:77], v[154:157], v[228:231], v[74:77]
	v_mfma_f32_16x16x32_bf16 v[118:121], v[158:161], v[180:183], v[118:121]
	v_mfma_f32_16x16x32_bf16 v[118:121], v[168:171], v[184:187], v[118:121]
	v_mfma_f32_16x16x32_bf16 v[114:117], v[172:175], v[180:183], v[114:117]
	v_mfma_f32_16x16x32_bf16 v[114:117], v[176:179], v[184:187], v[114:117]
	v_mfma_f32_16x16x32_bf16 v[102:105], v[158:161], v[188:191], v[102:105]
	v_mfma_f32_16x16x32_bf16 v[102:105], v[168:171], v[192:195], v[102:105]
	v_mfma_f32_16x16x32_bf16 v[98:101], v[172:175], v[188:191], v[98:101]
	v_mfma_f32_16x16x32_bf16 v[98:101], v[176:179], v[192:195], v[98:101]
	v_mfma_f32_16x16x32_bf16 v[86:89], v[158:161], v[196:199], v[86:89]
	v_mfma_f32_16x16x32_bf16 v[86:89], v[168:171], v[200:203], v[86:89]
	v_mfma_f32_16x16x32_bf16 v[82:85], v[172:175], v[196:199], v[82:85]
	v_mfma_f32_16x16x32_bf16 v[82:85], v[176:179], v[200:203], v[82:85]
	v_mfma_f32_16x16x32_bf16 v[70:73], v[158:161], v[224:227], v[70:73]
	v_mfma_f32_16x16x32_bf16 v[70:73], v[168:171], v[228:231], v[70:73]
	v_mfma_f32_16x16x32_bf16 v[66:69], v[172:175], v[224:227], v[66:69]
	v_mfma_f32_16x16x32_bf16 v[66:69], v[176:179], v[228:231], v[66:69]
	s_setprio 0
	s_barrier
; #define PG8_STAGE(bufoff, gbase, voff) do { _Pragma("unroll") for (int _i = 0; _i < 2; ++_i) \
;         __builtin_amdgcn_global_load_lds((const unsigned*)((const char*)(gbase) + (voff)[_i]), (PG8_LAS unsigned*)(lds + (bufoff) + ldsw + _i * 8192), 16, 0, 0); } while (0)
; #define PG8_LDA(dst, b, h) do { _Pragma("unroll") for (int m = 0; m < 4; ++m) _Pragma("unroll") for (int k = 0; k < 2; ++k) dst[m][k] = *(const PG8_LAS bf16x8*)(lds + PG8_SA(b, h) + aoff + m * 2048 + k * 1024); } while (0)
; #define PG8_MMA(ai, bj, At, Bt) do { __builtin_amdgcn_s_setprio(1); _Pragma("unroll") for (int m = 0; m < 4; ++m) _Pragma("unroll") for (int n = 0; n < 2; ++n) _Pragma("unroll") for (int k = 0; k < 2; ++k) \
;         acc[ai][bj][m][n] = __builtin_amdgcn_mfma_f32_16x16x32_bf16(Bt[n][k], At[m][k], acc[ai][bj][m][n], 0, 0, 0); __builtin_amdgcn_s_setprio(0); } while (0)
; #define PG8_WAIT_V(n) asm volatile("s_waitcnt vmcnt(" #n ")" ::: "memory")
; #define PG8_WAIT_L(n) asm volatile("s_waitcnt lgkmcnt(" #n ")" ::: "memory")
; #define PG8_BAR __builtin_amdgcn_s_barrier()
; #define PG8_SCHED __builtin_amdgcn_sched_barrier(0)
; template <class Epi, class Sched, bool ALIGN_EPI = false, bool SP2 = false>
; __device__ __forceinline__ void gemm_phase(PG8_LAS unsigned char* lds, const Gemm g, const Sched S, const Epi E) {
;     ...
;             PG8_LDA(At, 1, 1); PG8_STAGE(PG8_SB(1, 0), b3, voffB); PG8_STAGE(PG8_SB(1, 1), b3 + hstep, voffB); PG8_STAGE(PG8_SA(1, 0), a3, voffA);
;             PG8_WAIT_V(8); PG8_WAIT_L(0); PG8_BAR; PG8_MMA(1, 0, At, B0); PG8_MMA(1, 1, At, B1); PG8_BAR; PG8_SCHED;
;     ...
;         if constexpr (ALIGN_EPI) { if (wr == 0) PG8_BAR; }
	ds_read_b128 v[180:183], v145 offset:49152
	ds_read_b128 v[184:187], v145 offset:50176
	ds_read_b128 v[188:191], v145 offset:51200
	ds_read_b128 v[192:195], v145 offset:52224
	ds_read_b128 v[196:199], v145 offset:53248
	ds_read_b128 v[200:203], v145 offset:54272
	ds_read_b128 v[224:227], v145 offset:55296
	ds_read_b128 v[228:231], v145 offset:56320
	s_add_i32 s25, s25, s16
	v_lshl_add_u64 v[140:141], v[140:141], 0, s[28:29]
	s_mov_b32 m0, s25
	s_nop 0
	global_load_lds_dwordx4 v[140:141], off
	s_add_i32 m0, s25, 0x2000
	s_add_u32 s26, s58, 0x80080
	v_lshl_add_u64 v[140:141], v[232:233], 0, s[28:29]
	s_addc_u32 s27, s59, 0
	s_add_i32 s25, s30, s16
	global_load_lds_dwordx4 v[140:141], off
	v_lshl_add_u64 v[140:141], s[26:27], 0, v[0:1]
	s_mov_b32 m0, s25
	s_nop 0
	global_load_lds_dwordx4 v[140:141], off
	v_lshl_add_u64 v[140:141], s[26:27], 0, v[130:131]
	s_add_i32 m0, s25, 0x2000
	s_nop 0
	global_load_lds_dwordx4 v[140:141], off
	v_lshl_add_u64 v[140:141], v[234:235], 0, s[28:29]
	s_mov_b32 m0, s63
	s_nop 0
	global_load_lds_dwordx4 v[140:141], off
	v_lshl_add_u64 v[140:141], v[236:237], 0, s[28:29]
	s_mov_b32 m0, s66
	s_nop 0
	global_load_lds_dwordx4 v[140:141], off
	s_waitcnt vmcnt(8) lgkmcnt(0)
	s_barrier
	s_setprio 1
	v_mfma_f32_16x16x32_bf16 v[62:65], v[136:139], v[180:183], v[62:65]
	v_mfma_f32_16x16x32_bf16 v[62:65], v[146:149], v[184:187], v[62:65]
	v_mfma_f32_16x16x32_bf16 v[58:61], v[150:153], v[180:183], v[58:61]
	v_mfma_f32_16x16x32_bf16 v[58:61], v[154:157], v[184:187], v[58:61]
	v_mfma_f32_16x16x32_bf16 v[46:49], v[136:139], v[188:191], v[46:49]
	v_mfma_f32_16x16x32_bf16 v[46:49], v[146:149], v[192:195], v[46:49]
	v_mfma_f32_16x16x32_bf16 v[42:45], v[150:153], v[188:191], v[42:45]
	v_mfma_f32_16x16x32_bf16 v[42:45], v[154:157], v[192:195], v[42:45]
	v_mfma_f32_16x16x32_bf16 v[30:33], v[136:139], v[196:199], v[30:33]
	v_mfma_f32_16x16x32_bf16 v[30:33], v[146:149], v[200:203], v[30:33]
	v_mfma_f32_16x16x32_bf16 v[26:29], v[150:153], v[196:199], v[26:29]
	v_mfma_f32_16x16x32_bf16 v[26:29], v[154:157], v[200:203], v[26:29]
	v_mfma_f32_16x16x32_bf16 v[14:17], v[136:139], v[224:227], v[14:17]
	v_mfma_f32_16x16x32_bf16 v[14:17], v[146:149], v[228:231], v[14:17]
	v_mfma_f32_16x16x32_bf16 v[10:13], v[150:153], v[224:227], v[10:13]
	v_mfma_f32_16x16x32_bf16 v[10:13], v[154:157], v[228:231], v[10:13]
	v_mfma_f32_16x16x32_bf16 v[54:57], v[158:161], v[180:183], v[54:57]
	v_mfma_f32_16x16x32_bf16 v[54:57], v[168:171], v[184:187], v[54:57]
	v_mfma_f32_16x16x32_bf16 v[50:53], v[172:175], v[180:183], v[50:53]
	v_mfma_f32_16x16x32_bf16 v[50:53], v[176:179], v[184:187], v[50:53]
	v_mfma_f32_16x16x32_bf16 v[38:41], v[158:161], v[188:191], v[38:41]
	v_mfma_f32_16x16x32_bf16 v[38:41], v[168:171], v[192:195], v[38:41]
	v_mfma_f32_16x16x32_bf16 v[34:37], v[172:175], v[188:191], v[34:37]
	v_mfma_f32_16x16x32_bf16 v[34:37], v[176:179], v[192:195], v[34:37]
	v_mfma_f32_16x16x32_bf16 v[22:25], v[158:161], v[196:199], v[22:25]
	v_mfma_f32_16x16x32_bf16 v[22:25], v[168:171], v[200:203], v[22:25]
	v_mfma_f32_16x16x32_bf16 v[18:21], v[172:175], v[196:199], v[18:21]
	v_mfma_f32_16x16x32_bf16 v[18:21], v[176:179], v[200:203], v[18:21]
	v_mfma_f32_16x16x32_bf16 v[6:9], v[158:161], v[224:227], v[6:9]
	v_mfma_f32_16x16x32_bf16 v[6:9], v[168:171], v[228:231], v[6:9]
	v_mfma_f32_16x16x32_bf16 v[2:5], v[172:175], v[224:227], v[2:5]
	v_mfma_f32_16x16x32_bf16 v[2:5], v[176:179], v[228:231], v[2:5]
	s_setprio 0
	s_barrier
	s_add_i32 s24, s24, 2
	s_add_u32 s14, s14, 0x100
	s_addc_u32 s15, s15, 0
	s_cmp_gt_u32 s24, 29
	s_mov_b64 s[52:53], s[56:57]
	s_cbranch_scc0 .LBB0_2074
	s_and_b64 vcc, exec, s[38:39]
	s_cbranch_vccz .LBB0_2077
	s_barrier
